# all per-segment s_setprio deleted (no nop left in their place), one static s_setprio 1 for waves 4-7 at kernel entry
# speedup vs baseline: 1.0003x; 1.0003x over previous
; #define PG8_GOFFS(slot_) do { _Pragma("unroll") for (int _i = 0; _i < 2; ++_i) { int R, C; stage_rc(tid * 16 + _i * 8192, R, C); _Pragma("unroll") for (int _h = 0; _h < 2; ++_h) { \
;         unsigned t_ = gtab[(slot_) * 256 + R + 128 * _h]; t_ = t_ < (unsigned)(T - 1) ? t_ : (unsigned)(T - 1); voffA[_h][_i] = (t_ * (unsigned)K + (unsigned)C) * 2u; } } } while (0)
; #define PG8_STAGE(bufoff, gbase, voff) do { _Pragma("unroll") for (int _i = 0; _i < 2; ++_i) \
;         __builtin_amdgcn_global_load_lds((const unsigned*)((const char*)(gbase) + (voff)[_i]), (LAS unsigned*)(lds + (bufoff) + ldsw + _i * 8192), 16, 0, 0); } while (0)
; #define PG8_STAGE_A1(bufoff, gbase) do { if (Epi::GATHER) PG8_STAGE(bufoff, gbase, voffA[1]); else PG8_STAGE(bufoff, (gbase) + hstep, voffA[0]); } while (0)
; #define PG8_LDA(dst, b, h) do { _Pragma("unroll") for (int m = 0; m < 4; ++m) _Pragma("unroll") for (int k = 0; k < 2; ++k) dst[m][k] = *(const LAS bf16x8*)(lds + PG8_SA(b, h) + aoff + m * 2048 + k * 1024); } while (0)
; #define PG8_WAIT_V(n) asm volatile("s_waitcnt vmcnt(" #n ")" ::: "memory")
; #define PG8_WAIT_L(n) asm volatile("s_waitcnt lgkmcnt(" #n ")" ::: "memory")
; #define PG8_BAR __builtin_amdgcn_s_barrier()
; template <class Epi, class Sched>
; __device__ __forceinline__ void gemm_phase(const int tid, LAS unsigned char* lds, const bf16* Aop, const bf16* Bop, const int K_, const Sched& S, const Epi& E, const bf16* Aop1 = nullptr, const bf16* Bop1 = nullptr) {
;     ...
;         for (int t = 0; t < nt; t += 2) {
;             const bool last = (t == nt - 2);
;             const char* a1 = cA + (size_t)(t + 1) * kstep;
;             const char* a2 = last ? nA : cA + (size_t)(t + 2) * kstep; const char* b2 = last ? nB : cB + (size_t)(t + 2) * kstep;
;             const char* a3 = a2 + kstep; const char* b3 = b2 + kstep;
;             PG8_LDB(B0, 0, 0); PG8_LDB(B1, 0, 1); PG8_SCHED; PG8_LDA(At, 0, 0); PG8_STAGE_A1(PG8_SA(1, 1), a1);
;             PG8_WAIT_V(8); PG8_WAIT_L(0); PG8_BAR; PG8_MMA(0, 0, At, B0); PG8_MMA(0, 1, At, B1); PG8_BAR; PG8_SCHED;
;             PG8_LDA(At, 0, 1); PG8_STAGE(PG8_SB(0, 0), b2, voffB); PG8_STAGE(PG8_SB(0, 1), b2 + hstep, voffB); if (Epi::GATHER && last && has_next) PG8_GOFFS((ui + 1) & 1); PG8_STAGE(PG8_SA(0, 0), a2, voffA[0]);
;             PG8_WAIT_V(8); PG8_WAIT_L(0); PG8_BAR; PG8_MMA(1, 0, At, B0); PG8_MMA(1, 1, At, B1); PG8_BAR; PG8_SCHED;
.LBB0_129:
	v_mov_b32_e32 v143, 0
	s_andn2_b64 vcc, exec, s[18:19]
	s_cbranch_vccnz .LBB0_133
	s_add_u32 s26, s26, 0x80
	s_addc_u32 s27, s27, 0
	s_add_u32 s11, s42, 0x100
	v_mov_b64_e32 v[180:181], v[178:179]
	v_mov_b64_e32 v[178:179], v[176:177]
	v_mov_b64_e32 v[176:177], v[190:191]
	v_mov_b32_e32 v205, 0x7f800000
	v_mov_b32_e32 v203, 0x3ecc95a3
	v_mov_b32_e32 v200, 1
	v_mov_b64_e32 v[226:227], 0x100
	s_addc_u32 s42, s43, 0
	s_mov_b32 s40, 0
	s_add_i32 s43, s40, 2
	s_add_u32 s44, s26, 0x80
	s_addc_u32 s41, s27, 0
	s_add_i32 s48, 0, 0x10000
	s_cmp_eq_u32 s77, s40
	s_cselect_b32 s41, s35, s41
	s_cselect_b32 s40, s34, s44
	s_cselect_b32 s45, s37, s42
	s_cselect_b32 s44, s36, s11
	s_add_i32 s49, 0, 0x14000
	v_add_u32_e32 v80, s48, v3
	v_add_u32_e32 v160, s49, v3
	ds_read_b128 v[60:63], v80
	ds_read_b128 v[68:71], v80 offset:1024
	ds_read_b128 v[76:79], v80 offset:2048
	ds_read_b128 v[80:83], v80 offset:3072
	ds_read_b128 v[148:151], v160
	ds_read_b128 v[152:155], v160 offset:1024
	ds_read_b128 v[156:159], v160 offset:2048
	ds_read_b128 v[160:163], v160 offset:3072
	v_lshl_add_u64 v[164:165], s[26:27], 0, v[192:193]
	s_add_i32 m0, s70, 0xc000
	ds_read_b128 v[206:209], v175
	ds_read_b128 v[210:213], v175 offset:1024
	ds_read_b128 v[214:217], v175 offset:2048
	ds_read_b128 v[218:221], v175 offset:3072
	ds_read_b128 v[238:241], v175 offset:4096
	ds_read_b128 v[242:245], v175 offset:5120
	ds_read_b128 v[246:249], v175 offset:6144
	ds_read_b128 v[230:233], v175 offset:7168
	global_load_lds_dwordx4 v[164:165], off
	v_lshl_add_u64 v[164:165], s[26:27], 0, v[194:195]
	s_add_i32 m0, s70, 0xe000
	s_nop 0
	global_load_lds_dwordx4 v[164:165], off
	s_waitcnt vmcnt(8)
	s_waitcnt lgkmcnt(0)
	s_barrier
	v_mfma_f32_16x16x32_bf16 v[140:143], v[60:63], v[206:209], 0
	v_mfma_f32_16x16x32_bf16 v[144:147], v[76:79], v[206:209], 0
	v_mfma_f32_16x16x32_bf16 v[128:131], v[60:63], v[214:217], 0
	v_mfma_f32_16x16x32_bf16 v[124:127], v[76:79], v[214:217], 0
	v_mfma_f32_16x16x32_bf16 v[112:115], v[60:63], v[238:241], 0
	v_mfma_f32_16x16x32_bf16 v[108:111], v[76:79], v[238:241], 0
	v_mfma_f32_16x16x32_bf16 v[96:99], v[60:63], v[246:249], 0
	v_mfma_f32_16x16x32_bf16 v[92:95], v[76:79], v[246:249], 0
	v_mfma_f32_16x16x32_bf16 v[140:143], v[68:71], v[210:213], v[140:143]
	v_mfma_f32_16x16x32_bf16 v[144:147], v[80:83], v[210:213], v[144:147]
	v_mfma_f32_16x16x32_bf16 v[128:131], v[68:71], v[218:221], v[128:131]
	v_mfma_f32_16x16x32_bf16 v[124:127], v[80:83], v[218:221], v[124:127]
	v_mfma_f32_16x16x32_bf16 v[112:115], v[68:71], v[242:245], v[112:115]
	v_mfma_f32_16x16x32_bf16 v[108:111], v[80:83], v[242:245], v[108:111]
	v_mfma_f32_16x16x32_bf16 v[96:99], v[68:71], v[230:233], v[96:99]
	v_mfma_f32_16x16x32_bf16 v[92:95], v[80:83], v[230:233], v[92:95]
	v_mfma_f32_16x16x32_bf16 v[136:139], v[148:151], v[206:209], 0
	v_mfma_f32_16x16x32_bf16 v[132:135], v[156:159], v[206:209], 0
	v_mfma_f32_16x16x32_bf16 v[120:123], v[148:151], v[214:217], 0
	v_mfma_f32_16x16x32_bf16 v[116:119], v[156:159], v[214:217], 0
	v_mfma_f32_16x16x32_bf16 v[104:107], v[148:151], v[238:241], 0
	v_mfma_f32_16x16x32_bf16 v[100:103], v[156:159], v[238:241], 0
	v_mfma_f32_16x16x32_bf16 v[88:91], v[148:151], v[246:249], 0
	v_mfma_f32_16x16x32_bf16 v[84:87], v[156:159], v[246:249], 0
	v_mfma_f32_16x16x32_bf16 v[136:139], v[152:155], v[210:213], v[136:139]
	v_mfma_f32_16x16x32_bf16 v[132:135], v[160:163], v[210:213], v[132:135]
	v_mfma_f32_16x16x32_bf16 v[120:123], v[152:155], v[218:221], v[120:123]
	v_mfma_f32_16x16x32_bf16 v[116:119], v[160:163], v[218:221], v[116:119]
	v_mfma_f32_16x16x32_bf16 v[104:107], v[152:155], v[242:245], v[104:107]
	v_mfma_f32_16x16x32_bf16 v[100:103], v[160:163], v[242:245], v[100:103]
	v_mfma_f32_16x16x32_bf16 v[88:91], v[152:155], v[230:233], v[88:91]
	v_mfma_f32_16x16x32_bf16 v[84:87], v[160:163], v[230:233], v[84:87]
	s_barrier
	s_add_i32 s48, s48, s69
	v_lshl_add_u64 v[164:165], s[44:45], 0, v[166:167]
	s_mov_b32 m0, s48
	ds_read_b128 v[206:209], v175 offset:16384
	ds_read_b128 v[210:213], v175 offset:17408
	ds_read_b128 v[214:217], v175 offset:18432
	ds_read_b128 v[218:221], v175 offset:19456
	ds_read_b128 v[230:233], v175 offset:20480
	ds_read_b128 v[238:241], v175 offset:21504
	ds_read_b128 v[242:245], v175 offset:22528
	ds_read_b128 v[246:249], v175 offset:23552
	global_load_lds_dwordx4 v[164:165], off
	s_add_i32 m0, s48, 0x2000
	v_lshl_add_u64 v[222:223], s[44:45], 0, v[170:171]
	s_add_u32 s44, s44, s6
	s_addc_u32 s45, s45, s7
	s_add_i32 s48, s49, s69
	global_load_lds_dwordx4 v[222:223], off
	v_lshl_add_u64 v[250:251], s[44:45], 0, v[166:167]
	s_mov_b32 m0, s48
	v_lshl_add_u64 v[196:197], s[44:45], 0, v[170:171]
	global_load_lds_dwordx4 v[250:251], off
	s_add_i32 m0, s48, 0x2000
	v_lshl_add_u64 v[198:199], s[40:41], 0, v[0:1]
	global_load_lds_dwordx4 v[196:197], off
	s_mov_b32 m0, s70
	v_lshl_add_u64 v[224:225], s[40:41], 0, v[168:169]
	global_load_lds_dwordx4 v[198:199], off
	s_mov_b32 m0, s71
	s_nop 0
	global_load_lds_dwordx4 v[224:225], off
	s_waitcnt vmcnt(8)
	s_waitcnt lgkmcnt(0)
	s_barrier
; #define PG8_STAGE(bufoff, gbase, voff) do { _Pragma("unroll") for (int _i = 0; _i < 2; ++_i) \
;         __builtin_amdgcn_global_load_lds((const unsigned*)((const char*)(gbase) + (voff)[_i]), (LAS unsigned*)(lds + (bufoff) + ldsw + _i * 8192), 16, 0, 0); } while (0)
; #define PG8_STAGE_A1(bufoff, gbase) do { if (Epi::GATHER) PG8_STAGE(bufoff, gbase, voffA[1]); else PG8_STAGE(bufoff, (gbase) + hstep, voffA[0]); } while (0)
; #define PG8_LDA(dst, b, h) do { _Pragma("unroll") for (int m = 0; m < 4; ++m) _Pragma("unroll") for (int k = 0; k < 2; ++k) dst[m][k] = *(const LAS bf16x8*)(lds + PG8_SA(b, h) + aoff + m * 2048 + k * 1024); } while (0)
; #define PG8_LDB(dst, b, h) do { _Pragma("unroll") for (int n = 0; n < 2; ++n) _Pragma("unroll") for (int k = 0; k < 2; ++k) dst[n][k] = *(const LAS bf16x8*)(lds + PG8_SB(b, h) + boff + n * 2048 + k * 1024); } while (0)
; #define PG8_MMA(ai, bj, At, Bt) do { __builtin_amdgcn_s_setprio(1); _Pragma("unroll") for (int m = 0; m < 4; ++m) _Pragma("unroll") for (int n = 0; n < 2; ++n) _Pragma("unroll") for (int k = 0; k < 2; ++k) \
;         acc[ai][bj][m][n] = __builtin_amdgcn_mfma_f32_16x16x32_bf16(Bt[n][k], At[m][k], acc[ai][bj][m][n], 0, 0, 0); __builtin_amdgcn_s_setprio(0); } while (0)
; #define PG8_WAIT_V(n) asm volatile("s_waitcnt vmcnt(" #n ")" ::: "memory")
; #define PG8_WAIT_L(n) asm volatile("s_waitcnt lgkmcnt(" #n ")" ::: "memory")
; #define PG8_BAR __builtin_amdgcn_s_barrier()
; #define PG8_SCHED __builtin_amdgcn_sched_barrier(0)
; template <class Epi, class Sched>
; __device__ __forceinline__ void gemm_phase(const int tid, LAS unsigned char* lds, const bf16* Aop, const bf16* Bop, const int K_, const Sched& S, const Epi& E, const bf16* Aop1 = nullptr, const bf16* Bop1 = nullptr) {
;     ...
;             PG8_WAIT_V(8); PG8_WAIT_L(0); PG8_BAR; PG8_MMA(1, 0, At, B0); PG8_MMA(1, 1, At, B1); PG8_BAR; PG8_SCHED;
;             PG8_LDB(B0, 1, 0); PG8_LDB(B1, 1, 1); PG8_SCHED; PG8_LDA(At, 1, 0); PG8_STAGE_A1(PG8_SA(0, 1), a2);
;             PG8_WAIT_V(8); PG8_WAIT_L(0); PG8_BAR; PG8_MMA(0, 0, At, B0); PG8_MMA(0, 1, At, B1); PG8_BAR; PG8_SCHED;
;             PG8_LDA(At, 1, 1); PG8_STAGE(PG8_SB(1, 0), b3, voffB); PG8_STAGE(PG8_SB(1, 1), b3 + hstep, voffB); PG8_STAGE(PG8_SA(1, 0), a3, voffA[0]);
;             PG8_WAIT_V(8); PG8_WAIT_L(0); PG8_BAR; PG8_MMA(1, 0, At, B0); PG8_MMA(1, 1, At, B1); PG8_BAR; PG8_SCHED;
	v_mfma_f32_16x16x32_bf16 v[72:75], v[60:63], v[206:209], 0
	v_mfma_f32_16x16x32_bf16 v[64:67], v[76:79], v[206:209], 0
	v_mfma_f32_16x16x32_bf16 v[48:51], v[60:63], v[214:217], 0
	v_mfma_f32_16x16x32_bf16 v[44:47], v[76:79], v[214:217], 0
	v_mfma_f32_16x16x32_bf16 v[32:35], v[60:63], v[230:233], 0
	v_mfma_f32_16x16x32_bf16 v[28:31], v[76:79], v[230:233], 0
	v_mfma_f32_16x16x32_bf16 v[16:19], v[60:63], v[242:245], 0
	v_mfma_f32_16x16x32_bf16 v[12:15], v[76:79], v[242:245], 0
	v_mfma_f32_16x16x32_bf16 v[72:75], v[68:71], v[210:213], v[72:75]
	v_mfma_f32_16x16x32_bf16 v[64:67], v[80:83], v[210:213], v[64:67]
	v_mfma_f32_16x16x32_bf16 v[48:51], v[68:71], v[218:221], v[48:51]
	v_mfma_f32_16x16x32_bf16 v[44:47], v[80:83], v[218:221], v[44:47]
	v_mfma_f32_16x16x32_bf16 v[32:35], v[68:71], v[238:241], v[32:35]
	v_mfma_f32_16x16x32_bf16 v[28:31], v[80:83], v[238:241], v[28:31]
	v_mfma_f32_16x16x32_bf16 v[16:19], v[68:71], v[246:249], v[16:19]
	v_mfma_f32_16x16x32_bf16 v[12:15], v[80:83], v[246:249], v[12:15]
	v_mfma_f32_16x16x32_bf16 v[56:59], v[148:151], v[206:209], 0
	v_mfma_f32_16x16x32_bf16 v[52:55], v[156:159], v[206:209], 0
	v_mfma_f32_16x16x32_bf16 v[40:43], v[148:151], v[214:217], 0
	v_mfma_f32_16x16x32_bf16 v[36:39], v[156:159], v[214:217], 0
	v_mfma_f32_16x16x32_bf16 v[24:27], v[148:151], v[230:233], 0
	v_mfma_f32_16x16x32_bf16 v[20:23], v[156:159], v[230:233], 0
	v_mfma_f32_16x16x32_bf16 v[8:11], v[148:151], v[242:245], 0
	v_mfma_f32_16x16x32_bf16 v[4:7], v[156:159], v[242:245], 0
	v_mfma_f32_16x16x32_bf16 v[56:59], v[152:155], v[210:213], v[56:59]
	v_mfma_f32_16x16x32_bf16 v[52:55], v[160:163], v[210:213], v[52:55]
	v_mfma_f32_16x16x32_bf16 v[40:43], v[152:155], v[218:221], v[40:43]
	v_mfma_f32_16x16x32_bf16 v[36:39], v[160:163], v[218:221], v[36:39]
	v_mfma_f32_16x16x32_bf16 v[24:27], v[152:155], v[238:241], v[24:27]
	v_mfma_f32_16x16x32_bf16 v[20:23], v[160:163], v[238:241], v[20:23]
	v_mfma_f32_16x16x32_bf16 v[8:11], v[152:155], v[246:249], v[8:11]
	v_mfma_f32_16x16x32_bf16 v[4:7], v[160:163], v[246:249], v[4:7]
	s_barrier
	s_add_i32 s44, 0, 0x18000
	s_add_i32 s45, 0, 0x1c000
	v_add_u32_e32 v80, s44, v3
	v_add_u32_e32 v160, s45, v3
	ds_read_b128 v[60:63], v80
	ds_read_b128 v[68:71], v80 offset:1024
	ds_read_b128 v[76:79], v80 offset:2048
	ds_read_b128 v[80:83], v80 offset:3072
	ds_read_b128 v[148:151], v160
	ds_read_b128 v[152:155], v160 offset:1024
	ds_read_b128 v[156:159], v160 offset:2048
	ds_read_b128 v[160:163], v160 offset:3072
	s_add_u32 s40, s40, s6
	s_addc_u32 s41, s41, s7
	s_mov_b32 m0, s72
	v_lshl_add_u64 v[190:191], s[40:41], 0, v[0:1]
	ds_read_b128 v[206:209], v175 offset:32768
	ds_read_b128 v[210:213], v175 offset:33792
	ds_read_b128 v[214:217], v175 offset:34816
	ds_read_b128 v[218:221], v175 offset:35840
	ds_read_b128 v[230:233], v175 offset:36864
	ds_read_b128 v[238:241], v175 offset:37888
	ds_read_b128 v[242:245], v175 offset:38912
	ds_read_b128 v[246:249], v175 offset:39936
	global_load_lds_dwordx4 v[190:191], off
	v_lshl_add_u64 v[190:191], s[40:41], 0, v[168:169]
	s_mov_b32 m0, s73
	s_nop 0
	global_load_lds_dwordx4 v[190:191], off
	s_waitcnt vmcnt(8)
	s_waitcnt lgkmcnt(0)
	s_barrier
	v_mfma_f32_16x16x32_bf16 v[140:143], v[60:63], v[206:209], v[140:143]
	v_mfma_f32_16x16x32_bf16 v[144:147], v[76:79], v[206:209], v[144:147]
	v_mfma_f32_16x16x32_bf16 v[128:131], v[60:63], v[214:217], v[128:131]
	v_mfma_f32_16x16x32_bf16 v[124:127], v[76:79], v[214:217], v[124:127]
	v_mfma_f32_16x16x32_bf16 v[112:115], v[60:63], v[230:233], v[112:115]
	v_mfma_f32_16x16x32_bf16 v[108:111], v[76:79], v[230:233], v[108:111]
	v_mfma_f32_16x16x32_bf16 v[96:99], v[60:63], v[242:245], v[96:99]
	v_mfma_f32_16x16x32_bf16 v[92:95], v[76:79], v[242:245], v[92:95]
	v_mfma_f32_16x16x32_bf16 v[140:143], v[68:71], v[210:213], v[140:143]
	v_mfma_f32_16x16x32_bf16 v[144:147], v[80:83], v[210:213], v[144:147]
	v_mfma_f32_16x16x32_bf16 v[128:131], v[68:71], v[218:221], v[128:131]
	v_mfma_f32_16x16x32_bf16 v[124:127], v[80:83], v[218:221], v[124:127]
	v_mfma_f32_16x16x32_bf16 v[112:115], v[68:71], v[238:241], v[112:115]
	v_mfma_f32_16x16x32_bf16 v[108:111], v[80:83], v[238:241], v[108:111]
	v_mfma_f32_16x16x32_bf16 v[96:99], v[68:71], v[246:249], v[96:99]
	v_mfma_f32_16x16x32_bf16 v[92:95], v[80:83], v[246:249], v[92:95]
	v_mfma_f32_16x16x32_bf16 v[136:139], v[148:151], v[206:209], v[136:139]
	v_mfma_f32_16x16x32_bf16 v[132:135], v[156:159], v[206:209], v[132:135]
	v_mfma_f32_16x16x32_bf16 v[120:123], v[148:151], v[214:217], v[120:123]
	v_mfma_f32_16x16x32_bf16 v[116:119], v[156:159], v[214:217], v[116:119]
	v_mfma_f32_16x16x32_bf16 v[104:107], v[148:151], v[230:233], v[104:107]
	v_mfma_f32_16x16x32_bf16 v[100:103], v[156:159], v[230:233], v[100:103]
	v_mfma_f32_16x16x32_bf16 v[88:91], v[148:151], v[242:245], v[88:91]
	v_mfma_f32_16x16x32_bf16 v[84:87], v[156:159], v[242:245], v[84:87]
	v_mfma_f32_16x16x32_bf16 v[136:139], v[152:155], v[210:213], v[136:139]
	v_mfma_f32_16x16x32_bf16 v[132:135], v[160:163], v[210:213], v[132:135]
	v_mfma_f32_16x16x32_bf16 v[120:123], v[152:155], v[218:221], v[120:123]
	v_mfma_f32_16x16x32_bf16 v[116:119], v[160:163], v[218:221], v[116:119]
	v_mfma_f32_16x16x32_bf16 v[104:107], v[152:155], v[238:241], v[104:107]
	v_mfma_f32_16x16x32_bf16 v[100:103], v[160:163], v[238:241], v[100:103]
	v_mfma_f32_16x16x32_bf16 v[88:91], v[152:155], v[246:249], v[88:91]
	v_mfma_f32_16x16x32_bf16 v[84:87], v[160:163], v[246:249], v[84:87]
	s_barrier
; #define PG8_GOFFS(slot_) do { _Pragma("unroll") for (int _i = 0; _i < 2; ++_i) { int R, C; stage_rc(tid * 16 + _i * 8192, R, C); _Pragma("unroll") for (int _h = 0; _h < 2; ++_h) { \
;         unsigned t_ = gtab[(slot_) * 256 + R + 128 * _h]; t_ = t_ < (unsigned)(T - 1) ? t_ : (unsigned)(T - 1); voffA[_h][_i] = (t_ * (unsigned)K + (unsigned)C) * 2u; } } } while (0)
; #define PG8_STAGE(bufoff, gbase, voff) do { _Pragma("unroll") for (int _i = 0; _i < 2; ++_i) \
;         __builtin_amdgcn_global_load_lds((const unsigned*)((const char*)(gbase) + (voff)[_i]), (LAS unsigned*)(lds + (bufoff) + ldsw + _i * 8192), 16, 0, 0); } while (0)
; #define PG8_STAGE_A1(bufoff, gbase) do { if (Epi::GATHER) PG8_STAGE(bufoff, gbase, voffA[1]); else PG8_STAGE(bufoff, (gbase) + hstep, voffA[0]); } while (0)
; #define PG8_LDA(dst, b, h) do { _Pragma("unroll") for (int m = 0; m < 4; ++m) _Pragma("unroll") for (int k = 0; k < 2; ++k) dst[m][k] = *(const LAS bf16x8*)(lds + PG8_SA(b, h) + aoff + m * 2048 + k * 1024); } while (0)
; #define PG8_BAR __builtin_amdgcn_s_barrier()
; template <class Epi, class Sched>
; __device__ __forceinline__ void gemm_phase(const int tid, LAS unsigned char* lds, const bf16* Aop, const bf16* Bop, const int K_, const Sched& S, const Epi& E, const bf16* Aop1 = nullptr, const bf16* Bop1 = nullptr) {
;     ...
;             PG8_LDB(B0, 0, 0); PG8_LDB(B1, 0, 1); PG8_SCHED; PG8_LDA(At, 0, 0); PG8_STAGE_A1(PG8_SA(1, 1), a1);
;             PG8_WAIT_V(8); PG8_WAIT_L(0); PG8_BAR; PG8_MMA(0, 0, At, B0); PG8_MMA(0, 1, At, B1); PG8_BAR; PG8_SCHED;
;             PG8_LDA(At, 0, 1); PG8_STAGE(PG8_SB(0, 0), b2, voffB); PG8_STAGE(PG8_SB(0, 1), b2 + hstep, voffB); if (Epi::GATHER && last && has_next) PG8_GOFFS((ui + 1) & 1); PG8_STAGE(PG8_SA(0, 0), a2, voffA[0]);
;             PG8_WAIT_V(8); PG8_WAIT_L(0); PG8_BAR; PG8_MMA(1, 0, At, B0); PG8_MMA(1, 1, At, B1); PG8_BAR; PG8_SCHED;
;             PG8_LDB(B0, 1, 0); PG8_LDB(B1, 1, 1); PG8_SCHED; PG8_LDA(At, 1, 0); PG8_STAGE_A1(PG8_SA(0, 1), a2);
;             PG8_WAIT_V(8); PG8_WAIT_L(0); PG8_BAR; PG8_MMA(0, 0, At, B0); PG8_MMA(0, 1, At, B1); PG8_BAR; PG8_SCHED;
;             PG8_LDA(At, 1, 1); PG8_STAGE(PG8_SB(1, 0), b3, voffB); PG8_STAGE(PG8_SB(1, 1), b3 + hstep, voffB); PG8_STAGE(PG8_SA(1, 0), a3, voffA[0]);
;             PG8_WAIT_V(8); PG8_WAIT_L(0); PG8_BAR; PG8_MMA(1, 0, At, B0); PG8_MMA(1, 1, At, B1); PG8_BAR; PG8_SCHED;
	s_add_i32 s40, s44, s69
	v_lshl_add_u64 v[164:165], v[164:165], 0, s[20:21]
	s_mov_b32 m0, s40
	ds_read_b128 v[206:209], v175 offset:49152
	ds_read_b128 v[210:213], v175 offset:50176
	ds_read_b128 v[214:217], v175 offset:51200
	ds_read_b128 v[218:221], v175 offset:52224
	ds_read_b128 v[230:233], v175 offset:53248
	ds_read_b128 v[238:241], v175 offset:54272
	ds_read_b128 v[242:245], v175 offset:55296
	ds_read_b128 v[246:249], v175 offset:56320
	global_load_lds_dwordx4 v[164:165], off
	v_lshl_add_u64 v[164:165], v[222:223], 0, s[20:21]
	s_add_i32 m0, s40, 0x2000
	s_add_i32 s40, s45, s69
	global_load_lds_dwordx4 v[164:165], off
	v_lshl_add_u64 v[164:165], v[250:251], 0, s[20:21]
	s_mov_b32 m0, s40
	s_nop 0
	global_load_lds_dwordx4 v[164:165], off
	v_lshl_add_u64 v[164:165], v[196:197], 0, s[20:21]
	s_add_i32 m0, s40, 0x2000
	s_nop 0
	global_load_lds_dwordx4 v[164:165], off
	v_lshl_add_u64 v[164:165], v[198:199], 0, s[20:21]
	s_mov_b32 m0, s75
	s_nop 0
	global_load_lds_dwordx4 v[164:165], off
	v_lshl_add_u64 v[164:165], v[224:225], 0, s[20:21]
	s_mov_b32 m0, s76
	s_nop 0
	global_load_lds_dwordx4 v[164:165], off
	s_waitcnt vmcnt(8)
	s_waitcnt lgkmcnt(0)
	s_barrier
	v_mfma_f32_16x16x32_bf16 v[72:75], v[60:63], v[206:209], v[72:75]
	v_mfma_f32_16x16x32_bf16 v[64:67], v[76:79], v[206:209], v[64:67]
	v_mfma_f32_16x16x32_bf16 v[48:51], v[60:63], v[214:217], v[48:51]
	v_mfma_f32_16x16x32_bf16 v[44:47], v[76:79], v[214:217], v[44:47]
	v_mfma_f32_16x16x32_bf16 v[32:35], v[60:63], v[230:233], v[32:35]
	v_mfma_f32_16x16x32_bf16 v[28:31], v[76:79], v[230:233], v[28:31]
	v_mfma_f32_16x16x32_bf16 v[16:19], v[60:63], v[242:245], v[16:19]
	v_mfma_f32_16x16x32_bf16 v[12:15], v[76:79], v[242:245], v[12:15]
	v_mfma_f32_16x16x32_bf16 v[72:75], v[68:71], v[210:213], v[72:75]
	v_mfma_f32_16x16x32_bf16 v[64:67], v[80:83], v[210:213], v[64:67]
	v_mfma_f32_16x16x32_bf16 v[48:51], v[68:71], v[218:221], v[48:51]
	v_mfma_f32_16x16x32_bf16 v[44:47], v[80:83], v[218:221], v[44:47]
	v_mfma_f32_16x16x32_bf16 v[32:35], v[68:71], v[238:241], v[32:35]
	v_mfma_f32_16x16x32_bf16 v[28:31], v[80:83], v[238:241], v[28:31]
	v_mfma_f32_16x16x32_bf16 v[16:19], v[68:71], v[246:249], v[16:19]
	v_mfma_f32_16x16x32_bf16 v[12:15], v[80:83], v[246:249], v[12:15]
	v_mfma_f32_16x16x32_bf16 v[56:59], v[148:151], v[206:209], v[56:59]
	v_mfma_f32_16x16x32_bf16 v[52:55], v[156:159], v[206:209], v[52:55]
	v_mfma_f32_16x16x32_bf16 v[40:43], v[148:151], v[214:217], v[40:43]
	v_mfma_f32_16x16x32_bf16 v[36:39], v[156:159], v[214:217], v[36:39]
	v_mfma_f32_16x16x32_bf16 v[24:27], v[148:151], v[230:233], v[24:27]
	v_mfma_f32_16x16x32_bf16 v[20:23], v[156:159], v[230:233], v[20:23]
	v_mfma_f32_16x16x32_bf16 v[8:11], v[148:151], v[242:245], v[8:11]
	v_mfma_f32_16x16x32_bf16 v[4:7], v[156:159], v[242:245], v[4:7]
	v_mfma_f32_16x16x32_bf16 v[56:59], v[152:155], v[210:213], v[56:59]
	v_mfma_f32_16x16x32_bf16 v[52:55], v[160:163], v[210:213], v[52:55]
	v_mfma_f32_16x16x32_bf16 v[40:43], v[152:155], v[218:221], v[40:43]
	v_mfma_f32_16x16x32_bf16 v[36:39], v[160:163], v[218:221], v[36:39]
	v_mfma_f32_16x16x32_bf16 v[24:27], v[152:155], v[238:241], v[24:27]
	v_mfma_f32_16x16x32_bf16 v[20:23], v[160:163], v[238:241], v[20:23]
	v_mfma_f32_16x16x32_bf16 v[8:11], v[152:155], v[246:249], v[8:11]
	v_mfma_f32_16x16x32_bf16 v[4:7], v[160:163], v[246:249], v[4:7]
	s_barrier
	s_add_u32 s26, s26, 0x100
	s_addc_u32 s27, s27, 0
	s_add_u32 s11, s11, 0x100
	s_addc_u32 s42, s42, 0
	s_cmp_ge_i32 s43, s74
	s_mov_b32 s40, s43
	s_cbranch_scc0 .LBB0_131
	s_branch .Lpeel_exit_131
.LBB0_131:
	s_add_i32 s43, s40, 2
	s_add_u32 s44, s26, 0x80
	s_addc_u32 s41, s27, 0
	s_add_i32 s48, 0, 0x10000
	s_cmp_eq_u32 s77, s40
	s_cselect_b32 s41, s35, s41
	s_cselect_b32 s40, s34, s44
	s_cselect_b32 s45, s37, s42
	s_cselect_b32 s44, s36, s11
	s_add_i32 s49, 0, 0x14000
	v_add_u32_e32 v80, s48, v3
	v_add_u32_e32 v160, s49, v3
	ds_read_b128 v[60:63], v80
	ds_read_b128 v[68:71], v80 offset:1024
	ds_read_b128 v[76:79], v80 offset:2048
	ds_read_b128 v[80:83], v80 offset:3072
	ds_read_b128 v[148:151], v160
	ds_read_b128 v[152:155], v160 offset:1024
	ds_read_b128 v[156:159], v160 offset:2048
	ds_read_b128 v[160:163], v160 offset:3072
	v_lshl_add_u64 v[164:165], s[26:27], 0, v[192:193]
	s_add_i32 m0, s70, 0xc000
	ds_read_b128 v[206:209], v175
	ds_read_b128 v[210:213], v175 offset:1024
	ds_read_b128 v[214:217], v175 offset:2048
	ds_read_b128 v[218:221], v175 offset:3072
	ds_read_b128 v[238:241], v175 offset:4096
	ds_read_b128 v[242:245], v175 offset:5120
	ds_read_b128 v[246:249], v175 offset:6144
	ds_read_b128 v[230:233], v175 offset:7168
	global_load_lds_dwordx4 v[164:165], off
	v_lshl_add_u64 v[164:165], s[26:27], 0, v[194:195]
	s_add_i32 m0, s70, 0xe000
	s_nop 0
	global_load_lds_dwordx4 v[164:165], off
	s_waitcnt vmcnt(8)
	s_waitcnt lgkmcnt(0)
	s_barrier
; #define PG8_GOFFS(slot_) do { _Pragma("unroll") for (int _i = 0; _i < 2; ++_i) { int R, C; stage_rc(tid * 16 + _i * 8192, R, C); _Pragma("unroll") for (int _h = 0; _h < 2; ++_h) { \
;         unsigned t_ = gtab[(slot_) * 256 + R + 128 * _h]; t_ = t_ < (unsigned)(T - 1) ? t_ : (unsigned)(T - 1); voffA[_h][_i] = (t_ * (unsigned)K + (unsigned)C) * 2u; } } } while (0)
; #define PG8_STAGE(bufoff, gbase, voff) do { _Pragma("unroll") for (int _i = 0; _i < 2; ++_i) \
;         __builtin_amdgcn_global_load_lds((const unsigned*)((const char*)(gbase) + (voff)[_i]), (LAS unsigned*)(lds + (bufoff) + ldsw + _i * 8192), 16, 0, 0); } while (0)
; #define PG8_STAGE_A1(bufoff, gbase) do { if (Epi::GATHER) PG8_STAGE(bufoff, gbase, voffA[1]); else PG8_STAGE(bufoff, (gbase) + hstep, voffA[0]); } while (0)
; #define PG8_LDA(dst, b, h) do { _Pragma("unroll") for (int m = 0; m < 4; ++m) _Pragma("unroll") for (int k = 0; k < 2; ++k) dst[m][k] = *(const LAS bf16x8*)(lds + PG8_SA(b, h) + aoff + m * 2048 + k * 1024); } while (0)
; #define PG8_LDB(dst, b, h) do { _Pragma("unroll") for (int n = 0; n < 2; ++n) _Pragma("unroll") for (int k = 0; k < 2; ++k) dst[n][k] = *(const LAS bf16x8*)(lds + PG8_SB(b, h) + boff + n * 2048 + k * 1024); } while (0)
; #define PG8_WAIT_V(n) asm volatile("s_waitcnt vmcnt(" #n ")" ::: "memory")
; #define PG8_WAIT_L(n) asm volatile("s_waitcnt lgkmcnt(" #n ")" ::: "memory")
; #define PG8_BAR __builtin_amdgcn_s_barrier()
; #define PG8_SCHED __builtin_amdgcn_sched_barrier(0)
; template <class Epi, class Sched>
; __device__ __forceinline__ void gemm_phase(const int tid, LAS unsigned char* lds, const bf16* Aop, const bf16* Bop, const int K_, const Sched& S, const Epi& E, const bf16* Aop1 = nullptr, const bf16* Bop1 = nullptr) {
;     ...
;             PG8_WAIT_V(8); PG8_WAIT_L(0); PG8_BAR; PG8_MMA(0, 0, At, B0); PG8_MMA(0, 1, At, B1); PG8_BAR; PG8_SCHED;
;             PG8_LDA(At, 0, 1); PG8_STAGE(PG8_SB(0, 0), b2, voffB); PG8_STAGE(PG8_SB(0, 1), b2 + hstep, voffB); if (Epi::GATHER && last && has_next) PG8_GOFFS((ui + 1) & 1); PG8_STAGE(PG8_SA(0, 0), a2, voffA[0]);
;             PG8_WAIT_V(8); PG8_WAIT_L(0); PG8_BAR; PG8_MMA(1, 0, At, B0); PG8_MMA(1, 1, At, B1); PG8_BAR; PG8_SCHED;
;             PG8_LDB(B0, 1, 0); PG8_LDB(B1, 1, 1); PG8_SCHED; PG8_LDA(At, 1, 0); PG8_STAGE_A1(PG8_SA(0, 1), a2);
	v_mfma_f32_16x16x32_bf16 v[140:143], v[60:63], v[206:209], v[140:143]
	v_mfma_f32_16x16x32_bf16 v[144:147], v[76:79], v[206:209], v[144:147]
	v_mfma_f32_16x16x32_bf16 v[128:131], v[60:63], v[214:217], v[128:131]
	v_mfma_f32_16x16x32_bf16 v[124:127], v[76:79], v[214:217], v[124:127]
	v_mfma_f32_16x16x32_bf16 v[112:115], v[60:63], v[238:241], v[112:115]
	v_mfma_f32_16x16x32_bf16 v[108:111], v[76:79], v[238:241], v[108:111]
	v_mfma_f32_16x16x32_bf16 v[96:99], v[60:63], v[246:249], v[96:99]
	v_mfma_f32_16x16x32_bf16 v[92:95], v[76:79], v[246:249], v[92:95]
	v_mfma_f32_16x16x32_bf16 v[140:143], v[68:71], v[210:213], v[140:143]
	v_mfma_f32_16x16x32_bf16 v[144:147], v[80:83], v[210:213], v[144:147]
	v_mfma_f32_16x16x32_bf16 v[128:131], v[68:71], v[218:221], v[128:131]
	v_mfma_f32_16x16x32_bf16 v[124:127], v[80:83], v[218:221], v[124:127]
	v_mfma_f32_16x16x32_bf16 v[112:115], v[68:71], v[242:245], v[112:115]
	v_mfma_f32_16x16x32_bf16 v[108:111], v[80:83], v[242:245], v[108:111]
	v_mfma_f32_16x16x32_bf16 v[96:99], v[68:71], v[230:233], v[96:99]
	v_mfma_f32_16x16x32_bf16 v[92:95], v[80:83], v[230:233], v[92:95]
	v_mfma_f32_16x16x32_bf16 v[136:139], v[148:151], v[206:209], v[136:139]
	v_mfma_f32_16x16x32_bf16 v[132:135], v[156:159], v[206:209], v[132:135]
	v_mfma_f32_16x16x32_bf16 v[120:123], v[148:151], v[214:217], v[120:123]
	v_mfma_f32_16x16x32_bf16 v[116:119], v[156:159], v[214:217], v[116:119]
	v_mfma_f32_16x16x32_bf16 v[104:107], v[148:151], v[238:241], v[104:107]
	v_mfma_f32_16x16x32_bf16 v[100:103], v[156:159], v[238:241], v[100:103]
	v_mfma_f32_16x16x32_bf16 v[88:91], v[148:151], v[246:249], v[88:91]
	v_mfma_f32_16x16x32_bf16 v[84:87], v[156:159], v[246:249], v[84:87]
	v_mfma_f32_16x16x32_bf16 v[136:139], v[152:155], v[210:213], v[136:139]
	v_mfma_f32_16x16x32_bf16 v[132:135], v[160:163], v[210:213], v[132:135]
	v_mfma_f32_16x16x32_bf16 v[120:123], v[152:155], v[218:221], v[120:123]
	v_mfma_f32_16x16x32_bf16 v[116:119], v[160:163], v[218:221], v[116:119]
	v_mfma_f32_16x16x32_bf16 v[104:107], v[152:155], v[242:245], v[104:107]
	v_mfma_f32_16x16x32_bf16 v[100:103], v[160:163], v[242:245], v[100:103]
	v_mfma_f32_16x16x32_bf16 v[88:91], v[152:155], v[230:233], v[88:91]
	v_mfma_f32_16x16x32_bf16 v[84:87], v[160:163], v[230:233], v[84:87]
	s_barrier
	s_add_i32 s48, s48, s69
	v_lshl_add_u64 v[164:165], s[44:45], 0, v[166:167]
	s_mov_b32 m0, s48
	ds_read_b128 v[206:209], v175 offset:16384
	ds_read_b128 v[210:213], v175 offset:17408
	ds_read_b128 v[214:217], v175 offset:18432
	ds_read_b128 v[218:221], v175 offset:19456
	ds_read_b128 v[230:233], v175 offset:20480
	ds_read_b128 v[238:241], v175 offset:21504
	ds_read_b128 v[242:245], v175 offset:22528
	ds_read_b128 v[246:249], v175 offset:23552
	global_load_lds_dwordx4 v[164:165], off
	s_add_i32 m0, s48, 0x2000
	v_lshl_add_u64 v[222:223], s[44:45], 0, v[170:171]
	s_add_u32 s44, s44, s6
	s_addc_u32 s45, s45, s7
	s_add_i32 s48, s49, s69
	global_load_lds_dwordx4 v[222:223], off
	v_lshl_add_u64 v[250:251], s[44:45], 0, v[166:167]
	s_mov_b32 m0, s48
	v_lshl_add_u64 v[196:197], s[44:45], 0, v[170:171]
	global_load_lds_dwordx4 v[250:251], off
	s_add_i32 m0, s48, 0x2000
	v_lshl_add_u64 v[198:199], s[40:41], 0, v[0:1]
	global_load_lds_dwordx4 v[196:197], off
	s_mov_b32 m0, s70
	v_lshl_add_u64 v[224:225], s[40:41], 0, v[168:169]
	global_load_lds_dwordx4 v[198:199], off
	s_mov_b32 m0, s71
	s_nop 0
	global_load_lds_dwordx4 v[224:225], off
	s_waitcnt vmcnt(8)
	s_waitcnt lgkmcnt(0)
	s_barrier
	v_mfma_f32_16x16x32_bf16 v[72:75], v[60:63], v[206:209], v[72:75]
	v_mfma_f32_16x16x32_bf16 v[64:67], v[76:79], v[206:209], v[64:67]
	v_mfma_f32_16x16x32_bf16 v[48:51], v[60:63], v[214:217], v[48:51]
	v_mfma_f32_16x16x32_bf16 v[44:47], v[76:79], v[214:217], v[44:47]
	v_mfma_f32_16x16x32_bf16 v[32:35], v[60:63], v[230:233], v[32:35]
	v_mfma_f32_16x16x32_bf16 v[28:31], v[76:79], v[230:233], v[28:31]
	v_mfma_f32_16x16x32_bf16 v[16:19], v[60:63], v[242:245], v[16:19]
	v_mfma_f32_16x16x32_bf16 v[12:15], v[76:79], v[242:245], v[12:15]
	v_mfma_f32_16x16x32_bf16 v[72:75], v[68:71], v[210:213], v[72:75]
	v_mfma_f32_16x16x32_bf16 v[64:67], v[80:83], v[210:213], v[64:67]
	v_mfma_f32_16x16x32_bf16 v[48:51], v[68:71], v[218:221], v[48:51]
	v_mfma_f32_16x16x32_bf16 v[44:47], v[80:83], v[218:221], v[44:47]
	v_mfma_f32_16x16x32_bf16 v[32:35], v[68:71], v[238:241], v[32:35]
	v_mfma_f32_16x16x32_bf16 v[28:31], v[80:83], v[238:241], v[28:31]
	v_mfma_f32_16x16x32_bf16 v[16:19], v[68:71], v[246:249], v[16:19]
	v_mfma_f32_16x16x32_bf16 v[12:15], v[80:83], v[246:249], v[12:15]
	v_mfma_f32_16x16x32_bf16 v[56:59], v[148:151], v[206:209], v[56:59]
	v_mfma_f32_16x16x32_bf16 v[52:55], v[156:159], v[206:209], v[52:55]
	v_mfma_f32_16x16x32_bf16 v[40:43], v[148:151], v[214:217], v[40:43]
	v_mfma_f32_16x16x32_bf16 v[36:39], v[156:159], v[214:217], v[36:39]
	v_mfma_f32_16x16x32_bf16 v[24:27], v[148:151], v[230:233], v[24:27]
	v_mfma_f32_16x16x32_bf16 v[20:23], v[156:159], v[230:233], v[20:23]
	v_mfma_f32_16x16x32_bf16 v[8:11], v[148:151], v[242:245], v[8:11]
	v_mfma_f32_16x16x32_bf16 v[4:7], v[156:159], v[242:245], v[4:7]
	v_mfma_f32_16x16x32_bf16 v[56:59], v[152:155], v[210:213], v[56:59]
	v_mfma_f32_16x16x32_bf16 v[52:55], v[160:163], v[210:213], v[52:55]
	v_mfma_f32_16x16x32_bf16 v[40:43], v[152:155], v[218:221], v[40:43]
	v_mfma_f32_16x16x32_bf16 v[36:39], v[160:163], v[218:221], v[36:39]
	v_mfma_f32_16x16x32_bf16 v[24:27], v[152:155], v[238:241], v[24:27]
	v_mfma_f32_16x16x32_bf16 v[20:23], v[160:163], v[238:241], v[20:23]
	v_mfma_f32_16x16x32_bf16 v[8:11], v[152:155], v[246:249], v[8:11]
	v_mfma_f32_16x16x32_bf16 v[4:7], v[160:163], v[246:249], v[4:7]
	s_barrier
; #define PG8_STAGE(bufoff, gbase, voff) do { _Pragma("unroll") for (int _i = 0; _i < 2; ++_i) \
;         __builtin_amdgcn_global_load_lds((const unsigned*)((const char*)(gbase) + (voff)[_i]), (LAS unsigned*)(lds + (bufoff) + ldsw + _i * 8192), 16, 0, 0); } while (0)
; #define PG8_STAGE_A1(bufoff, gbase) do { if (Epi::GATHER) PG8_STAGE(bufoff, gbase, voffA[1]); else PG8_STAGE(bufoff, (gbase) + hstep, voffA[0]); } while (0)
; #define PG8_LDA(dst, b, h) do { _Pragma("unroll") for (int m = 0; m < 4; ++m) _Pragma("unroll") for (int k = 0; k < 2; ++k) dst[m][k] = *(const LAS bf16x8*)(lds + PG8_SA(b, h) + aoff + m * 2048 + k * 1024); } while (0)
; #define PG8_LDB(dst, b, h) do { _Pragma("unroll") for (int n = 0; n < 2; ++n) _Pragma("unroll") for (int k = 0; k < 2; ++k) dst[n][k] = *(const LAS bf16x8*)(lds + PG8_SB(b, h) + boff + n * 2048 + k * 1024); } while (0)
; #define PG8_MMA(ai, bj, At, Bt) do { __builtin_amdgcn_s_setprio(1); _Pragma("unroll") for (int m = 0; m < 4; ++m) _Pragma("unroll") for (int n = 0; n < 2; ++n) _Pragma("unroll") for (int k = 0; k < 2; ++k) \
;         acc[ai][bj][m][n] = __builtin_amdgcn_mfma_f32_16x16x32_bf16(Bt[n][k], At[m][k], acc[ai][bj][m][n], 0, 0, 0); __builtin_amdgcn_s_setprio(0); } while (0)
; #define PG8_WAIT_V(n) asm volatile("s_waitcnt vmcnt(" #n ")" ::: "memory")
; #define PG8_WAIT_L(n) asm volatile("s_waitcnt lgkmcnt(" #n ")" ::: "memory")
; #define PG8_BAR __builtin_amdgcn_s_barrier()
; #define PG8_SCHED __builtin_amdgcn_sched_barrier(0)
; template <class Epi, class Sched>
; __device__ __forceinline__ void gemm_phase(const int tid, LAS unsigned char* lds, const bf16* Aop, const bf16* Bop, const int K_, const Sched& S, const Epi& E, const bf16* Aop1 = nullptr, const bf16* Bop1 = nullptr) {
;     ...
;             PG8_LDB(B0, 1, 0); PG8_LDB(B1, 1, 1); PG8_SCHED; PG8_LDA(At, 1, 0); PG8_STAGE_A1(PG8_SA(0, 1), a2);
;             PG8_WAIT_V(8); PG8_WAIT_L(0); PG8_BAR; PG8_MMA(0, 0, At, B0); PG8_MMA(0, 1, At, B1); PG8_BAR; PG8_SCHED;
;             PG8_LDA(At, 1, 1); PG8_STAGE(PG8_SB(1, 0), b3, voffB); PG8_STAGE(PG8_SB(1, 1), b3 + hstep, voffB); PG8_STAGE(PG8_SA(1, 0), a3, voffA[0]);
;             PG8_WAIT_V(8); PG8_WAIT_L(0); PG8_BAR; PG8_MMA(1, 0, At, B0); PG8_MMA(1, 1, At, B1); PG8_BAR; PG8_SCHED;
	s_add_i32 s44, 0, 0x18000
	s_add_i32 s45, 0, 0x1c000
	v_add_u32_e32 v80, s44, v3
	v_add_u32_e32 v160, s45, v3
	ds_read_b128 v[60:63], v80
	ds_read_b128 v[68:71], v80 offset:1024
	ds_read_b128 v[76:79], v80 offset:2048
	ds_read_b128 v[80:83], v80 offset:3072
	ds_read_b128 v[148:151], v160
	ds_read_b128 v[152:155], v160 offset:1024
	ds_read_b128 v[156:159], v160 offset:2048
	ds_read_b128 v[160:163], v160 offset:3072
	s_add_u32 s40, s40, s6
	s_addc_u32 s41, s41, s7
	s_mov_b32 m0, s72
	v_lshl_add_u64 v[190:191], s[40:41], 0, v[0:1]
	ds_read_b128 v[206:209], v175 offset:32768
	ds_read_b128 v[210:213], v175 offset:33792
	ds_read_b128 v[214:217], v175 offset:34816
	ds_read_b128 v[218:221], v175 offset:35840
	ds_read_b128 v[230:233], v175 offset:36864
	ds_read_b128 v[238:241], v175 offset:37888
	ds_read_b128 v[242:245], v175 offset:38912
	ds_read_b128 v[246:249], v175 offset:39936
	global_load_lds_dwordx4 v[190:191], off
	v_lshl_add_u64 v[190:191], s[40:41], 0, v[168:169]
	s_mov_b32 m0, s73
	s_nop 0
	global_load_lds_dwordx4 v[190:191], off
	s_waitcnt vmcnt(8)
	s_waitcnt lgkmcnt(0)
	s_barrier
	v_mfma_f32_16x16x32_bf16 v[140:143], v[60:63], v[206:209], v[140:143]
	v_mfma_f32_16x16x32_bf16 v[144:147], v[76:79], v[206:209], v[144:147]
	v_mfma_f32_16x16x32_bf16 v[128:131], v[60:63], v[214:217], v[128:131]
	v_mfma_f32_16x16x32_bf16 v[124:127], v[76:79], v[214:217], v[124:127]
	v_mfma_f32_16x16x32_bf16 v[112:115], v[60:63], v[230:233], v[112:115]
	v_mfma_f32_16x16x32_bf16 v[108:111], v[76:79], v[230:233], v[108:111]
	v_mfma_f32_16x16x32_bf16 v[96:99], v[60:63], v[242:245], v[96:99]
	v_mfma_f32_16x16x32_bf16 v[92:95], v[76:79], v[242:245], v[92:95]
	v_mfma_f32_16x16x32_bf16 v[140:143], v[68:71], v[210:213], v[140:143]
	v_mfma_f32_16x16x32_bf16 v[144:147], v[80:83], v[210:213], v[144:147]
	v_mfma_f32_16x16x32_bf16 v[128:131], v[68:71], v[218:221], v[128:131]
	v_mfma_f32_16x16x32_bf16 v[124:127], v[80:83], v[218:221], v[124:127]
	v_mfma_f32_16x16x32_bf16 v[112:115], v[68:71], v[238:241], v[112:115]
	v_mfma_f32_16x16x32_bf16 v[108:111], v[80:83], v[238:241], v[108:111]
	v_mfma_f32_16x16x32_bf16 v[96:99], v[68:71], v[246:249], v[96:99]
	v_mfma_f32_16x16x32_bf16 v[92:95], v[80:83], v[246:249], v[92:95]
	v_mfma_f32_16x16x32_bf16 v[136:139], v[148:151], v[206:209], v[136:139]
	v_mfma_f32_16x16x32_bf16 v[132:135], v[156:159], v[206:209], v[132:135]
	v_mfma_f32_16x16x32_bf16 v[120:123], v[148:151], v[214:217], v[120:123]
	v_mfma_f32_16x16x32_bf16 v[116:119], v[156:159], v[214:217], v[116:119]
	v_mfma_f32_16x16x32_bf16 v[104:107], v[148:151], v[230:233], v[104:107]
	v_mfma_f32_16x16x32_bf16 v[100:103], v[156:159], v[230:233], v[100:103]
	v_mfma_f32_16x16x32_bf16 v[88:91], v[148:151], v[242:245], v[88:91]
	v_mfma_f32_16x16x32_bf16 v[84:87], v[156:159], v[242:245], v[84:87]
	v_mfma_f32_16x16x32_bf16 v[136:139], v[152:155], v[210:213], v[136:139]
	v_mfma_f32_16x16x32_bf16 v[132:135], v[160:163], v[210:213], v[132:135]
	v_mfma_f32_16x16x32_bf16 v[120:123], v[152:155], v[218:221], v[120:123]
	v_mfma_f32_16x16x32_bf16 v[116:119], v[160:163], v[218:221], v[116:119]
	v_mfma_f32_16x16x32_bf16 v[104:107], v[152:155], v[238:241], v[104:107]
	v_mfma_f32_16x16x32_bf16 v[100:103], v[160:163], v[238:241], v[100:103]
	v_mfma_f32_16x16x32_bf16 v[88:91], v[152:155], v[246:249], v[88:91]
	v_mfma_f32_16x16x32_bf16 v[84:87], v[160:163], v[246:249], v[84:87]
	s_barrier
	s_add_i32 s40, s44, s69
	v_lshl_add_u64 v[164:165], v[164:165], 0, s[20:21]
	s_mov_b32 m0, s40
	ds_read_b128 v[206:209], v175 offset:49152
	ds_read_b128 v[210:213], v175 offset:50176
	ds_read_b128 v[214:217], v175 offset:51200
	ds_read_b128 v[218:221], v175 offset:52224
	ds_read_b128 v[230:233], v175 offset:53248
	ds_read_b128 v[238:241], v175 offset:54272
	ds_read_b128 v[242:245], v175 offset:55296
	ds_read_b128 v[246:249], v175 offset:56320
	global_load_lds_dwordx4 v[164:165], off
	v_lshl_add_u64 v[164:165], v[222:223], 0, s[20:21]
	s_add_i32 m0, s40, 0x2000
	s_add_i32 s40, s45, s69
	global_load_lds_dwordx4 v[164:165], off
	v_lshl_add_u64 v[164:165], v[250:251], 0, s[20:21]
	s_mov_b32 m0, s40
	s_nop 0
	global_load_lds_dwordx4 v[164:165], off
	v_lshl_add_u64 v[164:165], v[196:197], 0, s[20:21]
	s_add_i32 m0, s40, 0x2000
	s_nop 0
	global_load_lds_dwordx4 v[164:165], off
	v_lshl_add_u64 v[164:165], v[198:199], 0, s[20:21]
	s_mov_b32 m0, s75
	s_nop 0
	global_load_lds_dwordx4 v[164:165], off
	v_lshl_add_u64 v[164:165], v[224:225], 0, s[20:21]
	s_mov_b32 m0, s76
	s_nop 0
	global_load_lds_dwordx4 v[164:165], off
	s_waitcnt vmcnt(8)
	s_waitcnt lgkmcnt(0)
	s_barrier
	v_mfma_f32_16x16x32_bf16 v[72:75], v[60:63], v[206:209], v[72:75]
	v_mfma_f32_16x16x32_bf16 v[64:67], v[76:79], v[206:209], v[64:67]
	v_mfma_f32_16x16x32_bf16 v[48:51], v[60:63], v[214:217], v[48:51]
	v_mfma_f32_16x16x32_bf16 v[44:47], v[76:79], v[214:217], v[44:47]
	v_mfma_f32_16x16x32_bf16 v[32:35], v[60:63], v[230:233], v[32:35]
	v_mfma_f32_16x16x32_bf16 v[28:31], v[76:79], v[230:233], v[28:31]
	v_mfma_f32_16x16x32_bf16 v[16:19], v[60:63], v[242:245], v[16:19]
	v_mfma_f32_16x16x32_bf16 v[12:15], v[76:79], v[242:245], v[12:15]
	v_mfma_f32_16x16x32_bf16 v[72:75], v[68:71], v[210:213], v[72:75]
	v_mfma_f32_16x16x32_bf16 v[64:67], v[80:83], v[210:213], v[64:67]
	v_mfma_f32_16x16x32_bf16 v[48:51], v[68:71], v[218:221], v[48:51]
	v_mfma_f32_16x16x32_bf16 v[44:47], v[80:83], v[218:221], v[44:47]
	v_mfma_f32_16x16x32_bf16 v[32:35], v[68:71], v[238:241], v[32:35]
	v_mfma_f32_16x16x32_bf16 v[28:31], v[80:83], v[238:241], v[28:31]
	v_mfma_f32_16x16x32_bf16 v[16:19], v[68:71], v[246:249], v[16:19]
	v_mfma_f32_16x16x32_bf16 v[12:15], v[80:83], v[246:249], v[12:15]
	v_mfma_f32_16x16x32_bf16 v[56:59], v[148:151], v[206:209], v[56:59]
	v_mfma_f32_16x16x32_bf16 v[52:55], v[156:159], v[206:209], v[52:55]
	v_mfma_f32_16x16x32_bf16 v[40:43], v[148:151], v[214:217], v[40:43]
	v_mfma_f32_16x16x32_bf16 v[36:39], v[156:159], v[214:217], v[36:39]
	v_mfma_f32_16x16x32_bf16 v[24:27], v[148:151], v[230:233], v[24:27]
	v_mfma_f32_16x16x32_bf16 v[20:23], v[156:159], v[230:233], v[20:23]
	v_mfma_f32_16x16x32_bf16 v[8:11], v[148:151], v[242:245], v[8:11]
	v_mfma_f32_16x16x32_bf16 v[4:7], v[156:159], v[242:245], v[4:7]
	v_mfma_f32_16x16x32_bf16 v[56:59], v[152:155], v[210:213], v[56:59]
	v_mfma_f32_16x16x32_bf16 v[52:55], v[160:163], v[210:213], v[52:55]
	v_mfma_f32_16x16x32_bf16 v[40:43], v[152:155], v[218:221], v[40:43]
	v_mfma_f32_16x16x32_bf16 v[36:39], v[160:163], v[218:221], v[36:39]
	v_mfma_f32_16x16x32_bf16 v[24:27], v[152:155], v[238:241], v[24:27]
	v_mfma_f32_16x16x32_bf16 v[20:23], v[160:163], v[238:241], v[20:23]
	v_mfma_f32_16x16x32_bf16 v[8:11], v[152:155], v[246:249], v[8:11]
	v_mfma_f32_16x16x32_bf16 v[4:7], v[160:163], v[246:249], v[4:7]
	s_barrier
	s_add_u32 s26, s26, 0x100
	s_addc_u32 s27, s27, 0
	s_add_u32 s11, s11, 0x100
	s_addc_u32 s42, s42, 0
	s_cmp_ge_i32 s43, s74
	s_mov_b32 s40, s43
	s_cbranch_scc0 .LBB0_131

; #define PG8_GOFFS(slot_) do { _Pragma("unroll") for (int _i = 0; _i < 2; ++_i) { int R, C; stage_rc(tid * 16 + _i * 8192, R, C); _Pragma("unroll") for (int _h = 0; _h < 2; ++_h) { \
;         unsigned t_ = gtab[(slot_) * 256 + R + 128 * _h]; t_ = t_ < (unsigned)(T - 1) ? t_ : (unsigned)(T - 1); voffA[_h][_i] = (t_ * (unsigned)K + (unsigned)C) * 2u; } } } while (0)
; #define PG8_STAGE(bufoff, gbase, voff) do { _Pragma("unroll") for (int _i = 0; _i < 2; ++_i) \
;         __builtin_amdgcn_global_load_lds((const unsigned*)((const char*)(gbase) + (voff)[_i]), (LAS unsigned*)(lds + (bufoff) + ldsw + _i * 8192), 16, 0, 0); } while (0)
; #define PG8_STAGE_A1(bufoff, gbase) do { if (Epi::GATHER) PG8_STAGE(bufoff, gbase, voffA[1]); else PG8_STAGE(bufoff, (gbase) + hstep, voffA[0]); } while (0)
; #define PG8_LDA(dst, b, h) do { _Pragma("unroll") for (int m = 0; m < 4; ++m) _Pragma("unroll") for (int k = 0; k < 2; ++k) dst[m][k] = *(const LAS bf16x8*)(lds + PG8_SA(b, h) + aoff + m * 2048 + k * 1024); } while (0)
; #define PG8_WAIT_V(n) asm volatile("s_waitcnt vmcnt(" #n ")" ::: "memory")
; #define PG8_WAIT_L(n) asm volatile("s_waitcnt lgkmcnt(" #n ")" ::: "memory")
; #define PG8_BAR __builtin_amdgcn_s_barrier()
; template <class Epi, class Sched>
; __device__ __forceinline__ void gemm_phase(const int tid, LAS unsigned char* lds, const bf16* Aop, const bf16* Bop, const int K_, const Sched& S, const Epi& E, const bf16* Aop1 = nullptr, const bf16* Bop1 = nullptr) {
;     ...
;         for (int t = 0; t < nt; t += 2) {
;             const bool last = (t == nt - 2);
;             const char* a1 = cA + (size_t)(t + 1) * kstep;
;             const char* a2 = last ? nA : cA + (size_t)(t + 2) * kstep; const char* b2 = last ? nB : cB + (size_t)(t + 2) * kstep;
;             const char* a3 = a2 + kstep; const char* b3 = b2 + kstep;
;             PG8_LDB(B0, 0, 0); PG8_LDB(B1, 0, 1); PG8_SCHED; PG8_LDA(At, 0, 0); PG8_STAGE_A1(PG8_SA(1, 1), a1);
;             PG8_WAIT_V(8); PG8_WAIT_L(0); PG8_BAR; PG8_MMA(0, 0, At, B0); PG8_MMA(0, 1, At, B1); PG8_BAR; PG8_SCHED;
;             PG8_LDA(At, 0, 1); PG8_STAGE(PG8_SB(0, 0), b2, voffB); PG8_STAGE(PG8_SB(0, 1), b2 + hstep, voffB); if (Epi::GATHER && last && has_next) PG8_GOFFS((ui + 1) & 1); PG8_STAGE(PG8_SA(0, 0), a2, voffA[0]);
;             PG8_WAIT_V(8); PG8_WAIT_L(0); PG8_BAR; PG8_MMA(1, 0, At, B0); PG8_MMA(1, 1, At, B1); PG8_BAR; PG8_SCHED;
.LBB0_998:
	v_mov_b32_e32 v131, 0
	s_andn2_b64 vcc, exec, s[44:45]
	s_cbranch_vccnz .LBB0_1001
	s_add_u32 s12, s12, 0x80
	s_addc_u32 s13, s13, 0
	s_add_u32 s11, s26, 0x100
	s_addc_u32 s71, s27, 0
	s_mov_b32 s26, 0
	s_add_i32 s72, s26, 2
	s_add_u32 s73, s12, 0x80
	s_addc_u32 s27, s13, 0
	s_add_i32 s76, 0, 0x10000
	s_cmp_eq_u32 s64, s26
	s_cselect_b32 s27, s7, s27
	s_cselect_b32 s26, s6, s73
	s_cselect_b32 s75, s41, s71
	s_cselect_b32 s74, s40, s11
	s_add_i32 s73, 0, 0x14000
	v_add_u32_e32 v156, s76, v171
	v_add_u32_e32 v178, s73, v171
	ds_read_b128 v[132:135], v156
	ds_read_b128 v[148:151], v156 offset:1024
	ds_read_b128 v[152:155], v156 offset:2048
	ds_read_b128 v[156:159], v156 offset:3072
	ds_read_b128 v[160:163], v178
	ds_read_b128 v[164:167], v178 offset:1024
	ds_read_b128 v[174:177], v178 offset:2048
	ds_read_b128 v[178:181], v178 offset:3072
	v_lshl_add_u64 v[194:195], s[12:13], 0, v[144:145]
	s_add_i32 m0, s56, 0xc000
	ds_read_b128 v[182:185], v173
	ds_read_b128 v[186:189], v173 offset:1024
	ds_read_b128 v[190:193], v173 offset:2048
	ds_read_b128 v[202:205], v173 offset:3072
	ds_read_b128 v[206:209], v173 offset:4096
	ds_read_b128 v[210:213], v173 offset:5120
	ds_read_b128 v[214:217], v173 offset:6144
	ds_read_b128 v[218:221], v173 offset:7168
	global_load_lds_dwordx4 v[194:195], off
	v_lshl_add_u64 v[194:195], s[12:13], 0, v[146:147]
	s_add_i32 m0, s56, 0xe000
	s_nop 0
	global_load_lds_dwordx4 v[194:195], off
	s_waitcnt vmcnt(8)
	s_waitcnt lgkmcnt(0)
	s_barrier
	v_mfma_f32_16x16x32_bf16 v[128:131], v[132:135], v[182:185], 0
	v_mfma_f32_16x16x32_bf16 v[124:127], v[152:155], v[182:185], 0
	v_mfma_f32_16x16x32_bf16 v[112:115], v[132:135], v[190:193], 0
	v_mfma_f32_16x16x32_bf16 v[108:111], v[152:155], v[190:193], 0
	v_mfma_f32_16x16x32_bf16 v[96:99], v[132:135], v[206:209], 0
	v_mfma_f32_16x16x32_bf16 v[92:95], v[152:155], v[206:209], 0
	v_mfma_f32_16x16x32_bf16 v[80:83], v[132:135], v[214:217], 0
	v_mfma_f32_16x16x32_bf16 v[76:79], v[152:155], v[214:217], 0
	v_mfma_f32_16x16x32_bf16 v[128:131], v[148:151], v[186:189], v[128:131]
	v_mfma_f32_16x16x32_bf16 v[124:127], v[156:159], v[186:189], v[124:127]
	v_mfma_f32_16x16x32_bf16 v[112:115], v[148:151], v[202:205], v[112:115]
	v_mfma_f32_16x16x32_bf16 v[108:111], v[156:159], v[202:205], v[108:111]
	v_mfma_f32_16x16x32_bf16 v[96:99], v[148:151], v[210:213], v[96:99]
	v_mfma_f32_16x16x32_bf16 v[92:95], v[156:159], v[210:213], v[92:95]
	v_mfma_f32_16x16x32_bf16 v[80:83], v[148:151], v[218:221], v[80:83]
	v_mfma_f32_16x16x32_bf16 v[76:79], v[156:159], v[218:221], v[76:79]
	v_mfma_f32_16x16x32_bf16 v[120:123], v[160:163], v[182:185], 0
	v_mfma_f32_16x16x32_bf16 v[116:119], v[174:177], v[182:185], 0
	v_mfma_f32_16x16x32_bf16 v[104:107], v[160:163], v[190:193], 0
	v_mfma_f32_16x16x32_bf16 v[100:103], v[174:177], v[190:193], 0
	v_mfma_f32_16x16x32_bf16 v[88:91], v[160:163], v[206:209], 0
	v_mfma_f32_16x16x32_bf16 v[84:87], v[174:177], v[206:209], 0
	v_mfma_f32_16x16x32_bf16 v[72:75], v[160:163], v[214:217], 0
	v_mfma_f32_16x16x32_bf16 v[68:71], v[174:177], v[214:217], 0
	v_mfma_f32_16x16x32_bf16 v[120:123], v[164:167], v[186:189], v[120:123]
	v_mfma_f32_16x16x32_bf16 v[116:119], v[178:181], v[186:189], v[116:119]
	v_mfma_f32_16x16x32_bf16 v[104:107], v[164:167], v[202:205], v[104:107]
	v_mfma_f32_16x16x32_bf16 v[100:103], v[178:181], v[202:205], v[100:103]
	v_mfma_f32_16x16x32_bf16 v[88:91], v[164:167], v[210:213], v[88:91]
	v_mfma_f32_16x16x32_bf16 v[84:87], v[178:181], v[210:213], v[84:87]
	v_mfma_f32_16x16x32_bf16 v[72:75], v[164:167], v[218:221], v[72:75]
	v_mfma_f32_16x16x32_bf16 v[68:71], v[178:181], v[218:221], v[68:71]
	s_barrier
	s_add_i32 s76, s76, s55
	v_lshl_add_u64 v[194:195], s[74:75], 0, v[136:137]
	s_mov_b32 m0, s76
	ds_read_b128 v[182:185], v173 offset:16384
	ds_read_b128 v[186:189], v173 offset:17408
	ds_read_b128 v[190:193], v173 offset:18432
	ds_read_b128 v[202:205], v173 offset:19456
	ds_read_b128 v[206:209], v173 offset:20480
	ds_read_b128 v[210:213], v173 offset:21504
	ds_read_b128 v[214:217], v173 offset:22528
	ds_read_b128 v[218:221], v173 offset:23552
	global_load_lds_dwordx4 v[194:195], off
	s_add_i32 m0, s76, 0x2000
	v_lshl_add_u64 v[196:197], s[74:75], 0, v[140:141]
	s_add_u32 s74, s74, s18
	s_addc_u32 s75, s75, s19
	s_add_i32 s73, s73, s55
	global_load_lds_dwordx4 v[196:197], off
	v_lshl_add_u64 v[198:199], s[74:75], 0, v[136:137]
	s_mov_b32 m0, s73
	v_lshl_add_u64 v[222:223], s[74:75], 0, v[140:141]
	global_load_lds_dwordx4 v[198:199], off
	s_add_i32 m0, s73, 0x2000
	v_lshl_add_u64 v[224:225], s[26:27], 0, v[0:1]
	global_load_lds_dwordx4 v[222:223], off
	s_mov_b32 m0, s56
	v_lshl_add_u64 v[230:231], s[26:27], 0, v[138:139]
	global_load_lds_dwordx4 v[224:225], off
	s_mov_b32 m0, s57
	s_nop 0
	global_load_lds_dwordx4 v[230:231], off
	s_waitcnt vmcnt(8)
	s_waitcnt lgkmcnt(0)
	s_barrier
; #define PG8_STAGE(bufoff, gbase, voff) do { _Pragma("unroll") for (int _i = 0; _i < 2; ++_i) \
;         __builtin_amdgcn_global_load_lds((const unsigned*)((const char*)(gbase) + (voff)[_i]), (LAS unsigned*)(lds + (bufoff) + ldsw + _i * 8192), 16, 0, 0); } while (0)
; #define PG8_STAGE_A1(bufoff, gbase) do { if (Epi::GATHER) PG8_STAGE(bufoff, gbase, voffA[1]); else PG8_STAGE(bufoff, (gbase) + hstep, voffA[0]); } while (0)
; #define PG8_LDA(dst, b, h) do { _Pragma("unroll") for (int m = 0; m < 4; ++m) _Pragma("unroll") for (int k = 0; k < 2; ++k) dst[m][k] = *(const LAS bf16x8*)(lds + PG8_SA(b, h) + aoff + m * 2048 + k * 1024); } while (0)
; #define PG8_LDB(dst, b, h) do { _Pragma("unroll") for (int n = 0; n < 2; ++n) _Pragma("unroll") for (int k = 0; k < 2; ++k) dst[n][k] = *(const LAS bf16x8*)(lds + PG8_SB(b, h) + boff + n * 2048 + k * 1024); } while (0)
; #define PG8_MMA(ai, bj, At, Bt) do { __builtin_amdgcn_s_setprio(1); _Pragma("unroll") for (int m = 0; m < 4; ++m) _Pragma("unroll") for (int n = 0; n < 2; ++n) _Pragma("unroll") for (int k = 0; k < 2; ++k) \
;         acc[ai][bj][m][n] = __builtin_amdgcn_mfma_f32_16x16x32_bf16(Bt[n][k], At[m][k], acc[ai][bj][m][n], 0, 0, 0); __builtin_amdgcn_s_setprio(0); } while (0)
; #define PG8_WAIT_V(n) asm volatile("s_waitcnt vmcnt(" #n ")" ::: "memory")
; #define PG8_WAIT_L(n) asm volatile("s_waitcnt lgkmcnt(" #n ")" ::: "memory")
; #define PG8_BAR __builtin_amdgcn_s_barrier()
; #define PG8_SCHED __builtin_amdgcn_sched_barrier(0)
; template <class Epi, class Sched>
; __device__ __forceinline__ void gemm_phase(const int tid, LAS unsigned char* lds, const bf16* Aop, const bf16* Bop, const int K_, const Sched& S, const Epi& E, const bf16* Aop1 = nullptr, const bf16* Bop1 = nullptr) {
;     ...
;             PG8_WAIT_V(8); PG8_WAIT_L(0); PG8_BAR; PG8_MMA(1, 0, At, B0); PG8_MMA(1, 1, At, B1); PG8_BAR; PG8_SCHED;
;             PG8_LDB(B0, 1, 0); PG8_LDB(B1, 1, 1); PG8_SCHED; PG8_LDA(At, 1, 0); PG8_STAGE_A1(PG8_SA(0, 1), a2);
;             PG8_WAIT_V(8); PG8_WAIT_L(0); PG8_BAR; PG8_MMA(0, 0, At, B0); PG8_MMA(0, 1, At, B1); PG8_BAR; PG8_SCHED;
;             PG8_LDA(At, 1, 1); PG8_STAGE(PG8_SB(1, 0), b3, voffB); PG8_STAGE(PG8_SB(1, 1), b3 + hstep, voffB); PG8_STAGE(PG8_SA(1, 0), a3, voffA[0]);
;             PG8_WAIT_V(8); PG8_WAIT_L(0); PG8_BAR; PG8_MMA(1, 0, At, B0); PG8_MMA(1, 1, At, B1); PG8_BAR; PG8_SCHED;
	v_mfma_f32_16x16x32_bf16 v[64:67], v[132:135], v[182:185], 0
	v_mfma_f32_16x16x32_bf16 v[60:63], v[152:155], v[182:185], 0
	v_mfma_f32_16x16x32_bf16 v[48:51], v[132:135], v[190:193], 0
	v_mfma_f32_16x16x32_bf16 v[44:47], v[152:155], v[190:193], 0
	v_mfma_f32_16x16x32_bf16 v[32:35], v[132:135], v[206:209], 0
	v_mfma_f32_16x16x32_bf16 v[28:31], v[152:155], v[206:209], 0
	v_mfma_f32_16x16x32_bf16 v[16:19], v[132:135], v[214:217], 0
	v_mfma_f32_16x16x32_bf16 v[12:15], v[152:155], v[214:217], 0
	v_mfma_f32_16x16x32_bf16 v[64:67], v[148:151], v[186:189], v[64:67]
	v_mfma_f32_16x16x32_bf16 v[60:63], v[156:159], v[186:189], v[60:63]
	v_mfma_f32_16x16x32_bf16 v[48:51], v[148:151], v[202:205], v[48:51]
	v_mfma_f32_16x16x32_bf16 v[44:47], v[156:159], v[202:205], v[44:47]
	v_mfma_f32_16x16x32_bf16 v[32:35], v[148:151], v[210:213], v[32:35]
	v_mfma_f32_16x16x32_bf16 v[28:31], v[156:159], v[210:213], v[28:31]
	v_mfma_f32_16x16x32_bf16 v[16:19], v[148:151], v[218:221], v[16:19]
	v_mfma_f32_16x16x32_bf16 v[12:15], v[156:159], v[218:221], v[12:15]
	v_mfma_f32_16x16x32_bf16 v[56:59], v[160:163], v[182:185], 0
	v_mfma_f32_16x16x32_bf16 v[52:55], v[174:177], v[182:185], 0
	v_mfma_f32_16x16x32_bf16 v[40:43], v[160:163], v[190:193], 0
	v_mfma_f32_16x16x32_bf16 v[36:39], v[174:177], v[190:193], 0
	v_mfma_f32_16x16x32_bf16 v[24:27], v[160:163], v[206:209], 0
	v_mfma_f32_16x16x32_bf16 v[20:23], v[174:177], v[206:209], 0
	v_mfma_f32_16x16x32_bf16 v[8:11], v[160:163], v[214:217], 0
	v_mfma_f32_16x16x32_bf16 v[4:7], v[174:177], v[214:217], 0
	v_mfma_f32_16x16x32_bf16 v[56:59], v[164:167], v[186:189], v[56:59]
	v_mfma_f32_16x16x32_bf16 v[52:55], v[178:181], v[186:189], v[52:55]
	v_mfma_f32_16x16x32_bf16 v[40:43], v[164:167], v[202:205], v[40:43]
	v_mfma_f32_16x16x32_bf16 v[36:39], v[178:181], v[202:205], v[36:39]
	v_mfma_f32_16x16x32_bf16 v[24:27], v[164:167], v[210:213], v[24:27]
	v_mfma_f32_16x16x32_bf16 v[20:23], v[178:181], v[210:213], v[20:23]
	v_mfma_f32_16x16x32_bf16 v[8:11], v[164:167], v[218:221], v[8:11]
	v_mfma_f32_16x16x32_bf16 v[4:7], v[178:181], v[218:221], v[4:7]
	s_barrier
	s_add_i32 s73, 0, 0x18000
	s_add_i32 s74, 0, 0x1c000
	v_add_u32_e32 v156, s73, v171
	v_add_u32_e32 v178, s74, v171
	ds_read_b128 v[132:135], v156
	ds_read_b128 v[148:151], v156 offset:1024
	ds_read_b128 v[152:155], v156 offset:2048
	ds_read_b128 v[156:159], v156 offset:3072
	ds_read_b128 v[160:163], v178
	ds_read_b128 v[164:167], v178 offset:1024
	ds_read_b128 v[174:177], v178 offset:2048
	ds_read_b128 v[178:181], v178 offset:3072
	s_add_u32 s26, s26, s18
	s_addc_u32 s27, s27, s19
	s_mov_b32 m0, s58
	v_lshl_add_u64 v[232:233], s[26:27], 0, v[0:1]
	ds_read_b128 v[182:185], v173 offset:32768
	ds_read_b128 v[186:189], v173 offset:33792
	ds_read_b128 v[190:193], v173 offset:34816
	ds_read_b128 v[202:205], v173 offset:35840
	ds_read_b128 v[206:209], v173 offset:36864
	ds_read_b128 v[210:213], v173 offset:37888
	ds_read_b128 v[214:217], v173 offset:38912
	ds_read_b128 v[218:221], v173 offset:39936
	global_load_lds_dwordx4 v[232:233], off
	v_lshl_add_u64 v[232:233], s[26:27], 0, v[138:139]
	s_mov_b32 m0, s59
	s_nop 0
	global_load_lds_dwordx4 v[232:233], off
	s_waitcnt vmcnt(8)
	s_waitcnt lgkmcnt(0)
	s_barrier
	v_mfma_f32_16x16x32_bf16 v[128:131], v[132:135], v[182:185], v[128:131]
	v_mfma_f32_16x16x32_bf16 v[124:127], v[152:155], v[182:185], v[124:127]
	v_mfma_f32_16x16x32_bf16 v[112:115], v[132:135], v[190:193], v[112:115]
	v_mfma_f32_16x16x32_bf16 v[108:111], v[152:155], v[190:193], v[108:111]
	v_mfma_f32_16x16x32_bf16 v[96:99], v[132:135], v[206:209], v[96:99]
	v_mfma_f32_16x16x32_bf16 v[92:95], v[152:155], v[206:209], v[92:95]
	v_mfma_f32_16x16x32_bf16 v[80:83], v[132:135], v[214:217], v[80:83]
	v_mfma_f32_16x16x32_bf16 v[76:79], v[152:155], v[214:217], v[76:79]
	v_mfma_f32_16x16x32_bf16 v[128:131], v[148:151], v[186:189], v[128:131]
	v_mfma_f32_16x16x32_bf16 v[124:127], v[156:159], v[186:189], v[124:127]
	v_mfma_f32_16x16x32_bf16 v[112:115], v[148:151], v[202:205], v[112:115]
	v_mfma_f32_16x16x32_bf16 v[108:111], v[156:159], v[202:205], v[108:111]
	v_mfma_f32_16x16x32_bf16 v[96:99], v[148:151], v[210:213], v[96:99]
	v_mfma_f32_16x16x32_bf16 v[92:95], v[156:159], v[210:213], v[92:95]
	v_mfma_f32_16x16x32_bf16 v[80:83], v[148:151], v[218:221], v[80:83]
	v_mfma_f32_16x16x32_bf16 v[76:79], v[156:159], v[218:221], v[76:79]
	v_mfma_f32_16x16x32_bf16 v[120:123], v[160:163], v[182:185], v[120:123]
	v_mfma_f32_16x16x32_bf16 v[116:119], v[174:177], v[182:185], v[116:119]
	v_mfma_f32_16x16x32_bf16 v[104:107], v[160:163], v[190:193], v[104:107]
	v_mfma_f32_16x16x32_bf16 v[100:103], v[174:177], v[190:193], v[100:103]
	v_mfma_f32_16x16x32_bf16 v[88:91], v[160:163], v[206:209], v[88:91]
	v_mfma_f32_16x16x32_bf16 v[84:87], v[174:177], v[206:209], v[84:87]
	v_mfma_f32_16x16x32_bf16 v[72:75], v[160:163], v[214:217], v[72:75]
	v_mfma_f32_16x16x32_bf16 v[68:71], v[174:177], v[214:217], v[68:71]
	v_mfma_f32_16x16x32_bf16 v[120:123], v[164:167], v[186:189], v[120:123]
	v_mfma_f32_16x16x32_bf16 v[116:119], v[178:181], v[186:189], v[116:119]
	v_mfma_f32_16x16x32_bf16 v[104:107], v[164:167], v[202:205], v[104:107]
	v_mfma_f32_16x16x32_bf16 v[100:103], v[178:181], v[202:205], v[100:103]
	v_mfma_f32_16x16x32_bf16 v[88:91], v[164:167], v[210:213], v[88:91]
	v_mfma_f32_16x16x32_bf16 v[84:87], v[178:181], v[210:213], v[84:87]
	v_mfma_f32_16x16x32_bf16 v[72:75], v[164:167], v[218:221], v[72:75]
	v_mfma_f32_16x16x32_bf16 v[68:71], v[178:181], v[218:221], v[68:71]
	s_barrier
; #define PG8_GOFFS(slot_) do { _Pragma("unroll") for (int _i = 0; _i < 2; ++_i) { int R, C; stage_rc(tid * 16 + _i * 8192, R, C); _Pragma("unroll") for (int _h = 0; _h < 2; ++_h) { \
;         unsigned t_ = gtab[(slot_) * 256 + R + 128 * _h]; t_ = t_ < (unsigned)(T - 1) ? t_ : (unsigned)(T - 1); voffA[_h][_i] = (t_ * (unsigned)K + (unsigned)C) * 2u; } } } while (0)
; #define PG8_STAGE(bufoff, gbase, voff) do { _Pragma("unroll") for (int _i = 0; _i < 2; ++_i) \
;         __builtin_amdgcn_global_load_lds((const unsigned*)((const char*)(gbase) + (voff)[_i]), (LAS unsigned*)(lds + (bufoff) + ldsw + _i * 8192), 16, 0, 0); } while (0)
; #define PG8_STAGE_A1(bufoff, gbase) do { if (Epi::GATHER) PG8_STAGE(bufoff, gbase, voffA[1]); else PG8_STAGE(bufoff, (gbase) + hstep, voffA[0]); } while (0)
; #define PG8_LDA(dst, b, h) do { _Pragma("unroll") for (int m = 0; m < 4; ++m) _Pragma("unroll") for (int k = 0; k < 2; ++k) dst[m][k] = *(const LAS bf16x8*)(lds + PG8_SA(b, h) + aoff + m * 2048 + k * 1024); } while (0)
; #define PG8_BAR __builtin_amdgcn_s_barrier()
; template <class Epi, class Sched>
; __device__ __forceinline__ void gemm_phase(const int tid, LAS unsigned char* lds, const bf16* Aop, const bf16* Bop, const int K_, const Sched& S, const Epi& E, const bf16* Aop1 = nullptr, const bf16* Bop1 = nullptr) {
;     ...
;             PG8_LDB(B0, 0, 0); PG8_LDB(B1, 0, 1); PG8_SCHED; PG8_LDA(At, 0, 0); PG8_STAGE_A1(PG8_SA(1, 1), a1);
;             PG8_WAIT_V(8); PG8_WAIT_L(0); PG8_BAR; PG8_MMA(0, 0, At, B0); PG8_MMA(0, 1, At, B1); PG8_BAR; PG8_SCHED;
;             PG8_LDA(At, 0, 1); PG8_STAGE(PG8_SB(0, 0), b2, voffB); PG8_STAGE(PG8_SB(0, 1), b2 + hstep, voffB); if (Epi::GATHER && last && has_next) PG8_GOFFS((ui + 1) & 1); PG8_STAGE(PG8_SA(0, 0), a2, voffA[0]);
;             PG8_WAIT_V(8); PG8_WAIT_L(0); PG8_BAR; PG8_MMA(1, 0, At, B0); PG8_MMA(1, 1, At, B1); PG8_BAR; PG8_SCHED;
;             PG8_LDB(B0, 1, 0); PG8_LDB(B1, 1, 1); PG8_SCHED; PG8_LDA(At, 1, 0); PG8_STAGE_A1(PG8_SA(0, 1), a2);
;             PG8_WAIT_V(8); PG8_WAIT_L(0); PG8_BAR; PG8_MMA(0, 0, At, B0); PG8_MMA(0, 1, At, B1); PG8_BAR; PG8_SCHED;
;             PG8_LDA(At, 1, 1); PG8_STAGE(PG8_SB(1, 0), b3, voffB); PG8_STAGE(PG8_SB(1, 1), b3 + hstep, voffB); PG8_STAGE(PG8_SA(1, 0), a3, voffA[0]);
;             PG8_WAIT_V(8); PG8_WAIT_L(0); PG8_BAR; PG8_MMA(1, 0, At, B0); PG8_MMA(1, 1, At, B1); PG8_BAR; PG8_SCHED;
	s_add_i32 s26, s73, s55
	v_lshl_add_u64 v[194:195], v[194:195], 0, s[20:21]
	s_mov_b32 m0, s26
	ds_read_b128 v[182:185], v173 offset:49152
	ds_read_b128 v[186:189], v173 offset:50176
	ds_read_b128 v[190:193], v173 offset:51200
	ds_read_b128 v[202:205], v173 offset:52224
	ds_read_b128 v[206:209], v173 offset:53248
	ds_read_b128 v[210:213], v173 offset:54272
	ds_read_b128 v[214:217], v173 offset:55296
	ds_read_b128 v[218:221], v173 offset:56320
	global_load_lds_dwordx4 v[194:195], off
	v_lshl_add_u64 v[194:195], v[196:197], 0, s[20:21]
	s_add_i32 m0, s26, 0x2000
	s_add_i32 s26, s74, s55
	global_load_lds_dwordx4 v[194:195], off
	v_lshl_add_u64 v[194:195], v[198:199], 0, s[20:21]
	s_mov_b32 m0, s26
	s_nop 0
	global_load_lds_dwordx4 v[194:195], off
	v_lshl_add_u64 v[194:195], v[222:223], 0, s[20:21]
	s_add_i32 m0, s26, 0x2000
	s_nop 0
	global_load_lds_dwordx4 v[194:195], off
	v_lshl_add_u64 v[194:195], v[224:225], 0, s[20:21]
	s_mov_b32 m0, s60
	s_nop 0
	global_load_lds_dwordx4 v[194:195], off
	v_lshl_add_u64 v[194:195], v[230:231], 0, s[20:21]
	s_mov_b32 m0, s61
	s_nop 0
	global_load_lds_dwordx4 v[194:195], off
	s_waitcnt vmcnt(8)
	s_waitcnt lgkmcnt(0)
	s_barrier
	v_mfma_f32_16x16x32_bf16 v[64:67], v[132:135], v[182:185], v[64:67]
	v_mfma_f32_16x16x32_bf16 v[60:63], v[152:155], v[182:185], v[60:63]
	v_mfma_f32_16x16x32_bf16 v[48:51], v[132:135], v[190:193], v[48:51]
	v_mfma_f32_16x16x32_bf16 v[44:47], v[152:155], v[190:193], v[44:47]
	v_mfma_f32_16x16x32_bf16 v[32:35], v[132:135], v[206:209], v[32:35]
	v_mfma_f32_16x16x32_bf16 v[28:31], v[152:155], v[206:209], v[28:31]
	v_mfma_f32_16x16x32_bf16 v[16:19], v[132:135], v[214:217], v[16:19]
	v_mfma_f32_16x16x32_bf16 v[12:15], v[152:155], v[214:217], v[12:15]
	v_mfma_f32_16x16x32_bf16 v[64:67], v[148:151], v[186:189], v[64:67]
	v_mfma_f32_16x16x32_bf16 v[60:63], v[156:159], v[186:189], v[60:63]
	v_mfma_f32_16x16x32_bf16 v[48:51], v[148:151], v[202:205], v[48:51]
	v_mfma_f32_16x16x32_bf16 v[44:47], v[156:159], v[202:205], v[44:47]
	v_mfma_f32_16x16x32_bf16 v[32:35], v[148:151], v[210:213], v[32:35]
	v_mfma_f32_16x16x32_bf16 v[28:31], v[156:159], v[210:213], v[28:31]
	v_mfma_f32_16x16x32_bf16 v[16:19], v[148:151], v[218:221], v[16:19]
	v_mfma_f32_16x16x32_bf16 v[12:15], v[156:159], v[218:221], v[12:15]
	v_mfma_f32_16x16x32_bf16 v[56:59], v[160:163], v[182:185], v[56:59]
	v_mfma_f32_16x16x32_bf16 v[52:55], v[174:177], v[182:185], v[52:55]
	v_mfma_f32_16x16x32_bf16 v[40:43], v[160:163], v[190:193], v[40:43]
	v_mfma_f32_16x16x32_bf16 v[36:39], v[174:177], v[190:193], v[36:39]
	v_mfma_f32_16x16x32_bf16 v[24:27], v[160:163], v[206:209], v[24:27]
	v_mfma_f32_16x16x32_bf16 v[20:23], v[174:177], v[206:209], v[20:23]
	v_mfma_f32_16x16x32_bf16 v[8:11], v[160:163], v[214:217], v[8:11]
	v_mfma_f32_16x16x32_bf16 v[4:7], v[174:177], v[214:217], v[4:7]
	v_mfma_f32_16x16x32_bf16 v[56:59], v[164:167], v[186:189], v[56:59]
	v_mfma_f32_16x16x32_bf16 v[52:55], v[178:181], v[186:189], v[52:55]
	v_mfma_f32_16x16x32_bf16 v[40:43], v[164:167], v[202:205], v[40:43]
	v_mfma_f32_16x16x32_bf16 v[36:39], v[178:181], v[202:205], v[36:39]
	v_mfma_f32_16x16x32_bf16 v[24:27], v[164:167], v[210:213], v[24:27]
	v_mfma_f32_16x16x32_bf16 v[20:23], v[178:181], v[210:213], v[20:23]
	v_mfma_f32_16x16x32_bf16 v[8:11], v[164:167], v[218:221], v[8:11]
	v_mfma_f32_16x16x32_bf16 v[4:7], v[178:181], v[218:221], v[4:7]
	s_barrier
	s_add_u32 s12, s12, 0x100
	s_addc_u32 s13, s13, 0
	s_add_u32 s11, s11, 0x100
	s_addc_u32 s71, s71, 0
	s_cmp_ge_i32 s72, s8
	s_mov_b32 s26, s72
	s_cbranch_scc0 .LBB0_1000
	s_branch .LBB0_1001
.LBB0_1000:
	s_add_i32 s72, s26, 2
	s_add_u32 s73, s12, 0x80
	s_addc_u32 s27, s13, 0
	s_add_i32 s76, 0, 0x10000
	s_cmp_eq_u32 s64, s26
	s_cselect_b32 s27, s7, s27
	s_cselect_b32 s26, s6, s73
	s_cselect_b32 s75, s41, s71
	s_cselect_b32 s74, s40, s11
	s_add_i32 s73, 0, 0x14000
	v_add_u32_e32 v156, s76, v171
	v_add_u32_e32 v178, s73, v171
	ds_read_b128 v[132:135], v156
	ds_read_b128 v[148:151], v156 offset:1024
	ds_read_b128 v[152:155], v156 offset:2048
	ds_read_b128 v[156:159], v156 offset:3072
	ds_read_b128 v[160:163], v178
	ds_read_b128 v[164:167], v178 offset:1024
	ds_read_b128 v[174:177], v178 offset:2048
	ds_read_b128 v[178:181], v178 offset:3072
	v_lshl_add_u64 v[194:195], s[12:13], 0, v[144:145]
	s_add_i32 m0, s56, 0xc000
	ds_read_b128 v[182:185], v173
	ds_read_b128 v[186:189], v173 offset:1024
	ds_read_b128 v[190:193], v173 offset:2048
	ds_read_b128 v[202:205], v173 offset:3072
	ds_read_b128 v[206:209], v173 offset:4096
	ds_read_b128 v[210:213], v173 offset:5120
	ds_read_b128 v[214:217], v173 offset:6144
	ds_read_b128 v[218:221], v173 offset:7168
	global_load_lds_dwordx4 v[194:195], off
	v_lshl_add_u64 v[194:195], s[12:13], 0, v[146:147]
	s_add_i32 m0, s56, 0xe000
	s_nop 0
	global_load_lds_dwordx4 v[194:195], off
	s_waitcnt vmcnt(8)
	s_waitcnt lgkmcnt(0)
	s_barrier
; #define PG8_GOFFS(slot_) do { _Pragma("unroll") for (int _i = 0; _i < 2; ++_i) { int R, C; stage_rc(tid * 16 + _i * 8192, R, C); _Pragma("unroll") for (int _h = 0; _h < 2; ++_h) { \
;         unsigned t_ = gtab[(slot_) * 256 + R + 128 * _h]; t_ = t_ < (unsigned)(T - 1) ? t_ : (unsigned)(T - 1); voffA[_h][_i] = (t_ * (unsigned)K + (unsigned)C) * 2u; } } } while (0)
; #define PG8_STAGE(bufoff, gbase, voff) do { _Pragma("unroll") for (int _i = 0; _i < 2; ++_i) \
;         __builtin_amdgcn_global_load_lds((const unsigned*)((const char*)(gbase) + (voff)[_i]), (LAS unsigned*)(lds + (bufoff) + ldsw + _i * 8192), 16, 0, 0); } while (0)
; #define PG8_STAGE_A1(bufoff, gbase) do { if (Epi::GATHER) PG8_STAGE(bufoff, gbase, voffA[1]); else PG8_STAGE(bufoff, (gbase) + hstep, voffA[0]); } while (0)
; #define PG8_LDA(dst, b, h) do { _Pragma("unroll") for (int m = 0; m < 4; ++m) _Pragma("unroll") for (int k = 0; k < 2; ++k) dst[m][k] = *(const LAS bf16x8*)(lds + PG8_SA(b, h) + aoff + m * 2048 + k * 1024); } while (0)
; #define PG8_LDB(dst, b, h) do { _Pragma("unroll") for (int n = 0; n < 2; ++n) _Pragma("unroll") for (int k = 0; k < 2; ++k) dst[n][k] = *(const LAS bf16x8*)(lds + PG8_SB(b, h) + boff + n * 2048 + k * 1024); } while (0)
; #define PG8_WAIT_V(n) asm volatile("s_waitcnt vmcnt(" #n ")" ::: "memory")
; #define PG8_WAIT_L(n) asm volatile("s_waitcnt lgkmcnt(" #n ")" ::: "memory")
; #define PG8_BAR __builtin_amdgcn_s_barrier()
; #define PG8_SCHED __builtin_amdgcn_sched_barrier(0)
; template <class Epi, class Sched>
; __device__ __forceinline__ void gemm_phase(const int tid, LAS unsigned char* lds, const bf16* Aop, const bf16* Bop, const int K_, const Sched& S, const Epi& E, const bf16* Aop1 = nullptr, const bf16* Bop1 = nullptr) {
;     ...
;             PG8_WAIT_V(8); PG8_WAIT_L(0); PG8_BAR; PG8_MMA(0, 0, At, B0); PG8_MMA(0, 1, At, B1); PG8_BAR; PG8_SCHED;
;             PG8_LDA(At, 0, 1); PG8_STAGE(PG8_SB(0, 0), b2, voffB); PG8_STAGE(PG8_SB(0, 1), b2 + hstep, voffB); if (Epi::GATHER && last && has_next) PG8_GOFFS((ui + 1) & 1); PG8_STAGE(PG8_SA(0, 0), a2, voffA[0]);
;             PG8_WAIT_V(8); PG8_WAIT_L(0); PG8_BAR; PG8_MMA(1, 0, At, B0); PG8_MMA(1, 1, At, B1); PG8_BAR; PG8_SCHED;
;             PG8_LDB(B0, 1, 0); PG8_LDB(B1, 1, 1); PG8_SCHED; PG8_LDA(At, 1, 0); PG8_STAGE_A1(PG8_SA(0, 1), a2);
	v_mfma_f32_16x16x32_bf16 v[128:131], v[132:135], v[182:185], v[128:131]
	v_mfma_f32_16x16x32_bf16 v[124:127], v[152:155], v[182:185], v[124:127]
	v_mfma_f32_16x16x32_bf16 v[112:115], v[132:135], v[190:193], v[112:115]
	v_mfma_f32_16x16x32_bf16 v[108:111], v[152:155], v[190:193], v[108:111]
	v_mfma_f32_16x16x32_bf16 v[96:99], v[132:135], v[206:209], v[96:99]
	v_mfma_f32_16x16x32_bf16 v[92:95], v[152:155], v[206:209], v[92:95]
	v_mfma_f32_16x16x32_bf16 v[80:83], v[132:135], v[214:217], v[80:83]
	v_mfma_f32_16x16x32_bf16 v[76:79], v[152:155], v[214:217], v[76:79]
	v_mfma_f32_16x16x32_bf16 v[128:131], v[148:151], v[186:189], v[128:131]
	v_mfma_f32_16x16x32_bf16 v[124:127], v[156:159], v[186:189], v[124:127]
	v_mfma_f32_16x16x32_bf16 v[112:115], v[148:151], v[202:205], v[112:115]
	v_mfma_f32_16x16x32_bf16 v[108:111], v[156:159], v[202:205], v[108:111]
	v_mfma_f32_16x16x32_bf16 v[96:99], v[148:151], v[210:213], v[96:99]
	v_mfma_f32_16x16x32_bf16 v[92:95], v[156:159], v[210:213], v[92:95]
	v_mfma_f32_16x16x32_bf16 v[80:83], v[148:151], v[218:221], v[80:83]
	v_mfma_f32_16x16x32_bf16 v[76:79], v[156:159], v[218:221], v[76:79]
	v_mfma_f32_16x16x32_bf16 v[120:123], v[160:163], v[182:185], v[120:123]
	v_mfma_f32_16x16x32_bf16 v[116:119], v[174:177], v[182:185], v[116:119]
	v_mfma_f32_16x16x32_bf16 v[104:107], v[160:163], v[190:193], v[104:107]
	v_mfma_f32_16x16x32_bf16 v[100:103], v[174:177], v[190:193], v[100:103]
	v_mfma_f32_16x16x32_bf16 v[88:91], v[160:163], v[206:209], v[88:91]
	v_mfma_f32_16x16x32_bf16 v[84:87], v[174:177], v[206:209], v[84:87]
	v_mfma_f32_16x16x32_bf16 v[72:75], v[160:163], v[214:217], v[72:75]
	v_mfma_f32_16x16x32_bf16 v[68:71], v[174:177], v[214:217], v[68:71]
	v_mfma_f32_16x16x32_bf16 v[120:123], v[164:167], v[186:189], v[120:123]
	v_mfma_f32_16x16x32_bf16 v[116:119], v[178:181], v[186:189], v[116:119]
	v_mfma_f32_16x16x32_bf16 v[104:107], v[164:167], v[202:205], v[104:107]
	v_mfma_f32_16x16x32_bf16 v[100:103], v[178:181], v[202:205], v[100:103]
	v_mfma_f32_16x16x32_bf16 v[88:91], v[164:167], v[210:213], v[88:91]
	v_mfma_f32_16x16x32_bf16 v[84:87], v[178:181], v[210:213], v[84:87]
	v_mfma_f32_16x16x32_bf16 v[72:75], v[164:167], v[218:221], v[72:75]
	v_mfma_f32_16x16x32_bf16 v[68:71], v[178:181], v[218:221], v[68:71]
	s_barrier
	s_add_i32 s76, s76, s55
	v_lshl_add_u64 v[194:195], s[74:75], 0, v[136:137]
	s_mov_b32 m0, s76
	ds_read_b128 v[182:185], v173 offset:16384
	ds_read_b128 v[186:189], v173 offset:17408
	ds_read_b128 v[190:193], v173 offset:18432
	ds_read_b128 v[202:205], v173 offset:19456
	ds_read_b128 v[206:209], v173 offset:20480
	ds_read_b128 v[210:213], v173 offset:21504
	ds_read_b128 v[214:217], v173 offset:22528
	ds_read_b128 v[218:221], v173 offset:23552
	global_load_lds_dwordx4 v[194:195], off
	s_add_i32 m0, s76, 0x2000
	v_lshl_add_u64 v[196:197], s[74:75], 0, v[140:141]
	s_add_u32 s74, s74, s18
	s_addc_u32 s75, s75, s19
	s_add_i32 s73, s73, s55
	global_load_lds_dwordx4 v[196:197], off
	v_lshl_add_u64 v[198:199], s[74:75], 0, v[136:137]
	s_mov_b32 m0, s73
	v_lshl_add_u64 v[222:223], s[74:75], 0, v[140:141]
	global_load_lds_dwordx4 v[198:199], off
	s_add_i32 m0, s73, 0x2000
	v_lshl_add_u64 v[224:225], s[26:27], 0, v[0:1]
	global_load_lds_dwordx4 v[222:223], off
	s_mov_b32 m0, s56
	v_lshl_add_u64 v[230:231], s[26:27], 0, v[138:139]
	global_load_lds_dwordx4 v[224:225], off
	s_mov_b32 m0, s57
	s_nop 0
	global_load_lds_dwordx4 v[230:231], off
	s_waitcnt vmcnt(8)
	s_waitcnt lgkmcnt(0)
	s_barrier
	v_mfma_f32_16x16x32_bf16 v[64:67], v[132:135], v[182:185], v[64:67]
	v_mfma_f32_16x16x32_bf16 v[60:63], v[152:155], v[182:185], v[60:63]
	v_mfma_f32_16x16x32_bf16 v[48:51], v[132:135], v[190:193], v[48:51]
	v_mfma_f32_16x16x32_bf16 v[44:47], v[152:155], v[190:193], v[44:47]
	v_mfma_f32_16x16x32_bf16 v[32:35], v[132:135], v[206:209], v[32:35]
	v_mfma_f32_16x16x32_bf16 v[28:31], v[152:155], v[206:209], v[28:31]
	v_mfma_f32_16x16x32_bf16 v[16:19], v[132:135], v[214:217], v[16:19]
	v_mfma_f32_16x16x32_bf16 v[12:15], v[152:155], v[214:217], v[12:15]
	v_mfma_f32_16x16x32_bf16 v[64:67], v[148:151], v[186:189], v[64:67]
	v_mfma_f32_16x16x32_bf16 v[60:63], v[156:159], v[186:189], v[60:63]
	v_mfma_f32_16x16x32_bf16 v[48:51], v[148:151], v[202:205], v[48:51]
	v_mfma_f32_16x16x32_bf16 v[44:47], v[156:159], v[202:205], v[44:47]
	v_mfma_f32_16x16x32_bf16 v[32:35], v[148:151], v[210:213], v[32:35]
	v_mfma_f32_16x16x32_bf16 v[28:31], v[156:159], v[210:213], v[28:31]
	v_mfma_f32_16x16x32_bf16 v[16:19], v[148:151], v[218:221], v[16:19]
	v_mfma_f32_16x16x32_bf16 v[12:15], v[156:159], v[218:221], v[12:15]
	v_mfma_f32_16x16x32_bf16 v[56:59], v[160:163], v[182:185], v[56:59]
	v_mfma_f32_16x16x32_bf16 v[52:55], v[174:177], v[182:185], v[52:55]
	v_mfma_f32_16x16x32_bf16 v[40:43], v[160:163], v[190:193], v[40:43]
	v_mfma_f32_16x16x32_bf16 v[36:39], v[174:177], v[190:193], v[36:39]
	v_mfma_f32_16x16x32_bf16 v[24:27], v[160:163], v[206:209], v[24:27]
	v_mfma_f32_16x16x32_bf16 v[20:23], v[174:177], v[206:209], v[20:23]
	v_mfma_f32_16x16x32_bf16 v[8:11], v[160:163], v[214:217], v[8:11]
	v_mfma_f32_16x16x32_bf16 v[4:7], v[174:177], v[214:217], v[4:7]
	v_mfma_f32_16x16x32_bf16 v[56:59], v[164:167], v[186:189], v[56:59]
	v_mfma_f32_16x16x32_bf16 v[52:55], v[178:181], v[186:189], v[52:55]
	v_mfma_f32_16x16x32_bf16 v[40:43], v[164:167], v[202:205], v[40:43]
	v_mfma_f32_16x16x32_bf16 v[36:39], v[178:181], v[202:205], v[36:39]
	v_mfma_f32_16x16x32_bf16 v[24:27], v[164:167], v[210:213], v[24:27]
	v_mfma_f32_16x16x32_bf16 v[20:23], v[178:181], v[210:213], v[20:23]
	v_mfma_f32_16x16x32_bf16 v[8:11], v[164:167], v[218:221], v[8:11]
	v_mfma_f32_16x16x32_bf16 v[4:7], v[178:181], v[218:221], v[4:7]
	s_barrier
; #define PG8_STAGE(bufoff, gbase, voff) do { _Pragma("unroll") for (int _i = 0; _i < 2; ++_i) \
;         __builtin_amdgcn_global_load_lds((const unsigned*)((const char*)(gbase) + (voff)[_i]), (LAS unsigned*)(lds + (bufoff) + ldsw + _i * 8192), 16, 0, 0); } while (0)
; #define PG8_STAGE_A1(bufoff, gbase) do { if (Epi::GATHER) PG8_STAGE(bufoff, gbase, voffA[1]); else PG8_STAGE(bufoff, (gbase) + hstep, voffA[0]); } while (0)
; #define PG8_LDA(dst, b, h) do { _Pragma("unroll") for (int m = 0; m < 4; ++m) _Pragma("unroll") for (int k = 0; k < 2; ++k) dst[m][k] = *(const LAS bf16x8*)(lds + PG8_SA(b, h) + aoff + m * 2048 + k * 1024); } while (0)
; #define PG8_LDB(dst, b, h) do { _Pragma("unroll") for (int n = 0; n < 2; ++n) _Pragma("unroll") for (int k = 0; k < 2; ++k) dst[n][k] = *(const LAS bf16x8*)(lds + PG8_SB(b, h) + boff + n * 2048 + k * 1024); } while (0)
; #define PG8_MMA(ai, bj, At, Bt) do { __builtin_amdgcn_s_setprio(1); _Pragma("unroll") for (int m = 0; m < 4; ++m) _Pragma("unroll") for (int n = 0; n < 2; ++n) _Pragma("unroll") for (int k = 0; k < 2; ++k) \
;         acc[ai][bj][m][n] = __builtin_amdgcn_mfma_f32_16x16x32_bf16(Bt[n][k], At[m][k], acc[ai][bj][m][n], 0, 0, 0); __builtin_amdgcn_s_setprio(0); } while (0)
; #define PG8_WAIT_V(n) asm volatile("s_waitcnt vmcnt(" #n ")" ::: "memory")
; #define PG8_WAIT_L(n) asm volatile("s_waitcnt lgkmcnt(" #n ")" ::: "memory")
; #define PG8_BAR __builtin_amdgcn_s_barrier()
; #define PG8_SCHED __builtin_amdgcn_sched_barrier(0)
; template <class Epi, class Sched>
; __device__ __forceinline__ void gemm_phase(const int tid, LAS unsigned char* lds, const bf16* Aop, const bf16* Bop, const int K_, const Sched& S, const Epi& E, const bf16* Aop1 = nullptr, const bf16* Bop1 = nullptr) {
;     ...
;             PG8_LDB(B0, 1, 0); PG8_LDB(B1, 1, 1); PG8_SCHED; PG8_LDA(At, 1, 0); PG8_STAGE_A1(PG8_SA(0, 1), a2);
;             PG8_WAIT_V(8); PG8_WAIT_L(0); PG8_BAR; PG8_MMA(0, 0, At, B0); PG8_MMA(0, 1, At, B1); PG8_BAR; PG8_SCHED;
;             PG8_LDA(At, 1, 1); PG8_STAGE(PG8_SB(1, 0), b3, voffB); PG8_STAGE(PG8_SB(1, 1), b3 + hstep, voffB); PG8_STAGE(PG8_SA(1, 0), a3, voffA[0]);
;             PG8_WAIT_V(8); PG8_WAIT_L(0); PG8_BAR; PG8_MMA(1, 0, At, B0); PG8_MMA(1, 1, At, B1); PG8_BAR; PG8_SCHED;
	s_add_i32 s73, 0, 0x18000
	s_add_i32 s74, 0, 0x1c000
	v_add_u32_e32 v156, s73, v171
	v_add_u32_e32 v178, s74, v171
	ds_read_b128 v[132:135], v156
	ds_read_b128 v[148:151], v156 offset:1024
	ds_read_b128 v[152:155], v156 offset:2048
	ds_read_b128 v[156:159], v156 offset:3072
	ds_read_b128 v[160:163], v178
	ds_read_b128 v[164:167], v178 offset:1024
	ds_read_b128 v[174:177], v178 offset:2048
	ds_read_b128 v[178:181], v178 offset:3072
	s_add_u32 s26, s26, s18
	s_addc_u32 s27, s27, s19
	s_mov_b32 m0, s58
	v_lshl_add_u64 v[232:233], s[26:27], 0, v[0:1]
	ds_read_b128 v[182:185], v173 offset:32768
	ds_read_b128 v[186:189], v173 offset:33792
	ds_read_b128 v[190:193], v173 offset:34816
	ds_read_b128 v[202:205], v173 offset:35840
	ds_read_b128 v[206:209], v173 offset:36864
	ds_read_b128 v[210:213], v173 offset:37888
	ds_read_b128 v[214:217], v173 offset:38912
	ds_read_b128 v[218:221], v173 offset:39936
	global_load_lds_dwordx4 v[232:233], off
	v_lshl_add_u64 v[232:233], s[26:27], 0, v[138:139]
	s_mov_b32 m0, s59
	s_nop 0
	global_load_lds_dwordx4 v[232:233], off
	s_waitcnt vmcnt(8)
	s_waitcnt lgkmcnt(0)
	s_barrier
	v_mfma_f32_16x16x32_bf16 v[128:131], v[132:135], v[182:185], v[128:131]
	v_mfma_f32_16x16x32_bf16 v[124:127], v[152:155], v[182:185], v[124:127]
	v_mfma_f32_16x16x32_bf16 v[112:115], v[132:135], v[190:193], v[112:115]
	v_mfma_f32_16x16x32_bf16 v[108:111], v[152:155], v[190:193], v[108:111]
	v_mfma_f32_16x16x32_bf16 v[96:99], v[132:135], v[206:209], v[96:99]
	v_mfma_f32_16x16x32_bf16 v[92:95], v[152:155], v[206:209], v[92:95]
	v_mfma_f32_16x16x32_bf16 v[80:83], v[132:135], v[214:217], v[80:83]
	v_mfma_f32_16x16x32_bf16 v[76:79], v[152:155], v[214:217], v[76:79]
	v_mfma_f32_16x16x32_bf16 v[128:131], v[148:151], v[186:189], v[128:131]
	v_mfma_f32_16x16x32_bf16 v[124:127], v[156:159], v[186:189], v[124:127]
	v_mfma_f32_16x16x32_bf16 v[112:115], v[148:151], v[202:205], v[112:115]
	v_mfma_f32_16x16x32_bf16 v[108:111], v[156:159], v[202:205], v[108:111]
	v_mfma_f32_16x16x32_bf16 v[96:99], v[148:151], v[210:213], v[96:99]
	v_mfma_f32_16x16x32_bf16 v[92:95], v[156:159], v[210:213], v[92:95]
	v_mfma_f32_16x16x32_bf16 v[80:83], v[148:151], v[218:221], v[80:83]
	v_mfma_f32_16x16x32_bf16 v[76:79], v[156:159], v[218:221], v[76:79]
	v_mfma_f32_16x16x32_bf16 v[120:123], v[160:163], v[182:185], v[120:123]
	v_mfma_f32_16x16x32_bf16 v[116:119], v[174:177], v[182:185], v[116:119]
	v_mfma_f32_16x16x32_bf16 v[104:107], v[160:163], v[190:193], v[104:107]
	v_mfma_f32_16x16x32_bf16 v[100:103], v[174:177], v[190:193], v[100:103]
	v_mfma_f32_16x16x32_bf16 v[88:91], v[160:163], v[206:209], v[88:91]
	v_mfma_f32_16x16x32_bf16 v[84:87], v[174:177], v[206:209], v[84:87]
	v_mfma_f32_16x16x32_bf16 v[72:75], v[160:163], v[214:217], v[72:75]
	v_mfma_f32_16x16x32_bf16 v[68:71], v[174:177], v[214:217], v[68:71]
	v_mfma_f32_16x16x32_bf16 v[120:123], v[164:167], v[186:189], v[120:123]
	v_mfma_f32_16x16x32_bf16 v[116:119], v[178:181], v[186:189], v[116:119]
	v_mfma_f32_16x16x32_bf16 v[104:107], v[164:167], v[202:205], v[104:107]
	v_mfma_f32_16x16x32_bf16 v[100:103], v[178:181], v[202:205], v[100:103]
	v_mfma_f32_16x16x32_bf16 v[88:91], v[164:167], v[210:213], v[88:91]
	v_mfma_f32_16x16x32_bf16 v[84:87], v[178:181], v[210:213], v[84:87]
	v_mfma_f32_16x16x32_bf16 v[72:75], v[164:167], v[218:221], v[72:75]
	v_mfma_f32_16x16x32_bf16 v[68:71], v[178:181], v[218:221], v[68:71]
	s_barrier
	s_add_i32 s26, s73, s55
	v_lshl_add_u64 v[194:195], v[194:195], 0, s[20:21]
	s_mov_b32 m0, s26
	ds_read_b128 v[182:185], v173 offset:49152
	ds_read_b128 v[186:189], v173 offset:50176
	ds_read_b128 v[190:193], v173 offset:51200
	ds_read_b128 v[202:205], v173 offset:52224
	ds_read_b128 v[206:209], v173 offset:53248
	ds_read_b128 v[210:213], v173 offset:54272
	ds_read_b128 v[214:217], v173 offset:55296
	ds_read_b128 v[218:221], v173 offset:56320
	global_load_lds_dwordx4 v[194:195], off
	v_lshl_add_u64 v[194:195], v[196:197], 0, s[20:21]
	s_add_i32 m0, s26, 0x2000
	s_add_i32 s26, s74, s55
	global_load_lds_dwordx4 v[194:195], off
	v_lshl_add_u64 v[194:195], v[198:199], 0, s[20:21]
	s_mov_b32 m0, s26
	s_nop 0
	global_load_lds_dwordx4 v[194:195], off
	v_lshl_add_u64 v[194:195], v[222:223], 0, s[20:21]
	s_add_i32 m0, s26, 0x2000
	s_nop 0
	global_load_lds_dwordx4 v[194:195], off
	v_lshl_add_u64 v[194:195], v[224:225], 0, s[20:21]
	s_mov_b32 m0, s60
	s_nop 0
	global_load_lds_dwordx4 v[194:195], off
	v_lshl_add_u64 v[194:195], v[230:231], 0, s[20:21]
	s_mov_b32 m0, s61
	s_nop 0
	global_load_lds_dwordx4 v[194:195], off
	s_waitcnt vmcnt(8)
	s_waitcnt lgkmcnt(0)
	s_barrier
	v_mfma_f32_16x16x32_bf16 v[64:67], v[132:135], v[182:185], v[64:67]
	v_mfma_f32_16x16x32_bf16 v[60:63], v[152:155], v[182:185], v[60:63]
	v_mfma_f32_16x16x32_bf16 v[48:51], v[132:135], v[190:193], v[48:51]
	v_mfma_f32_16x16x32_bf16 v[44:47], v[152:155], v[190:193], v[44:47]
	v_mfma_f32_16x16x32_bf16 v[32:35], v[132:135], v[206:209], v[32:35]
	v_mfma_f32_16x16x32_bf16 v[28:31], v[152:155], v[206:209], v[28:31]
	v_mfma_f32_16x16x32_bf16 v[16:19], v[132:135], v[214:217], v[16:19]
	v_mfma_f32_16x16x32_bf16 v[12:15], v[152:155], v[214:217], v[12:15]
	v_mfma_f32_16x16x32_bf16 v[64:67], v[148:151], v[186:189], v[64:67]
	v_mfma_f32_16x16x32_bf16 v[60:63], v[156:159], v[186:189], v[60:63]
	v_mfma_f32_16x16x32_bf16 v[48:51], v[148:151], v[202:205], v[48:51]
	v_mfma_f32_16x16x32_bf16 v[44:47], v[156:159], v[202:205], v[44:47]
	v_mfma_f32_16x16x32_bf16 v[32:35], v[148:151], v[210:213], v[32:35]
	v_mfma_f32_16x16x32_bf16 v[28:31], v[156:159], v[210:213], v[28:31]
	v_mfma_f32_16x16x32_bf16 v[16:19], v[148:151], v[218:221], v[16:19]
	v_mfma_f32_16x16x32_bf16 v[12:15], v[156:159], v[218:221], v[12:15]
	v_mfma_f32_16x16x32_bf16 v[56:59], v[160:163], v[182:185], v[56:59]
	v_mfma_f32_16x16x32_bf16 v[52:55], v[174:177], v[182:185], v[52:55]
	v_mfma_f32_16x16x32_bf16 v[40:43], v[160:163], v[190:193], v[40:43]
	v_mfma_f32_16x16x32_bf16 v[36:39], v[174:177], v[190:193], v[36:39]
	v_mfma_f32_16x16x32_bf16 v[24:27], v[160:163], v[206:209], v[24:27]
	v_mfma_f32_16x16x32_bf16 v[20:23], v[174:177], v[206:209], v[20:23]
	v_mfma_f32_16x16x32_bf16 v[8:11], v[160:163], v[214:217], v[8:11]
	v_mfma_f32_16x16x32_bf16 v[4:7], v[174:177], v[214:217], v[4:7]
	v_mfma_f32_16x16x32_bf16 v[56:59], v[164:167], v[186:189], v[56:59]
	v_mfma_f32_16x16x32_bf16 v[52:55], v[178:181], v[186:189], v[52:55]
	v_mfma_f32_16x16x32_bf16 v[40:43], v[164:167], v[202:205], v[40:43]
	v_mfma_f32_16x16x32_bf16 v[36:39], v[178:181], v[202:205], v[36:39]
	v_mfma_f32_16x16x32_bf16 v[24:27], v[164:167], v[210:213], v[24:27]
	v_mfma_f32_16x16x32_bf16 v[20:23], v[178:181], v[210:213], v[20:23]
	v_mfma_f32_16x16x32_bf16 v[8:11], v[164:167], v[218:221], v[8:11]
	v_mfma_f32_16x16x32_bf16 v[4:7], v[178:181], v[218:221], v[4:7]
	s_barrier
	s_add_u32 s12, s12, 0x100
	s_addc_u32 s13, s13, 0
	s_add_u32 s11, s11, 0x100
	s_addc_u32 s71, s71, 0
	s_cmp_ge_i32 s72, s8
	s_mov_b32 s26, s72
	s_cbranch_scc0 .LBB0_1000

; #define PG8_GOFFS(slot_) do { _Pragma("unroll") for (int _i = 0; _i < 2; ++_i) { int R, C; stage_rc(tid * 16 + _i * 8192, R, C); _Pragma("unroll") for (int _h = 0; _h < 2; ++_h) { \
;         unsigned t_ = gtab[(slot_) * 256 + R + 128 * _h]; t_ = t_ < (unsigned)(T - 1) ? t_ : (unsigned)(T - 1); voffA[_h][_i] = (t_ * (unsigned)K + (unsigned)C) * 2u; } } } while (0)
; #define PG8_STAGE(bufoff, gbase, voff) do { _Pragma("unroll") for (int _i = 0; _i < 2; ++_i) \
;         __builtin_amdgcn_global_load_lds((const unsigned*)((const char*)(gbase) + (voff)[_i]), (LAS unsigned*)(lds + (bufoff) + ldsw + _i * 8192), 16, 0, 0); } while (0)
; #define PG8_STAGE_A1(bufoff, gbase) do { if (Epi::GATHER) PG8_STAGE(bufoff, gbase, voffA[1]); else PG8_STAGE(bufoff, (gbase) + hstep, voffA[0]); } while (0)
; #define PG8_LDA(dst, b, h) do { _Pragma("unroll") for (int m = 0; m < 4; ++m) _Pragma("unroll") for (int k = 0; k < 2; ++k) dst[m][k] = *(const LAS bf16x8*)(lds + PG8_SA(b, h) + aoff + m * 2048 + k * 1024); } while (0)
; #define PG8_WAIT_V(n) asm volatile("s_waitcnt vmcnt(" #n ")" ::: "memory")
; #define PG8_WAIT_L(n) asm volatile("s_waitcnt lgkmcnt(" #n ")" ::: "memory")
; #define PG8_BAR __builtin_amdgcn_s_barrier()
; template <class Epi, class Sched>
; __device__ __forceinline__ void gemm_phase(const int tid, LAS unsigned char* lds, const bf16* Aop, const bf16* Bop, const int K_, const Sched& S, const Epi& E, const bf16* Aop1 = nullptr, const bf16* Bop1 = nullptr) {
;     ...
;         for (int t = 0; t < nt; t += 2) {
;             const bool last = (t == nt - 2);
;             const char* a1 = cA + (size_t)(t + 1) * kstep;
;             const char* a2 = last ? nA : cA + (size_t)(t + 2) * kstep; const char* b2 = last ? nB : cB + (size_t)(t + 2) * kstep;
;             const char* a3 = a2 + kstep; const char* b3 = b2 + kstep;
;             PG8_LDB(B0, 0, 0); PG8_LDB(B1, 0, 1); PG8_SCHED; PG8_LDA(At, 0, 0); PG8_STAGE_A1(PG8_SA(1, 1), a1);
;             PG8_WAIT_V(8); PG8_WAIT_L(0); PG8_BAR; PG8_MMA(0, 0, At, B0); PG8_MMA(0, 1, At, B1); PG8_BAR; PG8_SCHED;
;             PG8_LDA(At, 0, 1); PG8_STAGE(PG8_SB(0, 0), b2, voffB); PG8_STAGE(PG8_SB(0, 1), b2 + hstep, voffB); if (Epi::GATHER && last && has_next) PG8_GOFFS((ui + 1) & 1); PG8_STAGE(PG8_SA(0, 0), a2, voffA[0]);
;             PG8_WAIT_V(8); PG8_WAIT_L(0); PG8_BAR; PG8_MMA(1, 0, At, B0); PG8_MMA(1, 1, At, B1); PG8_BAR; PG8_SCHED;
.LBB0_1092:
	v_mov_b32_e32 v127, 0
	s_andn2_b64 vcc, exec, s[14:15]
	s_cbranch_vccnz .LBB0_1095
	s_add_u32 s34, s34, 0x80
	s_addc_u32 s35, s35, 0
	s_add_u32 s40, s36, 0x100
	s_addc_u32 s41, s37, 0
	s_mov_b32 s36, 0
	s_add_i32 s60, s36, 2
	s_add_u32 s61, s34, 0x80
	s_addc_u32 s37, s35, 0
	s_add_i32 s66, 0, 0x10000
	s_cmp_eq_u32 s56, s36
	s_cselect_b32 s37, s19, s37
	s_cselect_b32 s36, s18, s61
	v_add_u32_e32 v144, s66, v149
	s_cselect_b32 s65, s27, s41
	s_cselect_b32 s64, s26, s40
	s_add_i32 s61, 0, 0x14000
	ds_read_b128 v[152:155], v144
	ds_read_b128 v[156:159], v144 offset:1024
	ds_read_b128 v[160:163], v144 offset:2048
	ds_read_b128 v[164:167], v144 offset:3072
	v_add_u32_e32 v144, s61, v149
	ds_read_b128 v[168:171], v144
	ds_read_b128 v[172:175], v144 offset:1024
	ds_read_b128 v[176:179], v144 offset:2048
	ds_read_b128 v[180:183], v144 offset:3072
	v_lshl_add_u64 v[144:145], s[34:35], 0, v[140:141]
	s_add_i32 m0, s50, 0xc000
	ds_read_b128 v[184:187], v151
	ds_read_b128 v[188:191], v151 offset:1024
	ds_read_b128 v[192:195], v151 offset:2048
	ds_read_b128 v[202:205], v151 offset:3072
	ds_read_b128 v[206:209], v151 offset:4096
	ds_read_b128 v[210:213], v151 offset:5120
	ds_read_b128 v[214:217], v151 offset:6144
	ds_read_b128 v[218:221], v151 offset:7168
	global_load_lds_dwordx4 v[144:145], off
	v_lshl_add_u64 v[144:145], s[34:35], 0, v[142:143]
	s_add_i32 m0, s50, 0xe000
	s_nop 0
	global_load_lds_dwordx4 v[144:145], off
	s_waitcnt vmcnt(8)
	s_waitcnt lgkmcnt(0)
	s_barrier
	v_mfma_f32_16x16x32_bf16 v[124:127], v[152:155], v[184:187], 0
	v_mfma_f32_16x16x32_bf16 v[128:131], v[160:163], v[184:187], 0
	v_mfma_f32_16x16x32_bf16 v[112:115], v[152:155], v[192:195], 0
	v_mfma_f32_16x16x32_bf16 v[108:111], v[160:163], v[192:195], 0
	v_mfma_f32_16x16x32_bf16 v[96:99], v[152:155], v[206:209], 0
	v_mfma_f32_16x16x32_bf16 v[92:95], v[160:163], v[206:209], 0
	v_mfma_f32_16x16x32_bf16 v[80:83], v[152:155], v[214:217], 0
	v_mfma_f32_16x16x32_bf16 v[76:79], v[160:163], v[214:217], 0
	v_mfma_f32_16x16x32_bf16 v[124:127], v[156:159], v[188:191], v[124:127]
	v_mfma_f32_16x16x32_bf16 v[128:131], v[164:167], v[188:191], v[128:131]
	v_mfma_f32_16x16x32_bf16 v[112:115], v[156:159], v[202:205], v[112:115]
	v_mfma_f32_16x16x32_bf16 v[108:111], v[164:167], v[202:205], v[108:111]
	v_mfma_f32_16x16x32_bf16 v[96:99], v[156:159], v[210:213], v[96:99]
	v_mfma_f32_16x16x32_bf16 v[92:95], v[164:167], v[210:213], v[92:95]
	v_mfma_f32_16x16x32_bf16 v[80:83], v[156:159], v[218:221], v[80:83]
	v_mfma_f32_16x16x32_bf16 v[76:79], v[164:167], v[218:221], v[76:79]
	v_mfma_f32_16x16x32_bf16 v[120:123], v[168:171], v[184:187], 0
	v_mfma_f32_16x16x32_bf16 v[116:119], v[176:179], v[184:187], 0
	v_mfma_f32_16x16x32_bf16 v[104:107], v[168:171], v[192:195], 0
	v_mfma_f32_16x16x32_bf16 v[100:103], v[176:179], v[192:195], 0
	v_mfma_f32_16x16x32_bf16 v[88:91], v[168:171], v[206:209], 0
	v_mfma_f32_16x16x32_bf16 v[84:87], v[176:179], v[206:209], 0
	v_mfma_f32_16x16x32_bf16 v[72:75], v[168:171], v[214:217], 0
	v_mfma_f32_16x16x32_bf16 v[68:71], v[176:179], v[214:217], 0
	v_mfma_f32_16x16x32_bf16 v[120:123], v[172:175], v[188:191], v[120:123]
	v_mfma_f32_16x16x32_bf16 v[116:119], v[180:183], v[188:191], v[116:119]
	v_mfma_f32_16x16x32_bf16 v[104:107], v[172:175], v[202:205], v[104:107]
	v_mfma_f32_16x16x32_bf16 v[100:103], v[180:183], v[202:205], v[100:103]
	v_mfma_f32_16x16x32_bf16 v[88:91], v[172:175], v[210:213], v[88:91]
	v_mfma_f32_16x16x32_bf16 v[84:87], v[180:183], v[210:213], v[84:87]
	v_mfma_f32_16x16x32_bf16 v[72:75], v[172:175], v[218:221], v[72:75]
	v_mfma_f32_16x16x32_bf16 v[68:71], v[180:183], v[218:221], v[68:71]
	s_barrier
	s_add_i32 s66, s66, s49
	v_lshl_add_u64 v[144:145], s[64:65], 0, v[132:133]
	s_mov_b32 m0, s66
	ds_read_b128 v[184:187], v151 offset:16384
	ds_read_b128 v[188:191], v151 offset:17408
	ds_read_b128 v[192:195], v151 offset:18432
	ds_read_b128 v[202:205], v151 offset:19456
	ds_read_b128 v[206:209], v151 offset:20480
	ds_read_b128 v[210:213], v151 offset:21504
	ds_read_b128 v[214:217], v151 offset:22528
	ds_read_b128 v[218:221], v151 offset:23552
	global_load_lds_dwordx4 v[144:145], off
	s_add_i32 m0, s66, 0x2000
	v_lshl_add_u64 v[196:197], s[64:65], 0, v[136:137]
	s_add_u32 s64, s64, s6
	s_addc_u32 s65, s65, s7
	s_add_i32 s61, s61, s49
	global_load_lds_dwordx4 v[196:197], off
	v_lshl_add_u64 v[198:199], s[64:65], 0, v[132:133]
	s_mov_b32 m0, s61
	v_lshl_add_u64 v[222:223], s[64:65], 0, v[136:137]
	global_load_lds_dwordx4 v[198:199], off
	s_add_i32 m0, s61, 0x2000
	v_lshl_add_u64 v[224:225], s[36:37], 0, v[0:1]
	global_load_lds_dwordx4 v[222:223], off
	s_mov_b32 m0, s50
	v_lshl_add_u64 v[230:231], s[36:37], 0, v[134:135]
	global_load_lds_dwordx4 v[224:225], off
	s_mov_b32 m0, s51
	s_nop 0
	global_load_lds_dwordx4 v[230:231], off
	s_waitcnt vmcnt(8)
	s_waitcnt lgkmcnt(0)
	s_barrier
; #define PG8_STAGE(bufoff, gbase, voff) do { _Pragma("unroll") for (int _i = 0; _i < 2; ++_i) \
;         __builtin_amdgcn_global_load_lds((const unsigned*)((const char*)(gbase) + (voff)[_i]), (LAS unsigned*)(lds + (bufoff) + ldsw + _i * 8192), 16, 0, 0); } while (0)
; #define PG8_STAGE_A1(bufoff, gbase) do { if (Epi::GATHER) PG8_STAGE(bufoff, gbase, voffA[1]); else PG8_STAGE(bufoff, (gbase) + hstep, voffA[0]); } while (0)
; #define PG8_LDA(dst, b, h) do { _Pragma("unroll") for (int m = 0; m < 4; ++m) _Pragma("unroll") for (int k = 0; k < 2; ++k) dst[m][k] = *(const LAS bf16x8*)(lds + PG8_SA(b, h) + aoff + m * 2048 + k * 1024); } while (0)
; #define PG8_LDB(dst, b, h) do { _Pragma("unroll") for (int n = 0; n < 2; ++n) _Pragma("unroll") for (int k = 0; k < 2; ++k) dst[n][k] = *(const LAS bf16x8*)(lds + PG8_SB(b, h) + boff + n * 2048 + k * 1024); } while (0)
; #define PG8_MMA(ai, bj, At, Bt) do { __builtin_amdgcn_s_setprio(1); _Pragma("unroll") for (int m = 0; m < 4; ++m) _Pragma("unroll") for (int n = 0; n < 2; ++n) _Pragma("unroll") for (int k = 0; k < 2; ++k) \
;         acc[ai][bj][m][n] = __builtin_amdgcn_mfma_f32_16x16x32_bf16(Bt[n][k], At[m][k], acc[ai][bj][m][n], 0, 0, 0); __builtin_amdgcn_s_setprio(0); } while (0)
; #define PG8_WAIT_V(n) asm volatile("s_waitcnt vmcnt(" #n ")" ::: "memory")
; #define PG8_WAIT_L(n) asm volatile("s_waitcnt lgkmcnt(" #n ")" ::: "memory")
; #define PG8_BAR __builtin_amdgcn_s_barrier()
; #define PG8_SCHED __builtin_amdgcn_sched_barrier(0)
; template <class Epi, class Sched>
; __device__ __forceinline__ void gemm_phase(const int tid, LAS unsigned char* lds, const bf16* Aop, const bf16* Bop, const int K_, const Sched& S, const Epi& E, const bf16* Aop1 = nullptr, const bf16* Bop1 = nullptr) {
;     ...
;             PG8_WAIT_V(8); PG8_WAIT_L(0); PG8_BAR; PG8_MMA(1, 0, At, B0); PG8_MMA(1, 1, At, B1); PG8_BAR; PG8_SCHED;
;             PG8_LDB(B0, 1, 0); PG8_LDB(B1, 1, 1); PG8_SCHED; PG8_LDA(At, 1, 0); PG8_STAGE_A1(PG8_SA(0, 1), a2);
;             PG8_WAIT_V(8); PG8_WAIT_L(0); PG8_BAR; PG8_MMA(0, 0, At, B0); PG8_MMA(0, 1, At, B1); PG8_BAR; PG8_SCHED;
;             PG8_LDA(At, 1, 1); PG8_STAGE(PG8_SB(1, 0), b3, voffB); PG8_STAGE(PG8_SB(1, 1), b3 + hstep, voffB); PG8_STAGE(PG8_SA(1, 0), a3, voffA[0]);
;             PG8_WAIT_V(8); PG8_WAIT_L(0); PG8_BAR; PG8_MMA(1, 0, At, B0); PG8_MMA(1, 1, At, B1); PG8_BAR; PG8_SCHED;
	v_mfma_f32_16x16x32_bf16 v[64:67], v[152:155], v[184:187], 0
	v_mfma_f32_16x16x32_bf16 v[60:63], v[160:163], v[184:187], 0
	v_mfma_f32_16x16x32_bf16 v[48:51], v[152:155], v[192:195], 0
	v_mfma_f32_16x16x32_bf16 v[44:47], v[160:163], v[192:195], 0
	v_mfma_f32_16x16x32_bf16 v[32:35], v[152:155], v[206:209], 0
	v_mfma_f32_16x16x32_bf16 v[28:31], v[160:163], v[206:209], 0
	v_mfma_f32_16x16x32_bf16 v[16:19], v[152:155], v[214:217], 0
	v_mfma_f32_16x16x32_bf16 v[12:15], v[160:163], v[214:217], 0
	v_mfma_f32_16x16x32_bf16 v[64:67], v[156:159], v[188:191], v[64:67]
	v_mfma_f32_16x16x32_bf16 v[60:63], v[164:167], v[188:191], v[60:63]
	v_mfma_f32_16x16x32_bf16 v[48:51], v[156:159], v[202:205], v[48:51]
	v_mfma_f32_16x16x32_bf16 v[44:47], v[164:167], v[202:205], v[44:47]
	v_mfma_f32_16x16x32_bf16 v[32:35], v[156:159], v[210:213], v[32:35]
	v_mfma_f32_16x16x32_bf16 v[28:31], v[164:167], v[210:213], v[28:31]
	v_mfma_f32_16x16x32_bf16 v[16:19], v[156:159], v[218:221], v[16:19]
	v_mfma_f32_16x16x32_bf16 v[12:15], v[164:167], v[218:221], v[12:15]
	v_mfma_f32_16x16x32_bf16 v[56:59], v[168:171], v[184:187], 0
	v_mfma_f32_16x16x32_bf16 v[52:55], v[176:179], v[184:187], 0
	v_mfma_f32_16x16x32_bf16 v[40:43], v[168:171], v[192:195], 0
	v_mfma_f32_16x16x32_bf16 v[36:39], v[176:179], v[192:195], 0
	v_mfma_f32_16x16x32_bf16 v[24:27], v[168:171], v[206:209], 0
	v_mfma_f32_16x16x32_bf16 v[20:23], v[176:179], v[206:209], 0
	v_mfma_f32_16x16x32_bf16 v[8:11], v[168:171], v[214:217], 0
	v_mfma_f32_16x16x32_bf16 v[4:7], v[176:179], v[214:217], 0
	v_mfma_f32_16x16x32_bf16 v[56:59], v[172:175], v[188:191], v[56:59]
	v_mfma_f32_16x16x32_bf16 v[52:55], v[180:183], v[188:191], v[52:55]
	v_mfma_f32_16x16x32_bf16 v[40:43], v[172:175], v[202:205], v[40:43]
	v_mfma_f32_16x16x32_bf16 v[36:39], v[180:183], v[202:205], v[36:39]
	v_mfma_f32_16x16x32_bf16 v[24:27], v[172:175], v[210:213], v[24:27]
	v_mfma_f32_16x16x32_bf16 v[20:23], v[180:183], v[210:213], v[20:23]
	v_mfma_f32_16x16x32_bf16 v[8:11], v[172:175], v[218:221], v[8:11]
	v_mfma_f32_16x16x32_bf16 v[4:7], v[180:183], v[218:221], v[4:7]
	s_barrier
	s_add_i32 s61, 0, 0x18000
	s_add_i32 s64, 0, 0x1c000
	v_add_u32_e32 v164, s61, v149
	v_add_u32_e32 v180, s64, v149
	ds_read_b128 v[152:155], v164
	ds_read_b128 v[156:159], v164 offset:1024
	ds_read_b128 v[160:163], v164 offset:2048
	ds_read_b128 v[164:167], v164 offset:3072
	ds_read_b128 v[168:171], v180
	ds_read_b128 v[172:175], v180 offset:1024
	ds_read_b128 v[176:179], v180 offset:2048
	ds_read_b128 v[180:183], v180 offset:3072
	s_add_u32 s36, s36, s6
	s_addc_u32 s37, s37, s7
	s_mov_b32 m0, s52
	v_lshl_add_u64 v[232:233], s[36:37], 0, v[0:1]
	ds_read_b128 v[184:187], v151 offset:32768
	ds_read_b128 v[188:191], v151 offset:33792
	ds_read_b128 v[192:195], v151 offset:34816
	ds_read_b128 v[202:205], v151 offset:35840
	ds_read_b128 v[206:209], v151 offset:36864
	ds_read_b128 v[210:213], v151 offset:37888
	ds_read_b128 v[214:217], v151 offset:38912
	ds_read_b128 v[218:221], v151 offset:39936
	global_load_lds_dwordx4 v[232:233], off
	v_lshl_add_u64 v[232:233], s[36:37], 0, v[134:135]
	s_mov_b32 m0, s53
	s_nop 0
	global_load_lds_dwordx4 v[232:233], off
	s_waitcnt vmcnt(8)
	s_waitcnt lgkmcnt(0)
	s_barrier
	v_mfma_f32_16x16x32_bf16 v[124:127], v[152:155], v[184:187], v[124:127]
	v_mfma_f32_16x16x32_bf16 v[128:131], v[160:163], v[184:187], v[128:131]
	v_mfma_f32_16x16x32_bf16 v[112:115], v[152:155], v[192:195], v[112:115]
	v_mfma_f32_16x16x32_bf16 v[108:111], v[160:163], v[192:195], v[108:111]
	v_mfma_f32_16x16x32_bf16 v[96:99], v[152:155], v[206:209], v[96:99]
	v_mfma_f32_16x16x32_bf16 v[92:95], v[160:163], v[206:209], v[92:95]
	v_mfma_f32_16x16x32_bf16 v[80:83], v[152:155], v[214:217], v[80:83]
	v_mfma_f32_16x16x32_bf16 v[76:79], v[160:163], v[214:217], v[76:79]
	v_mfma_f32_16x16x32_bf16 v[124:127], v[156:159], v[188:191], v[124:127]
	v_mfma_f32_16x16x32_bf16 v[128:131], v[164:167], v[188:191], v[128:131]
	v_mfma_f32_16x16x32_bf16 v[112:115], v[156:159], v[202:205], v[112:115]
	v_mfma_f32_16x16x32_bf16 v[108:111], v[164:167], v[202:205], v[108:111]
	v_mfma_f32_16x16x32_bf16 v[96:99], v[156:159], v[210:213], v[96:99]
	v_mfma_f32_16x16x32_bf16 v[92:95], v[164:167], v[210:213], v[92:95]
	v_mfma_f32_16x16x32_bf16 v[80:83], v[156:159], v[218:221], v[80:83]
	v_mfma_f32_16x16x32_bf16 v[76:79], v[164:167], v[218:221], v[76:79]
	v_mfma_f32_16x16x32_bf16 v[120:123], v[168:171], v[184:187], v[120:123]
	v_mfma_f32_16x16x32_bf16 v[116:119], v[176:179], v[184:187], v[116:119]
	v_mfma_f32_16x16x32_bf16 v[104:107], v[168:171], v[192:195], v[104:107]
	v_mfma_f32_16x16x32_bf16 v[100:103], v[176:179], v[192:195], v[100:103]
	v_mfma_f32_16x16x32_bf16 v[88:91], v[168:171], v[206:209], v[88:91]
	v_mfma_f32_16x16x32_bf16 v[84:87], v[176:179], v[206:209], v[84:87]
	v_mfma_f32_16x16x32_bf16 v[72:75], v[168:171], v[214:217], v[72:75]
	v_mfma_f32_16x16x32_bf16 v[68:71], v[176:179], v[214:217], v[68:71]
	v_mfma_f32_16x16x32_bf16 v[120:123], v[172:175], v[188:191], v[120:123]
	v_mfma_f32_16x16x32_bf16 v[116:119], v[180:183], v[188:191], v[116:119]
	v_mfma_f32_16x16x32_bf16 v[104:107], v[172:175], v[202:205], v[104:107]
	v_mfma_f32_16x16x32_bf16 v[100:103], v[180:183], v[202:205], v[100:103]
	v_mfma_f32_16x16x32_bf16 v[88:91], v[172:175], v[210:213], v[88:91]
	v_mfma_f32_16x16x32_bf16 v[84:87], v[180:183], v[210:213], v[84:87]
	v_mfma_f32_16x16x32_bf16 v[72:75], v[172:175], v[218:221], v[72:75]
	v_mfma_f32_16x16x32_bf16 v[68:71], v[180:183], v[218:221], v[68:71]
	s_barrier
; #define PG8_GOFFS(slot_) do { _Pragma("unroll") for (int _i = 0; _i < 2; ++_i) { int R, C; stage_rc(tid * 16 + _i * 8192, R, C); _Pragma("unroll") for (int _h = 0; _h < 2; ++_h) { \
;         unsigned t_ = gtab[(slot_) * 256 + R + 128 * _h]; t_ = t_ < (unsigned)(T - 1) ? t_ : (unsigned)(T - 1); voffA[_h][_i] = (t_ * (unsigned)K + (unsigned)C) * 2u; } } } while (0)
; #define PG8_STAGE(bufoff, gbase, voff) do { _Pragma("unroll") for (int _i = 0; _i < 2; ++_i) \
;         __builtin_amdgcn_global_load_lds((const unsigned*)((const char*)(gbase) + (voff)[_i]), (LAS unsigned*)(lds + (bufoff) + ldsw + _i * 8192), 16, 0, 0); } while (0)
; #define PG8_STAGE_A1(bufoff, gbase) do { if (Epi::GATHER) PG8_STAGE(bufoff, gbase, voffA[1]); else PG8_STAGE(bufoff, (gbase) + hstep, voffA[0]); } while (0)
; #define PG8_LDA(dst, b, h) do { _Pragma("unroll") for (int m = 0; m < 4; ++m) _Pragma("unroll") for (int k = 0; k < 2; ++k) dst[m][k] = *(const LAS bf16x8*)(lds + PG8_SA(b, h) + aoff + m * 2048 + k * 1024); } while (0)
; #define PG8_BAR __builtin_amdgcn_s_barrier()
; template <class Epi, class Sched>
; __device__ __forceinline__ void gemm_phase(const int tid, LAS unsigned char* lds, const bf16* Aop, const bf16* Bop, const int K_, const Sched& S, const Epi& E, const bf16* Aop1 = nullptr, const bf16* Bop1 = nullptr) {
;     ...
;             PG8_LDB(B0, 0, 0); PG8_LDB(B1, 0, 1); PG8_SCHED; PG8_LDA(At, 0, 0); PG8_STAGE_A1(PG8_SA(1, 1), a1);
;             PG8_WAIT_V(8); PG8_WAIT_L(0); PG8_BAR; PG8_MMA(0, 0, At, B0); PG8_MMA(0, 1, At, B1); PG8_BAR; PG8_SCHED;
;             PG8_LDA(At, 0, 1); PG8_STAGE(PG8_SB(0, 0), b2, voffB); PG8_STAGE(PG8_SB(0, 1), b2 + hstep, voffB); if (Epi::GATHER && last && has_next) PG8_GOFFS((ui + 1) & 1); PG8_STAGE(PG8_SA(0, 0), a2, voffA[0]);
;             PG8_WAIT_V(8); PG8_WAIT_L(0); PG8_BAR; PG8_MMA(1, 0, At, B0); PG8_MMA(1, 1, At, B1); PG8_BAR; PG8_SCHED;
;             PG8_LDB(B0, 1, 0); PG8_LDB(B1, 1, 1); PG8_SCHED; PG8_LDA(At, 1, 0); PG8_STAGE_A1(PG8_SA(0, 1), a2);
;             PG8_WAIT_V(8); PG8_WAIT_L(0); PG8_BAR; PG8_MMA(0, 0, At, B0); PG8_MMA(0, 1, At, B1); PG8_BAR; PG8_SCHED;
;             PG8_LDA(At, 1, 1); PG8_STAGE(PG8_SB(1, 0), b3, voffB); PG8_STAGE(PG8_SB(1, 1), b3 + hstep, voffB); PG8_STAGE(PG8_SA(1, 0), a3, voffA[0]);
;             PG8_WAIT_V(8); PG8_WAIT_L(0); PG8_BAR; PG8_MMA(1, 0, At, B0); PG8_MMA(1, 1, At, B1); PG8_BAR; PG8_SCHED;
	s_add_i32 s36, s61, s49
	v_lshl_add_u64 v[144:145], v[144:145], 0, s[20:21]
	s_mov_b32 m0, s36
	ds_read_b128 v[184:187], v151 offset:49152
	ds_read_b128 v[188:191], v151 offset:50176
	ds_read_b128 v[192:195], v151 offset:51200
	ds_read_b128 v[202:205], v151 offset:52224
	ds_read_b128 v[206:209], v151 offset:53248
	ds_read_b128 v[210:213], v151 offset:54272
	ds_read_b128 v[214:217], v151 offset:55296
	ds_read_b128 v[218:221], v151 offset:56320
	global_load_lds_dwordx4 v[144:145], off
	v_lshl_add_u64 v[144:145], v[196:197], 0, s[20:21]
	s_add_i32 m0, s36, 0x2000
	s_add_i32 s36, s64, s49
	global_load_lds_dwordx4 v[144:145], off
	v_lshl_add_u64 v[144:145], v[198:199], 0, s[20:21]
	s_mov_b32 m0, s36
	s_nop 0
	global_load_lds_dwordx4 v[144:145], off
	v_lshl_add_u64 v[144:145], v[222:223], 0, s[20:21]
	s_add_i32 m0, s36, 0x2000
	s_nop 0
	global_load_lds_dwordx4 v[144:145], off
	v_lshl_add_u64 v[144:145], v[224:225], 0, s[20:21]
	s_mov_b32 m0, s54
	s_nop 0
	global_load_lds_dwordx4 v[144:145], off
	v_lshl_add_u64 v[144:145], v[230:231], 0, s[20:21]
	s_mov_b32 m0, s55
	s_nop 0
	global_load_lds_dwordx4 v[144:145], off
	s_waitcnt vmcnt(8)
	s_waitcnt lgkmcnt(0)
	s_barrier
	v_mfma_f32_16x16x32_bf16 v[64:67], v[152:155], v[184:187], v[64:67]
	v_mfma_f32_16x16x32_bf16 v[60:63], v[160:163], v[184:187], v[60:63]
	v_mfma_f32_16x16x32_bf16 v[48:51], v[152:155], v[192:195], v[48:51]
	v_mfma_f32_16x16x32_bf16 v[44:47], v[160:163], v[192:195], v[44:47]
	v_mfma_f32_16x16x32_bf16 v[32:35], v[152:155], v[206:209], v[32:35]
	v_mfma_f32_16x16x32_bf16 v[28:31], v[160:163], v[206:209], v[28:31]
	v_mfma_f32_16x16x32_bf16 v[16:19], v[152:155], v[214:217], v[16:19]
	v_mfma_f32_16x16x32_bf16 v[12:15], v[160:163], v[214:217], v[12:15]
	v_mfma_f32_16x16x32_bf16 v[64:67], v[156:159], v[188:191], v[64:67]
	v_mfma_f32_16x16x32_bf16 v[60:63], v[164:167], v[188:191], v[60:63]
	v_mfma_f32_16x16x32_bf16 v[48:51], v[156:159], v[202:205], v[48:51]
	v_mfma_f32_16x16x32_bf16 v[44:47], v[164:167], v[202:205], v[44:47]
	v_mfma_f32_16x16x32_bf16 v[32:35], v[156:159], v[210:213], v[32:35]
	v_mfma_f32_16x16x32_bf16 v[28:31], v[164:167], v[210:213], v[28:31]
	v_mfma_f32_16x16x32_bf16 v[16:19], v[156:159], v[218:221], v[16:19]
	v_mfma_f32_16x16x32_bf16 v[12:15], v[164:167], v[218:221], v[12:15]
	v_mfma_f32_16x16x32_bf16 v[56:59], v[168:171], v[184:187], v[56:59]
	v_mfma_f32_16x16x32_bf16 v[52:55], v[176:179], v[184:187], v[52:55]
	v_mfma_f32_16x16x32_bf16 v[40:43], v[168:171], v[192:195], v[40:43]
	v_mfma_f32_16x16x32_bf16 v[36:39], v[176:179], v[192:195], v[36:39]
	v_mfma_f32_16x16x32_bf16 v[24:27], v[168:171], v[206:209], v[24:27]
	v_mfma_f32_16x16x32_bf16 v[20:23], v[176:179], v[206:209], v[20:23]
	v_mfma_f32_16x16x32_bf16 v[8:11], v[168:171], v[214:217], v[8:11]
	v_mfma_f32_16x16x32_bf16 v[4:7], v[176:179], v[214:217], v[4:7]
	v_mfma_f32_16x16x32_bf16 v[56:59], v[172:175], v[188:191], v[56:59]
	v_mfma_f32_16x16x32_bf16 v[52:55], v[180:183], v[188:191], v[52:55]
	v_mfma_f32_16x16x32_bf16 v[40:43], v[172:175], v[202:205], v[40:43]
	v_mfma_f32_16x16x32_bf16 v[36:39], v[180:183], v[202:205], v[36:39]
	v_mfma_f32_16x16x32_bf16 v[24:27], v[172:175], v[210:213], v[24:27]
	v_mfma_f32_16x16x32_bf16 v[20:23], v[180:183], v[210:213], v[20:23]
	v_mfma_f32_16x16x32_bf16 v[8:11], v[172:175], v[218:221], v[8:11]
	v_mfma_f32_16x16x32_bf16 v[4:7], v[180:183], v[218:221], v[4:7]
	s_barrier
	s_add_u32 s34, s34, 0x100
	s_addc_u32 s35, s35, 0
	s_add_u32 s40, s40, 0x100
	s_addc_u32 s41, s41, 0
	s_cmp_ge_i32 s60, s8
	s_mov_b32 s36, s60
	s_cbranch_scc0 .LBB0_1094
	s_branch .LBB0_1095
.LBB0_1094:
	s_add_i32 s60, s36, 2
	s_add_u32 s61, s34, 0x80
	s_addc_u32 s37, s35, 0
	s_add_i32 s66, 0, 0x10000
	s_cmp_eq_u32 s56, s36
	s_cselect_b32 s37, s19, s37
	s_cselect_b32 s36, s18, s61
	v_add_u32_e32 v144, s66, v149
	s_cselect_b32 s65, s27, s41
	s_cselect_b32 s64, s26, s40
	s_add_i32 s61, 0, 0x14000
	ds_read_b128 v[152:155], v144
	ds_read_b128 v[156:159], v144 offset:1024
	ds_read_b128 v[160:163], v144 offset:2048
	ds_read_b128 v[164:167], v144 offset:3072
	v_add_u32_e32 v144, s61, v149
	ds_read_b128 v[168:171], v144
	ds_read_b128 v[172:175], v144 offset:1024
	ds_read_b128 v[176:179], v144 offset:2048
	ds_read_b128 v[180:183], v144 offset:3072
	v_lshl_add_u64 v[144:145], s[34:35], 0, v[140:141]
	s_add_i32 m0, s50, 0xc000
	ds_read_b128 v[184:187], v151
	ds_read_b128 v[188:191], v151 offset:1024
	ds_read_b128 v[192:195], v151 offset:2048
	ds_read_b128 v[202:205], v151 offset:3072
	ds_read_b128 v[206:209], v151 offset:4096
	ds_read_b128 v[210:213], v151 offset:5120
	ds_read_b128 v[214:217], v151 offset:6144
	ds_read_b128 v[218:221], v151 offset:7168
	global_load_lds_dwordx4 v[144:145], off
	v_lshl_add_u64 v[144:145], s[34:35], 0, v[142:143]
	s_add_i32 m0, s50, 0xe000
	s_nop 0
	global_load_lds_dwordx4 v[144:145], off
	s_waitcnt vmcnt(8)
	s_waitcnt lgkmcnt(0)
	s_barrier
; #define PG8_GOFFS(slot_) do { _Pragma("unroll") for (int _i = 0; _i < 2; ++_i) { int R, C; stage_rc(tid * 16 + _i * 8192, R, C); _Pragma("unroll") for (int _h = 0; _h < 2; ++_h) { \
;         unsigned t_ = gtab[(slot_) * 256 + R + 128 * _h]; t_ = t_ < (unsigned)(T - 1) ? t_ : (unsigned)(T - 1); voffA[_h][_i] = (t_ * (unsigned)K + (unsigned)C) * 2u; } } } while (0)
; #define PG8_STAGE(bufoff, gbase, voff) do { _Pragma("unroll") for (int _i = 0; _i < 2; ++_i) \
;         __builtin_amdgcn_global_load_lds((const unsigned*)((const char*)(gbase) + (voff)[_i]), (LAS unsigned*)(lds + (bufoff) + ldsw + _i * 8192), 16, 0, 0); } while (0)
; #define PG8_STAGE_A1(bufoff, gbase) do { if (Epi::GATHER) PG8_STAGE(bufoff, gbase, voffA[1]); else PG8_STAGE(bufoff, (gbase) + hstep, voffA[0]); } while (0)
; #define PG8_LDA(dst, b, h) do { _Pragma("unroll") for (int m = 0; m < 4; ++m) _Pragma("unroll") for (int k = 0; k < 2; ++k) dst[m][k] = *(const LAS bf16x8*)(lds + PG8_SA(b, h) + aoff + m * 2048 + k * 1024); } while (0)
; #define PG8_LDB(dst, b, h) do { _Pragma("unroll") for (int n = 0; n < 2; ++n) _Pragma("unroll") for (int k = 0; k < 2; ++k) dst[n][k] = *(const LAS bf16x8*)(lds + PG8_SB(b, h) + boff + n * 2048 + k * 1024); } while (0)
; #define PG8_WAIT_V(n) asm volatile("s_waitcnt vmcnt(" #n ")" ::: "memory")
; #define PG8_WAIT_L(n) asm volatile("s_waitcnt lgkmcnt(" #n ")" ::: "memory")
; #define PG8_BAR __builtin_amdgcn_s_barrier()
; #define PG8_SCHED __builtin_amdgcn_sched_barrier(0)
; template <class Epi, class Sched>
; __device__ __forceinline__ void gemm_phase(const int tid, LAS unsigned char* lds, const bf16* Aop, const bf16* Bop, const int K_, const Sched& S, const Epi& E, const bf16* Aop1 = nullptr, const bf16* Bop1 = nullptr) {
;     ...
;             PG8_WAIT_V(8); PG8_WAIT_L(0); PG8_BAR; PG8_MMA(0, 0, At, B0); PG8_MMA(0, 1, At, B1); PG8_BAR; PG8_SCHED;
;             PG8_LDA(At, 0, 1); PG8_STAGE(PG8_SB(0, 0), b2, voffB); PG8_STAGE(PG8_SB(0, 1), b2 + hstep, voffB); if (Epi::GATHER && last && has_next) PG8_GOFFS((ui + 1) & 1); PG8_STAGE(PG8_SA(0, 0), a2, voffA[0]);
;             PG8_WAIT_V(8); PG8_WAIT_L(0); PG8_BAR; PG8_MMA(1, 0, At, B0); PG8_MMA(1, 1, At, B1); PG8_BAR; PG8_SCHED;
;             PG8_LDB(B0, 1, 0); PG8_LDB(B1, 1, 1); PG8_SCHED; PG8_LDA(At, 1, 0); PG8_STAGE_A1(PG8_SA(0, 1), a2);
	v_mfma_f32_16x16x32_bf16 v[124:127], v[152:155], v[184:187], v[124:127]
	v_mfma_f32_16x16x32_bf16 v[128:131], v[160:163], v[184:187], v[128:131]
	v_mfma_f32_16x16x32_bf16 v[112:115], v[152:155], v[192:195], v[112:115]
	v_mfma_f32_16x16x32_bf16 v[108:111], v[160:163], v[192:195], v[108:111]
	v_mfma_f32_16x16x32_bf16 v[96:99], v[152:155], v[206:209], v[96:99]
	v_mfma_f32_16x16x32_bf16 v[92:95], v[160:163], v[206:209], v[92:95]
	v_mfma_f32_16x16x32_bf16 v[80:83], v[152:155], v[214:217], v[80:83]
	v_mfma_f32_16x16x32_bf16 v[76:79], v[160:163], v[214:217], v[76:79]
	v_mfma_f32_16x16x32_bf16 v[124:127], v[156:159], v[188:191], v[124:127]
	v_mfma_f32_16x16x32_bf16 v[128:131], v[164:167], v[188:191], v[128:131]
	v_mfma_f32_16x16x32_bf16 v[112:115], v[156:159], v[202:205], v[112:115]
	v_mfma_f32_16x16x32_bf16 v[108:111], v[164:167], v[202:205], v[108:111]
	v_mfma_f32_16x16x32_bf16 v[96:99], v[156:159], v[210:213], v[96:99]
	v_mfma_f32_16x16x32_bf16 v[92:95], v[164:167], v[210:213], v[92:95]
	v_mfma_f32_16x16x32_bf16 v[80:83], v[156:159], v[218:221], v[80:83]
	v_mfma_f32_16x16x32_bf16 v[76:79], v[164:167], v[218:221], v[76:79]
	v_mfma_f32_16x16x32_bf16 v[120:123], v[168:171], v[184:187], v[120:123]
	v_mfma_f32_16x16x32_bf16 v[116:119], v[176:179], v[184:187], v[116:119]
	v_mfma_f32_16x16x32_bf16 v[104:107], v[168:171], v[192:195], v[104:107]
	v_mfma_f32_16x16x32_bf16 v[100:103], v[176:179], v[192:195], v[100:103]
	v_mfma_f32_16x16x32_bf16 v[88:91], v[168:171], v[206:209], v[88:91]
	v_mfma_f32_16x16x32_bf16 v[84:87], v[176:179], v[206:209], v[84:87]
	v_mfma_f32_16x16x32_bf16 v[72:75], v[168:171], v[214:217], v[72:75]
	v_mfma_f32_16x16x32_bf16 v[68:71], v[176:179], v[214:217], v[68:71]
	v_mfma_f32_16x16x32_bf16 v[120:123], v[172:175], v[188:191], v[120:123]
	v_mfma_f32_16x16x32_bf16 v[116:119], v[180:183], v[188:191], v[116:119]
	v_mfma_f32_16x16x32_bf16 v[104:107], v[172:175], v[202:205], v[104:107]
	v_mfma_f32_16x16x32_bf16 v[100:103], v[180:183], v[202:205], v[100:103]
	v_mfma_f32_16x16x32_bf16 v[88:91], v[172:175], v[210:213], v[88:91]
	v_mfma_f32_16x16x32_bf16 v[84:87], v[180:183], v[210:213], v[84:87]
	v_mfma_f32_16x16x32_bf16 v[72:75], v[172:175], v[218:221], v[72:75]
	v_mfma_f32_16x16x32_bf16 v[68:71], v[180:183], v[218:221], v[68:71]
	s_barrier
	s_add_i32 s66, s66, s49
	v_lshl_add_u64 v[144:145], s[64:65], 0, v[132:133]
	s_mov_b32 m0, s66
	ds_read_b128 v[184:187], v151 offset:16384
	ds_read_b128 v[188:191], v151 offset:17408
	ds_read_b128 v[192:195], v151 offset:18432
	ds_read_b128 v[202:205], v151 offset:19456
	ds_read_b128 v[206:209], v151 offset:20480
	ds_read_b128 v[210:213], v151 offset:21504
	ds_read_b128 v[214:217], v151 offset:22528
	ds_read_b128 v[218:221], v151 offset:23552
	global_load_lds_dwordx4 v[144:145], off
	s_add_i32 m0, s66, 0x2000
	v_lshl_add_u64 v[196:197], s[64:65], 0, v[136:137]
	s_add_u32 s64, s64, s6
	s_addc_u32 s65, s65, s7
	s_add_i32 s61, s61, s49
	global_load_lds_dwordx4 v[196:197], off
	v_lshl_add_u64 v[198:199], s[64:65], 0, v[132:133]
	s_mov_b32 m0, s61
	v_lshl_add_u64 v[222:223], s[64:65], 0, v[136:137]
	global_load_lds_dwordx4 v[198:199], off
	s_add_i32 m0, s61, 0x2000
	v_lshl_add_u64 v[224:225], s[36:37], 0, v[0:1]
	global_load_lds_dwordx4 v[222:223], off
	s_mov_b32 m0, s50
	v_lshl_add_u64 v[230:231], s[36:37], 0, v[134:135]
	global_load_lds_dwordx4 v[224:225], off
	s_mov_b32 m0, s51
	s_nop 0
	global_load_lds_dwordx4 v[230:231], off
	s_waitcnt vmcnt(8)
	s_waitcnt lgkmcnt(0)
	s_barrier
	v_mfma_f32_16x16x32_bf16 v[64:67], v[152:155], v[184:187], v[64:67]
	v_mfma_f32_16x16x32_bf16 v[60:63], v[160:163], v[184:187], v[60:63]
	v_mfma_f32_16x16x32_bf16 v[48:51], v[152:155], v[192:195], v[48:51]
	v_mfma_f32_16x16x32_bf16 v[44:47], v[160:163], v[192:195], v[44:47]
	v_mfma_f32_16x16x32_bf16 v[32:35], v[152:155], v[206:209], v[32:35]
	v_mfma_f32_16x16x32_bf16 v[28:31], v[160:163], v[206:209], v[28:31]
	v_mfma_f32_16x16x32_bf16 v[16:19], v[152:155], v[214:217], v[16:19]
	v_mfma_f32_16x16x32_bf16 v[12:15], v[160:163], v[214:217], v[12:15]
	v_mfma_f32_16x16x32_bf16 v[64:67], v[156:159], v[188:191], v[64:67]
	v_mfma_f32_16x16x32_bf16 v[60:63], v[164:167], v[188:191], v[60:63]
	v_mfma_f32_16x16x32_bf16 v[48:51], v[156:159], v[202:205], v[48:51]
	v_mfma_f32_16x16x32_bf16 v[44:47], v[164:167], v[202:205], v[44:47]
	v_mfma_f32_16x16x32_bf16 v[32:35], v[156:159], v[210:213], v[32:35]
	v_mfma_f32_16x16x32_bf16 v[28:31], v[164:167], v[210:213], v[28:31]
	v_mfma_f32_16x16x32_bf16 v[16:19], v[156:159], v[218:221], v[16:19]
	v_mfma_f32_16x16x32_bf16 v[12:15], v[164:167], v[218:221], v[12:15]
	v_mfma_f32_16x16x32_bf16 v[56:59], v[168:171], v[184:187], v[56:59]
	v_mfma_f32_16x16x32_bf16 v[52:55], v[176:179], v[184:187], v[52:55]
	v_mfma_f32_16x16x32_bf16 v[40:43], v[168:171], v[192:195], v[40:43]
	v_mfma_f32_16x16x32_bf16 v[36:39], v[176:179], v[192:195], v[36:39]
	v_mfma_f32_16x16x32_bf16 v[24:27], v[168:171], v[206:209], v[24:27]
	v_mfma_f32_16x16x32_bf16 v[20:23], v[176:179], v[206:209], v[20:23]
	v_mfma_f32_16x16x32_bf16 v[8:11], v[168:171], v[214:217], v[8:11]
	v_mfma_f32_16x16x32_bf16 v[4:7], v[176:179], v[214:217], v[4:7]
	v_mfma_f32_16x16x32_bf16 v[56:59], v[172:175], v[188:191], v[56:59]
	v_mfma_f32_16x16x32_bf16 v[52:55], v[180:183], v[188:191], v[52:55]
	v_mfma_f32_16x16x32_bf16 v[40:43], v[172:175], v[202:205], v[40:43]
	v_mfma_f32_16x16x32_bf16 v[36:39], v[180:183], v[202:205], v[36:39]
	v_mfma_f32_16x16x32_bf16 v[24:27], v[172:175], v[210:213], v[24:27]
	v_mfma_f32_16x16x32_bf16 v[20:23], v[180:183], v[210:213], v[20:23]
	v_mfma_f32_16x16x32_bf16 v[8:11], v[172:175], v[218:221], v[8:11]
	v_mfma_f32_16x16x32_bf16 v[4:7], v[180:183], v[218:221], v[4:7]
	s_barrier
; #define PG8_STAGE(bufoff, gbase, voff) do { _Pragma("unroll") for (int _i = 0; _i < 2; ++_i) \
;         __builtin_amdgcn_global_load_lds((const unsigned*)((const char*)(gbase) + (voff)[_i]), (LAS unsigned*)(lds + (bufoff) + ldsw + _i * 8192), 16, 0, 0); } while (0)
; #define PG8_STAGE_A1(bufoff, gbase) do { if (Epi::GATHER) PG8_STAGE(bufoff, gbase, voffA[1]); else PG8_STAGE(bufoff, (gbase) + hstep, voffA[0]); } while (0)
; #define PG8_LDA(dst, b, h) do { _Pragma("unroll") for (int m = 0; m < 4; ++m) _Pragma("unroll") for (int k = 0; k < 2; ++k) dst[m][k] = *(const LAS bf16x8*)(lds + PG8_SA(b, h) + aoff + m * 2048 + k * 1024); } while (0)
; #define PG8_LDB(dst, b, h) do { _Pragma("unroll") for (int n = 0; n < 2; ++n) _Pragma("unroll") for (int k = 0; k < 2; ++k) dst[n][k] = *(const LAS bf16x8*)(lds + PG8_SB(b, h) + boff + n * 2048 + k * 1024); } while (0)
; #define PG8_MMA(ai, bj, At, Bt) do { __builtin_amdgcn_s_setprio(1); _Pragma("unroll") for (int m = 0; m < 4; ++m) _Pragma("unroll") for (int n = 0; n < 2; ++n) _Pragma("unroll") for (int k = 0; k < 2; ++k) \
;         acc[ai][bj][m][n] = __builtin_amdgcn_mfma_f32_16x16x32_bf16(Bt[n][k], At[m][k], acc[ai][bj][m][n], 0, 0, 0); __builtin_amdgcn_s_setprio(0); } while (0)
; #define PG8_WAIT_V(n) asm volatile("s_waitcnt vmcnt(" #n ")" ::: "memory")
; #define PG8_WAIT_L(n) asm volatile("s_waitcnt lgkmcnt(" #n ")" ::: "memory")
; #define PG8_BAR __builtin_amdgcn_s_barrier()
; #define PG8_SCHED __builtin_amdgcn_sched_barrier(0)
; template <class Epi, class Sched>
; __device__ __forceinline__ void gemm_phase(const int tid, LAS unsigned char* lds, const bf16* Aop, const bf16* Bop, const int K_, const Sched& S, const Epi& E, const bf16* Aop1 = nullptr, const bf16* Bop1 = nullptr) {
;     ...
;             PG8_LDB(B0, 1, 0); PG8_LDB(B1, 1, 1); PG8_SCHED; PG8_LDA(At, 1, 0); PG8_STAGE_A1(PG8_SA(0, 1), a2);
;             PG8_WAIT_V(8); PG8_WAIT_L(0); PG8_BAR; PG8_MMA(0, 0, At, B0); PG8_MMA(0, 1, At, B1); PG8_BAR; PG8_SCHED;
;             PG8_LDA(At, 1, 1); PG8_STAGE(PG8_SB(1, 0), b3, voffB); PG8_STAGE(PG8_SB(1, 1), b3 + hstep, voffB); PG8_STAGE(PG8_SA(1, 0), a3, voffA[0]);
;             PG8_WAIT_V(8); PG8_WAIT_L(0); PG8_BAR; PG8_MMA(1, 0, At, B0); PG8_MMA(1, 1, At, B1); PG8_BAR; PG8_SCHED;
	s_add_i32 s61, 0, 0x18000
	s_add_i32 s64, 0, 0x1c000
	v_add_u32_e32 v164, s61, v149
	v_add_u32_e32 v180, s64, v149
	ds_read_b128 v[152:155], v164
	ds_read_b128 v[156:159], v164 offset:1024
	ds_read_b128 v[160:163], v164 offset:2048
	ds_read_b128 v[164:167], v164 offset:3072
	ds_read_b128 v[168:171], v180
	ds_read_b128 v[172:175], v180 offset:1024
	ds_read_b128 v[176:179], v180 offset:2048
	ds_read_b128 v[180:183], v180 offset:3072
	s_add_u32 s36, s36, s6
	s_addc_u32 s37, s37, s7
	s_mov_b32 m0, s52
	v_lshl_add_u64 v[232:233], s[36:37], 0, v[0:1]
	ds_read_b128 v[184:187], v151 offset:32768
	ds_read_b128 v[188:191], v151 offset:33792
	ds_read_b128 v[192:195], v151 offset:34816
	ds_read_b128 v[202:205], v151 offset:35840
	ds_read_b128 v[206:209], v151 offset:36864
	ds_read_b128 v[210:213], v151 offset:37888
	ds_read_b128 v[214:217], v151 offset:38912
	ds_read_b128 v[218:221], v151 offset:39936
	global_load_lds_dwordx4 v[232:233], off
	v_lshl_add_u64 v[232:233], s[36:37], 0, v[134:135]
	s_mov_b32 m0, s53
	s_nop 0
	global_load_lds_dwordx4 v[232:233], off
	s_waitcnt vmcnt(8)
	s_waitcnt lgkmcnt(0)
	s_barrier
	v_mfma_f32_16x16x32_bf16 v[124:127], v[152:155], v[184:187], v[124:127]
	v_mfma_f32_16x16x32_bf16 v[128:131], v[160:163], v[184:187], v[128:131]
	v_mfma_f32_16x16x32_bf16 v[112:115], v[152:155], v[192:195], v[112:115]
	v_mfma_f32_16x16x32_bf16 v[108:111], v[160:163], v[192:195], v[108:111]
	v_mfma_f32_16x16x32_bf16 v[96:99], v[152:155], v[206:209], v[96:99]
	v_mfma_f32_16x16x32_bf16 v[92:95], v[160:163], v[206:209], v[92:95]
	v_mfma_f32_16x16x32_bf16 v[80:83], v[152:155], v[214:217], v[80:83]
	v_mfma_f32_16x16x32_bf16 v[76:79], v[160:163], v[214:217], v[76:79]
	v_mfma_f32_16x16x32_bf16 v[124:127], v[156:159], v[188:191], v[124:127]
	v_mfma_f32_16x16x32_bf16 v[128:131], v[164:167], v[188:191], v[128:131]
	v_mfma_f32_16x16x32_bf16 v[112:115], v[156:159], v[202:205], v[112:115]
	v_mfma_f32_16x16x32_bf16 v[108:111], v[164:167], v[202:205], v[108:111]
	v_mfma_f32_16x16x32_bf16 v[96:99], v[156:159], v[210:213], v[96:99]
	v_mfma_f32_16x16x32_bf16 v[92:95], v[164:167], v[210:213], v[92:95]
	v_mfma_f32_16x16x32_bf16 v[80:83], v[156:159], v[218:221], v[80:83]
	v_mfma_f32_16x16x32_bf16 v[76:79], v[164:167], v[218:221], v[76:79]
	v_mfma_f32_16x16x32_bf16 v[120:123], v[168:171], v[184:187], v[120:123]
	v_mfma_f32_16x16x32_bf16 v[116:119], v[176:179], v[184:187], v[116:119]
	v_mfma_f32_16x16x32_bf16 v[104:107], v[168:171], v[192:195], v[104:107]
	v_mfma_f32_16x16x32_bf16 v[100:103], v[176:179], v[192:195], v[100:103]
	v_mfma_f32_16x16x32_bf16 v[88:91], v[168:171], v[206:209], v[88:91]
	v_mfma_f32_16x16x32_bf16 v[84:87], v[176:179], v[206:209], v[84:87]
	v_mfma_f32_16x16x32_bf16 v[72:75], v[168:171], v[214:217], v[72:75]
	v_mfma_f32_16x16x32_bf16 v[68:71], v[176:179], v[214:217], v[68:71]
	v_mfma_f32_16x16x32_bf16 v[120:123], v[172:175], v[188:191], v[120:123]
	v_mfma_f32_16x16x32_bf16 v[116:119], v[180:183], v[188:191], v[116:119]
	v_mfma_f32_16x16x32_bf16 v[104:107], v[172:175], v[202:205], v[104:107]
	v_mfma_f32_16x16x32_bf16 v[100:103], v[180:183], v[202:205], v[100:103]
	v_mfma_f32_16x16x32_bf16 v[88:91], v[172:175], v[210:213], v[88:91]
	v_mfma_f32_16x16x32_bf16 v[84:87], v[180:183], v[210:213], v[84:87]
	v_mfma_f32_16x16x32_bf16 v[72:75], v[172:175], v[218:221], v[72:75]
	v_mfma_f32_16x16x32_bf16 v[68:71], v[180:183], v[218:221], v[68:71]
	s_barrier
	s_add_i32 s36, s61, s49
	v_lshl_add_u64 v[144:145], v[144:145], 0, s[20:21]
	s_mov_b32 m0, s36
	ds_read_b128 v[184:187], v151 offset:49152
	ds_read_b128 v[188:191], v151 offset:50176
	ds_read_b128 v[192:195], v151 offset:51200
	ds_read_b128 v[202:205], v151 offset:52224
	ds_read_b128 v[206:209], v151 offset:53248
	ds_read_b128 v[210:213], v151 offset:54272
	ds_read_b128 v[214:217], v151 offset:55296
	ds_read_b128 v[218:221], v151 offset:56320
	global_load_lds_dwordx4 v[144:145], off
	v_lshl_add_u64 v[144:145], v[196:197], 0, s[20:21]
	s_add_i32 m0, s36, 0x2000
	s_add_i32 s36, s64, s49
	global_load_lds_dwordx4 v[144:145], off
	v_lshl_add_u64 v[144:145], v[198:199], 0, s[20:21]
	s_mov_b32 m0, s36
	s_nop 0
	global_load_lds_dwordx4 v[144:145], off
	v_lshl_add_u64 v[144:145], v[222:223], 0, s[20:21]
	s_add_i32 m0, s36, 0x2000
	s_nop 0
	global_load_lds_dwordx4 v[144:145], off
	v_lshl_add_u64 v[144:145], v[224:225], 0, s[20:21]
	s_mov_b32 m0, s54
	s_nop 0
	global_load_lds_dwordx4 v[144:145], off
	v_lshl_add_u64 v[144:145], v[230:231], 0, s[20:21]
	s_mov_b32 m0, s55
	s_nop 0
	global_load_lds_dwordx4 v[144:145], off
	s_waitcnt vmcnt(8)
	s_waitcnt lgkmcnt(0)
	s_barrier
	v_mfma_f32_16x16x32_bf16 v[64:67], v[152:155], v[184:187], v[64:67]
	v_mfma_f32_16x16x32_bf16 v[60:63], v[160:163], v[184:187], v[60:63]
	v_mfma_f32_16x16x32_bf16 v[48:51], v[152:155], v[192:195], v[48:51]
	v_mfma_f32_16x16x32_bf16 v[44:47], v[160:163], v[192:195], v[44:47]
	v_mfma_f32_16x16x32_bf16 v[32:35], v[152:155], v[206:209], v[32:35]
	v_mfma_f32_16x16x32_bf16 v[28:31], v[160:163], v[206:209], v[28:31]
	v_mfma_f32_16x16x32_bf16 v[16:19], v[152:155], v[214:217], v[16:19]
	v_mfma_f32_16x16x32_bf16 v[12:15], v[160:163], v[214:217], v[12:15]
	v_mfma_f32_16x16x32_bf16 v[64:67], v[156:159], v[188:191], v[64:67]
	v_mfma_f32_16x16x32_bf16 v[60:63], v[164:167], v[188:191], v[60:63]
	v_mfma_f32_16x16x32_bf16 v[48:51], v[156:159], v[202:205], v[48:51]
	v_mfma_f32_16x16x32_bf16 v[44:47], v[164:167], v[202:205], v[44:47]
	v_mfma_f32_16x16x32_bf16 v[32:35], v[156:159], v[210:213], v[32:35]
	v_mfma_f32_16x16x32_bf16 v[28:31], v[164:167], v[210:213], v[28:31]
	v_mfma_f32_16x16x32_bf16 v[16:19], v[156:159], v[218:221], v[16:19]
	v_mfma_f32_16x16x32_bf16 v[12:15], v[164:167], v[218:221], v[12:15]
	v_mfma_f32_16x16x32_bf16 v[56:59], v[168:171], v[184:187], v[56:59]
	v_mfma_f32_16x16x32_bf16 v[52:55], v[176:179], v[184:187], v[52:55]
	v_mfma_f32_16x16x32_bf16 v[40:43], v[168:171], v[192:195], v[40:43]
	v_mfma_f32_16x16x32_bf16 v[36:39], v[176:179], v[192:195], v[36:39]
	v_mfma_f32_16x16x32_bf16 v[24:27], v[168:171], v[206:209], v[24:27]
	v_mfma_f32_16x16x32_bf16 v[20:23], v[176:179], v[206:209], v[20:23]
	v_mfma_f32_16x16x32_bf16 v[8:11], v[168:171], v[214:217], v[8:11]
	v_mfma_f32_16x16x32_bf16 v[4:7], v[176:179], v[214:217], v[4:7]
	v_mfma_f32_16x16x32_bf16 v[56:59], v[172:175], v[188:191], v[56:59]
	v_mfma_f32_16x16x32_bf16 v[52:55], v[180:183], v[188:191], v[52:55]
	v_mfma_f32_16x16x32_bf16 v[40:43], v[172:175], v[202:205], v[40:43]
	v_mfma_f32_16x16x32_bf16 v[36:39], v[180:183], v[202:205], v[36:39]
	v_mfma_f32_16x16x32_bf16 v[24:27], v[172:175], v[210:213], v[24:27]
	v_mfma_f32_16x16x32_bf16 v[20:23], v[180:183], v[210:213], v[20:23]
	v_mfma_f32_16x16x32_bf16 v[8:11], v[172:175], v[218:221], v[8:11]
	v_mfma_f32_16x16x32_bf16 v[4:7], v[180:183], v[218:221], v[4:7]
	s_barrier
	s_add_u32 s34, s34, 0x100
	s_addc_u32 s35, s35, 0
	s_add_u32 s40, s40, 0x100
	s_addc_u32 s41, s41, 0
	s_cmp_ge_i32 s60, s8
	s_mov_b32 s36, s60
	s_cbranch_scc0 .LBB0_1094

; #define PG8_GOFFS(slot_) do { _Pragma("unroll") for (int _i = 0; _i < 2; ++_i) { int R, C; stage_rc(tid * 16 + _i * 8192, R, C); _Pragma("unroll") for (int _h = 0; _h < 2; ++_h) { \
;         unsigned t_ = gtab[(slot_) * 256 + R + 128 * _h]; t_ = t_ < (unsigned)(T - 1) ? t_ : (unsigned)(T - 1); voffA[_h][_i] = (t_ * (unsigned)K + (unsigned)C) * 2u; } } } while (0)
; #define PG8_STAGE(bufoff, gbase, voff) do { _Pragma("unroll") for (int _i = 0; _i < 2; ++_i) \
;         __builtin_amdgcn_global_load_lds((const unsigned*)((const char*)(gbase) + (voff)[_i]), (LAS unsigned*)(lds + (bufoff) + ldsw + _i * 8192), 16, 0, 0); } while (0)
; #define PG8_STAGE_A1(bufoff, gbase) do { if (Epi::GATHER) PG8_STAGE(bufoff, gbase, voffA[1]); else PG8_STAGE(bufoff, (gbase) + hstep, voffA[0]); } while (0)
; #define PG8_LDA(dst, b, h) do { _Pragma("unroll") for (int m = 0; m < 4; ++m) _Pragma("unroll") for (int k = 0; k < 2; ++k) dst[m][k] = *(const LAS bf16x8*)(lds + PG8_SA(b, h) + aoff + m * 2048 + k * 1024); } while (0)
; #define PG8_BAR __builtin_amdgcn_s_barrier()
; template <class Epi, class Sched>
; __device__ __forceinline__ void gemm_phase(const int tid, LAS unsigned char* lds, const bf16* Aop, const bf16* Bop, const int K_, const Sched& S, const Epi& E, const bf16* Aop1 = nullptr, const bf16* Bop1 = nullptr) {
;     ...
;             PG8_LDB(B0, 0, 0); PG8_LDB(B1, 0, 1); PG8_SCHED; PG8_LDA(At, 0, 0); PG8_STAGE_A1(PG8_SA(1, 1), a1);
;             PG8_WAIT_V(8); PG8_WAIT_L(0); PG8_BAR; PG8_MMA(0, 0, At, B0); PG8_MMA(0, 1, At, B1); PG8_BAR; PG8_SCHED;
;             PG8_LDA(At, 0, 1); PG8_STAGE(PG8_SB(0, 0), b2, voffB); PG8_STAGE(PG8_SB(0, 1), b2 + hstep, voffB); if (Epi::GATHER && last && has_next) PG8_GOFFS((ui + 1) & 1); PG8_STAGE(PG8_SA(0, 0), a2, voffA[0]);
;             PG8_WAIT_V(8); PG8_WAIT_L(0); PG8_BAR; PG8_MMA(1, 0, At, B0); PG8_MMA(1, 1, At, B1); PG8_BAR; PG8_SCHED;
;             PG8_LDB(B0, 1, 0); PG8_LDB(B1, 1, 1); PG8_SCHED; PG8_LDA(At, 1, 0); PG8_STAGE_A1(PG8_SA(0, 1), a2);
;             PG8_WAIT_V(8); PG8_WAIT_L(0); PG8_BAR; PG8_MMA(0, 0, At, B0); PG8_MMA(0, 1, At, B1); PG8_BAR; PG8_SCHED;
;             PG8_LDA(At, 1, 1); PG8_STAGE(PG8_SB(1, 0), b3, voffB); PG8_STAGE(PG8_SB(1, 1), b3 + hstep, voffB); PG8_STAGE(PG8_SA(1, 0), a3, voffA[0]);
;             PG8_WAIT_V(8); PG8_WAIT_L(0); PG8_BAR; PG8_MMA(1, 0, At, B0); PG8_MMA(1, 1, At, B1); PG8_BAR; PG8_SCHED;
.LBB0_1314:
	s_add_i32 s69, s69, 2
	s_add_u32 s40, s40, 0x100
	s_addc_u32 s41, s41, 0
	s_and_b64 s[42:43], s[42:43], exec
	s_cselect_b32 s42, 0, s40
	s_cselect_b32 s43, 0, s41
	s_add_u32 s42, s4, s42
	s_mov_b32 m0, s52
	s_addc_u32 s43, s5, s43
	global_load_lds_dwordx4 v204, s[42:43]
	s_mov_b32 m0, s53
	v_mov_b32_e32 v205, v2
	global_load_lds_dwordx4 v208, s[42:43]
	s_waitcnt vmcnt(8)
	s_waitcnt lgkmcnt(0)
	v_mov_b32_e32 v209, v2
	v_mov_b32_e32 v207, v2
	v_mov_b32_e32 v211, v2
	v_lshl_add_u64 v[196:197], s[42:43], 0, v[204:205]
	v_lshl_add_u64 v[198:199], s[42:43], 0, v[208:209]
	s_barrier
	s_waitcnt lgkmcnt(0)
	v_mfma_f32_16x16x32_bf16 v[64:67], v[148:151], v[188:191], v[64:67]
	v_mfma_f32_16x16x32_bf16 v[56:59], v[156:159], v[188:191], v[56:59]
	v_mfma_f32_16x16x32_bf16 v[48:51], v[148:151], v[180:183], v[48:51]
	v_mfma_f32_16x16x32_bf16 v[40:43], v[156:159], v[180:183], v[40:43]
	v_mfma_f32_16x16x32_bf16 v[32:35], v[148:151], v[172:175], v[32:35]
	v_mfma_f32_16x16x32_bf16 v[24:27], v[156:159], v[172:175], v[24:27]
	v_mfma_f32_16x16x32_bf16 v[16:19], v[148:151], v[164:167], v[16:19]
	v_mfma_f32_16x16x32_bf16 v[8:11], v[156:159], v[164:167], v[8:11]
	v_mfma_f32_16x16x32_bf16 v[64:67], v[152:155], v[192:195], v[64:67]
	v_mfma_f32_16x16x32_bf16 v[56:59], v[160:163], v[192:195], v[56:59]
	v_mfma_f32_16x16x32_bf16 v[48:51], v[152:155], v[184:187], v[48:51]
	v_mfma_f32_16x16x32_bf16 v[40:43], v[160:163], v[184:187], v[40:43]
	v_mfma_f32_16x16x32_bf16 v[32:35], v[152:155], v[176:179], v[32:35]
	v_mfma_f32_16x16x32_bf16 v[24:27], v[160:163], v[176:179], v[24:27]
	v_mfma_f32_16x16x32_bf16 v[16:19], v[152:155], v[168:171], v[16:19]
	v_mfma_f32_16x16x32_bf16 v[8:11], v[160:163], v[168:171], v[8:11]
	v_mfma_f32_16x16x32_bf16 v[60:63], v[132:135], v[188:191], v[60:63]
	v_mfma_f32_16x16x32_bf16 v[52:55], v[140:143], v[188:191], v[52:55]
	v_mfma_f32_16x16x32_bf16 v[44:47], v[132:135], v[180:183], v[44:47]
	v_mfma_f32_16x16x32_bf16 v[36:39], v[140:143], v[180:183], v[36:39]
	v_mfma_f32_16x16x32_bf16 v[28:31], v[132:135], v[172:175], v[28:31]
	v_mfma_f32_16x16x32_bf16 v[20:23], v[140:143], v[172:175], v[20:23]
	v_mfma_f32_16x16x32_bf16 v[12:15], v[132:135], v[164:167], v[12:15]
	v_mfma_f32_16x16x32_bf16 v[4:7], v[140:143], v[164:167], v[4:7]
	v_mfma_f32_16x16x32_bf16 v[60:63], v[136:139], v[192:195], v[60:63]
	v_mfma_f32_16x16x32_bf16 v[52:55], v[144:147], v[192:195], v[52:55]
	v_mfma_f32_16x16x32_bf16 v[44:47], v[136:139], v[184:187], v[44:47]
	v_mfma_f32_16x16x32_bf16 v[36:39], v[144:147], v[184:187], v[36:39]
	v_mfma_f32_16x16x32_bf16 v[28:31], v[136:139], v[176:179], v[28:31]
	v_mfma_f32_16x16x32_bf16 v[20:23], v[144:147], v[176:179], v[20:23]
	v_mfma_f32_16x16x32_bf16 v[12:15], v[136:139], v[168:171], v[12:15]
	v_mfma_f32_16x16x32_bf16 v[4:7], v[144:147], v[168:171], v[4:7]
	s_barrier
	s_add_i32 s70, 0, 0x18000
	s_add_i32 s71, 0, 0x1c000
	v_add_u32_e32 v144, s70, v242
	v_add_u32_e32 v160, s71, v242
	ds_read_b128 v[132:135], v144
	ds_read_b128 v[136:139], v144 offset:1024
	ds_read_b128 v[140:143], v144 offset:2048
	ds_read_b128 v[144:147], v144 offset:3072
	ds_read_b128 v[148:151], v160
	ds_read_b128 v[152:155], v160 offset:1024
	ds_read_b128 v[156:159], v160 offset:2048
	ds_read_b128 v[160:163], v160 offset:3072
	s_mov_b32 m0, s54
	v_lshl_add_u64 v[224:225], s[42:43], 0, v[206:207]
	ds_read_b128 v[164:167], v244 offset:32768
	ds_read_b128 v[168:171], v244 offset:33792
	ds_read_b128 v[172:175], v244 offset:34816
	ds_read_b128 v[176:179], v244 offset:35840
	ds_read_b128 v[180:183], v244 offset:36864
	ds_read_b128 v[184:187], v244 offset:37888
	ds_read_b128 v[188:191], v244 offset:38912
	ds_read_b128 v[192:195], v244 offset:39936
	global_load_lds_dwordx4 v[224:225], off
	v_lshl_add_u64 v[224:225], s[42:43], 0, v[210:211]
	s_mov_b32 m0, s55
	s_nop 0
	global_load_lds_dwordx4 v[224:225], off
	s_waitcnt vmcnt(8)
	s_waitcnt lgkmcnt(0)
	s_barrier
	v_mfma_f32_16x16x32_bf16 v[124:127], v[132:135], v[164:167], v[124:127]
	v_mfma_f32_16x16x32_bf16 v[120:123], v[140:143], v[164:167], v[120:123]
	v_mfma_f32_16x16x32_bf16 v[112:115], v[132:135], v[172:175], v[112:115]
	v_mfma_f32_16x16x32_bf16 v[104:107], v[140:143], v[172:175], v[104:107]
	v_mfma_f32_16x16x32_bf16 v[96:99], v[132:135], v[180:183], v[96:99]
	v_mfma_f32_16x16x32_bf16 v[88:91], v[140:143], v[180:183], v[88:91]
	v_mfma_f32_16x16x32_bf16 v[80:83], v[132:135], v[188:191], v[80:83]
	v_mfma_f32_16x16x32_bf16 v[72:75], v[140:143], v[188:191], v[72:75]
	v_mfma_f32_16x16x32_bf16 v[124:127], v[136:139], v[168:171], v[124:127]
	v_mfma_f32_16x16x32_bf16 v[120:123], v[144:147], v[168:171], v[120:123]
	v_mfma_f32_16x16x32_bf16 v[112:115], v[136:139], v[176:179], v[112:115]
	v_mfma_f32_16x16x32_bf16 v[104:107], v[144:147], v[176:179], v[104:107]
	v_mfma_f32_16x16x32_bf16 v[96:99], v[136:139], v[184:187], v[96:99]
	v_mfma_f32_16x16x32_bf16 v[88:91], v[144:147], v[184:187], v[88:91]
	v_mfma_f32_16x16x32_bf16 v[80:83], v[136:139], v[192:195], v[80:83]
	v_mfma_f32_16x16x32_bf16 v[72:75], v[144:147], v[192:195], v[72:75]
	v_mfma_f32_16x16x32_bf16 v[128:131], v[148:151], v[164:167], v[128:131]
	v_mfma_f32_16x16x32_bf16 v[116:119], v[156:159], v[164:167], v[116:119]
	v_mfma_f32_16x16x32_bf16 v[108:111], v[148:151], v[172:175], v[108:111]
	v_mfma_f32_16x16x32_bf16 v[100:103], v[156:159], v[172:175], v[100:103]
	v_mfma_f32_16x16x32_bf16 v[92:95], v[148:151], v[180:183], v[92:95]
	v_mfma_f32_16x16x32_bf16 v[84:87], v[156:159], v[180:183], v[84:87]
	v_mfma_f32_16x16x32_bf16 v[76:79], v[148:151], v[188:191], v[76:79]
	v_mfma_f32_16x16x32_bf16 v[68:71], v[156:159], v[188:191], v[68:71]
	v_mfma_f32_16x16x32_bf16 v[128:131], v[152:155], v[168:171], v[128:131]
	v_mfma_f32_16x16x32_bf16 v[116:119], v[160:163], v[168:171], v[116:119]
	v_mfma_f32_16x16x32_bf16 v[108:111], v[152:155], v[176:179], v[108:111]
	v_mfma_f32_16x16x32_bf16 v[100:103], v[160:163], v[176:179], v[100:103]
	v_mfma_f32_16x16x32_bf16 v[92:95], v[152:155], v[184:187], v[92:95]
	v_mfma_f32_16x16x32_bf16 v[84:87], v[160:163], v[184:187], v[84:87]
	v_mfma_f32_16x16x32_bf16 v[76:79], v[152:155], v[192:195], v[76:79]
	v_mfma_f32_16x16x32_bf16 v[68:71], v[160:163], v[192:195], v[68:71]
	s_barrier
; #define PG8_STAGE(bufoff, gbase, voff) do { _Pragma("unroll") for (int _i = 0; _i < 2; ++_i) \
;         __builtin_amdgcn_global_load_lds((const unsigned*)((const char*)(gbase) + (voff)[_i]), (LAS unsigned*)(lds + (bufoff) + ldsw + _i * 8192), 16, 0, 0); } while (0)
; #define PG8_STAGE_A1(bufoff, gbase) do { if (Epi::GATHER) PG8_STAGE(bufoff, gbase, voffA[1]); else PG8_STAGE(bufoff, (gbase) + hstep, voffA[0]); } while (0)
; #define PG8_LDA(dst, b, h) do { _Pragma("unroll") for (int m = 0; m < 4; ++m) _Pragma("unroll") for (int k = 0; k < 2; ++k) dst[m][k] = *(const LAS bf16x8*)(lds + PG8_SA(b, h) + aoff + m * 2048 + k * 1024); } while (0)
; #define PG8_LDB(dst, b, h) do { _Pragma("unroll") for (int n = 0; n < 2; ++n) _Pragma("unroll") for (int k = 0; k < 2; ++k) dst[n][k] = *(const LAS bf16x8*)(lds + PG8_SB(b, h) + boff + n * 2048 + k * 1024); } while (0)
; #define PG8_MMA(ai, bj, At, Bt) do { __builtin_amdgcn_s_setprio(1); _Pragma("unroll") for (int m = 0; m < 4; ++m) _Pragma("unroll") for (int n = 0; n < 2; ++n) _Pragma("unroll") for (int k = 0; k < 2; ++k) \
;         acc[ai][bj][m][n] = __builtin_amdgcn_mfma_f32_16x16x32_bf16(Bt[n][k], At[m][k], acc[ai][bj][m][n], 0, 0, 0); __builtin_amdgcn_s_setprio(0); } while (0)
; #define PG8_WAIT_V(n) asm volatile("s_waitcnt vmcnt(" #n ")" ::: "memory")
; #define PG8_WAIT_L(n) asm volatile("s_waitcnt lgkmcnt(" #n ")" ::: "memory")
; #define PG8_BAR __builtin_amdgcn_s_barrier()
; #define PG8_SCHED __builtin_amdgcn_sched_barrier(0)
; template <class Epi, class Sched>
; __device__ __forceinline__ void gemm_phase(const int tid, LAS unsigned char* lds, const bf16* Aop, const bf16* Bop, const int K_, const Sched& S, const Epi& E, const bf16* Aop1 = nullptr, const bf16* Bop1 = nullptr) {
;     ...
;             PG8_LDB(B0, 1, 0); PG8_LDB(B1, 1, 1); PG8_SCHED; PG8_LDA(At, 1, 0); PG8_STAGE_A1(PG8_SA(0, 1), a2);
;             PG8_WAIT_V(8); PG8_WAIT_L(0); PG8_BAR; PG8_MMA(0, 0, At, B0); PG8_MMA(0, 1, At, B1); PG8_BAR; PG8_SCHED;
;             PG8_LDA(At, 1, 1); PG8_STAGE(PG8_SB(1, 0), b3, voffB); PG8_STAGE(PG8_SB(1, 1), b3 + hstep, voffB); PG8_STAGE(PG8_SA(1, 0), a3, voffA[0]);
;             PG8_WAIT_V(8); PG8_WAIT_L(0); PG8_BAR; PG8_MMA(1, 0, At, B0); PG8_MMA(1, 1, At, B1); PG8_BAR; PG8_SCHED;
	s_add_i32 s42, s70, s51
	v_lshl_add_u64 v[216:217], v[216:217], 0, s[20:21]
	s_mov_b32 m0, s42
	ds_read_b128 v[164:167], v244 offset:49152
	ds_read_b128 v[168:171], v244 offset:50176
	ds_read_b128 v[172:175], v244 offset:51200
	ds_read_b128 v[176:179], v244 offset:52224
	ds_read_b128 v[180:183], v244 offset:53248
	ds_read_b128 v[184:187], v244 offset:54272
	ds_read_b128 v[188:191], v244 offset:55296
	ds_read_b128 v[192:195], v244 offset:56320
	global_load_lds_dwordx4 v[216:217], off
	v_lshl_add_u64 v[216:217], v[218:219], 0, s[20:21]
	s_add_i32 m0, s42, 0x2000
	s_add_i32 s42, s71, s51
	global_load_lds_dwordx4 v[216:217], off
	v_lshl_add_u64 v[216:217], v[220:221], 0, s[20:21]
	s_mov_b32 m0, s42
	v_lshl_add_u64 v[196:197], v[196:197], 0, s[20:21]
	global_load_lds_dwordx4 v[216:217], off
	v_lshl_add_u64 v[216:217], v[222:223], 0, s[20:21]
	s_add_i32 m0, s42, 0x2000
	s_nop 0
	global_load_lds_dwordx4 v[216:217], off
	s_mov_b32 m0, s56
	s_nop 0
	global_load_lds_dwordx4 v[196:197], off
	v_lshl_add_u64 v[196:197], v[198:199], 0, s[20:21]
	s_mov_b32 m0, s57
	s_nop 0
	global_load_lds_dwordx4 v[196:197], off
	s_waitcnt vmcnt(8)
	s_waitcnt lgkmcnt(0)
	s_barrier
	v_mfma_f32_16x16x32_bf16 v[64:67], v[132:135], v[164:167], v[64:67]
	v_mfma_f32_16x16x32_bf16 v[56:59], v[140:143], v[164:167], v[56:59]
	v_mfma_f32_16x16x32_bf16 v[48:51], v[132:135], v[172:175], v[48:51]
	v_mfma_f32_16x16x32_bf16 v[40:43], v[140:143], v[172:175], v[40:43]
	v_mfma_f32_16x16x32_bf16 v[32:35], v[132:135], v[180:183], v[32:35]
	v_mfma_f32_16x16x32_bf16 v[24:27], v[140:143], v[180:183], v[24:27]
	v_mfma_f32_16x16x32_bf16 v[16:19], v[132:135], v[188:191], v[16:19]
	v_mfma_f32_16x16x32_bf16 v[8:11], v[140:143], v[188:191], v[8:11]
	v_mfma_f32_16x16x32_bf16 v[64:67], v[136:139], v[168:171], v[64:67]
	v_mfma_f32_16x16x32_bf16 v[56:59], v[144:147], v[168:171], v[56:59]
	v_mfma_f32_16x16x32_bf16 v[48:51], v[136:139], v[176:179], v[48:51]
	v_mfma_f32_16x16x32_bf16 v[40:43], v[144:147], v[176:179], v[40:43]
	v_mfma_f32_16x16x32_bf16 v[32:35], v[136:139], v[184:187], v[32:35]
	v_mfma_f32_16x16x32_bf16 v[24:27], v[144:147], v[184:187], v[24:27]
	v_mfma_f32_16x16x32_bf16 v[16:19], v[136:139], v[192:195], v[16:19]
	v_mfma_f32_16x16x32_bf16 v[8:11], v[144:147], v[192:195], v[8:11]
	v_mfma_f32_16x16x32_bf16 v[60:63], v[148:151], v[164:167], v[60:63]
	v_mfma_f32_16x16x32_bf16 v[52:55], v[156:159], v[164:167], v[52:55]
	v_mfma_f32_16x16x32_bf16 v[44:47], v[148:151], v[172:175], v[44:47]
	v_mfma_f32_16x16x32_bf16 v[36:39], v[156:159], v[172:175], v[36:39]
	v_mfma_f32_16x16x32_bf16 v[28:31], v[148:151], v[180:183], v[28:31]
	v_mfma_f32_16x16x32_bf16 v[20:23], v[156:159], v[180:183], v[20:23]
	v_mfma_f32_16x16x32_bf16 v[12:15], v[148:151], v[188:191], v[12:15]
	v_mfma_f32_16x16x32_bf16 v[4:7], v[156:159], v[188:191], v[4:7]
	v_mfma_f32_16x16x32_bf16 v[60:63], v[152:155], v[168:171], v[60:63]
	v_mfma_f32_16x16x32_bf16 v[52:55], v[160:163], v[168:171], v[52:55]
	v_mfma_f32_16x16x32_bf16 v[44:47], v[152:155], v[176:179], v[44:47]
	v_mfma_f32_16x16x32_bf16 v[36:39], v[160:163], v[176:179], v[36:39]
	v_mfma_f32_16x16x32_bf16 v[28:31], v[152:155], v[184:187], v[28:31]
	v_mfma_f32_16x16x32_bf16 v[20:23], v[160:163], v[184:187], v[20:23]
	v_mfma_f32_16x16x32_bf16 v[12:15], v[152:155], v[192:195], v[12:15]
	v_mfma_f32_16x16x32_bf16 v[4:7], v[160:163], v[192:195], v[4:7]
	s_barrier
	s_cmp_ge_i32 s69, s3
	s_cbranch_scc1 .LBB0_1318
; #define PG8_GOFFS(slot_) do { _Pragma("unroll") for (int _i = 0; _i < 2; ++_i) { int R, C; stage_rc(tid * 16 + _i * 8192, R, C); _Pragma("unroll") for (int _h = 0; _h < 2; ++_h) { \
;         unsigned t_ = gtab[(slot_) * 256 + R + 128 * _h]; t_ = t_ < (unsigned)(T - 1) ? t_ : (unsigned)(T - 1); voffA[_h][_i] = (t_ * (unsigned)K + (unsigned)C) * 2u; } } } while (0)
; #define PG8_STAGE(bufoff, gbase, voff) do { _Pragma("unroll") for (int _i = 0; _i < 2; ++_i) \
;         __builtin_amdgcn_global_load_lds((const unsigned*)((const char*)(gbase) + (voff)[_i]), (LAS unsigned*)(lds + (bufoff) + ldsw + _i * 8192), 16, 0, 0); } while (0)
; #define PG8_STAGE_A1(bufoff, gbase) do { if (Epi::GATHER) PG8_STAGE(bufoff, gbase, voffA[1]); else PG8_STAGE(bufoff, (gbase) + hstep, voffA[0]); } while (0)
; #define PG8_LDA(dst, b, h) do { _Pragma("unroll") for (int m = 0; m < 4; ++m) _Pragma("unroll") for (int k = 0; k < 2; ++k) dst[m][k] = *(const LAS bf16x8*)(lds + PG8_SA(b, h) + aoff + m * 2048 + k * 1024); } while (0)
; #define PG8_LDB(dst, b, h) do { _Pragma("unroll") for (int n = 0; n < 2; ++n) _Pragma("unroll") for (int k = 0; k < 2; ++k) dst[n][k] = *(const LAS bf16x8*)(lds + PG8_SB(b, h) + boff + n * 2048 + k * 1024); } while (0)
; #define PG8_WAIT_V(n) asm volatile("s_waitcnt vmcnt(" #n ")" ::: "memory")
; template <class Epi, class Sched>
; __device__ __forceinline__ void gemm_phase(const int tid, LAS unsigned char* lds, const bf16* Aop, const bf16* Bop, const int K_, const Sched& S, const Epi& E, const bf16* Aop1 = nullptr, const bf16* Bop1 = nullptr) {
;     ...
;         for (int t = 0; t < nt; t += 2) {
;             const bool last = (t == nt - 2);
;             const char* a1 = cA + (size_t)(t + 1) * kstep;
;             const char* a2 = last ? nA : cA + (size_t)(t + 2) * kstep; const char* b2 = last ? nB : cB + (size_t)(t + 2) * kstep;
;             const char* a3 = a2 + kstep; const char* b3 = b2 + kstep;
;             PG8_LDB(B0, 0, 0); PG8_LDB(B1, 0, 1); PG8_SCHED; PG8_LDA(At, 0, 0); PG8_STAGE_A1(PG8_SA(1, 1), a1);
;             PG8_WAIT_V(8); PG8_WAIT_L(0); PG8_BAR; PG8_MMA(0, 0, At, B0); PG8_MMA(0, 1, At, B1); PG8_BAR; PG8_SCHED;
;             PG8_LDA(At, 0, 1); PG8_STAGE(PG8_SB(0, 0), b2, voffB); PG8_STAGE(PG8_SB(0, 1), b2 + hstep, voffB); if (Epi::GATHER && last && has_next) PG8_GOFFS((ui + 1) & 1); PG8_STAGE(PG8_SA(0, 0), a2, voffA[0]);
.LBB0_1315:
	s_cmp_eq_u32 s60, s69
	s_cselect_b64 s[42:43], -1, 0
	s_add_u32 s72, s67, s40
	s_addc_u32 s73, s68, s41
	s_add_i32 s74, 0, 0x10000
	s_and_b64 s[70:71], s[42:43], exec
	s_cselect_b32 s71, s29, s73
	s_cselect_b32 s70, s28, s72
	s_add_i32 s75, 0, 0x14000
	v_add_u32_e32 v132, s74, v242
	v_add_u32_e32 v144, s75, v242
	ds_read_b128 v[148:151], v132
	ds_read_b128 v[152:155], v132 offset:1024
	ds_read_b128 v[156:159], v132 offset:2048
	ds_read_b128 v[160:163], v132 offset:3072
	ds_read_b128 v[132:135], v144
	ds_read_b128 v[136:139], v144 offset:1024
	ds_read_b128 v[140:143], v144 offset:2048
	ds_read_b128 v[144:147], v144 offset:3072
	s_add_i32 m0, s52, 0xc000
	s_add_u32 s72, s14, s40
	s_addc_u32 s73, s15, s41
	ds_read_b128 v[164:167], v244
	ds_read_b128 v[168:171], v244 offset:1024
	ds_read_b128 v[172:175], v244 offset:2048
	ds_read_b128 v[176:179], v244 offset:3072
	ds_read_b128 v[180:183], v244 offset:4096
	ds_read_b128 v[184:187], v244 offset:5120
	ds_read_b128 v[188:191], v244 offset:6144
	ds_read_b128 v[192:195], v244 offset:7168
	global_load_lds_dwordx4 v206, s[72:73]
	s_add_i32 m0, s52, 0xe000
	s_nop 0
	global_load_lds_dwordx4 v210, s[72:73]
	s_waitcnt vmcnt(8)
	s_waitcnt lgkmcnt(0)
	s_barrier
	v_mfma_f32_16x16x32_bf16 v[124:127], v[148:151], v[164:167], v[124:127]
	v_mfma_f32_16x16x32_bf16 v[120:123], v[156:159], v[164:167], v[120:123]
	v_mfma_f32_16x16x32_bf16 v[112:115], v[148:151], v[172:175], v[112:115]
	v_mfma_f32_16x16x32_bf16 v[104:107], v[156:159], v[172:175], v[104:107]
	v_mfma_f32_16x16x32_bf16 v[96:99], v[148:151], v[180:183], v[96:99]
	v_mfma_f32_16x16x32_bf16 v[88:91], v[156:159], v[180:183], v[88:91]
	v_mfma_f32_16x16x32_bf16 v[80:83], v[148:151], v[188:191], v[80:83]
	v_mfma_f32_16x16x32_bf16 v[72:75], v[156:159], v[188:191], v[72:75]
	v_mfma_f32_16x16x32_bf16 v[124:127], v[152:155], v[168:171], v[124:127]
	v_mfma_f32_16x16x32_bf16 v[120:123], v[160:163], v[168:171], v[120:123]
	v_mfma_f32_16x16x32_bf16 v[112:115], v[152:155], v[176:179], v[112:115]
	v_mfma_f32_16x16x32_bf16 v[104:107], v[160:163], v[176:179], v[104:107]
	v_mfma_f32_16x16x32_bf16 v[96:99], v[152:155], v[184:187], v[96:99]
	v_mfma_f32_16x16x32_bf16 v[88:91], v[160:163], v[184:187], v[88:91]
	v_mfma_f32_16x16x32_bf16 v[80:83], v[152:155], v[192:195], v[80:83]
	v_mfma_f32_16x16x32_bf16 v[72:75], v[160:163], v[192:195], v[72:75]
	v_mfma_f32_16x16x32_bf16 v[128:131], v[132:135], v[164:167], v[128:131]
	v_mfma_f32_16x16x32_bf16 v[116:119], v[140:143], v[164:167], v[116:119]
	v_mfma_f32_16x16x32_bf16 v[108:111], v[132:135], v[172:175], v[108:111]
	v_mfma_f32_16x16x32_bf16 v[100:103], v[140:143], v[172:175], v[100:103]
	v_mfma_f32_16x16x32_bf16 v[92:95], v[132:135], v[180:183], v[92:95]
	v_mfma_f32_16x16x32_bf16 v[84:87], v[140:143], v[180:183], v[84:87]
	v_mfma_f32_16x16x32_bf16 v[76:79], v[132:135], v[188:191], v[76:79]
	v_mfma_f32_16x16x32_bf16 v[68:71], v[140:143], v[188:191], v[68:71]
	v_mfma_f32_16x16x32_bf16 v[128:131], v[136:139], v[168:171], v[128:131]
	v_mfma_f32_16x16x32_bf16 v[116:119], v[144:147], v[168:171], v[116:119]
	v_mfma_f32_16x16x32_bf16 v[108:111], v[136:139], v[176:179], v[108:111]
	v_mfma_f32_16x16x32_bf16 v[100:103], v[144:147], v[176:179], v[100:103]
	v_mfma_f32_16x16x32_bf16 v[92:95], v[136:139], v[184:187], v[92:95]
	v_mfma_f32_16x16x32_bf16 v[84:87], v[144:147], v[184:187], v[84:87]
	v_mfma_f32_16x16x32_bf16 v[76:79], v[136:139], v[192:195], v[76:79]
	v_mfma_f32_16x16x32_bf16 v[68:71], v[144:147], v[192:195], v[68:71]
	s_barrier
	s_add_i32 s72, s74, s51
	v_lshl_add_u64 v[216:217], s[70:71], 0, v[0:1]
	s_mov_b32 m0, s72
	ds_read_b128 v[188:191], v244 offset:16384
	ds_read_b128 v[192:195], v244 offset:17408
	ds_read_b128 v[180:183], v244 offset:18432
	ds_read_b128 v[184:187], v244 offset:19456
	ds_read_b128 v[172:175], v244 offset:20480
	ds_read_b128 v[176:179], v244 offset:21504
	ds_read_b128 v[164:167], v244 offset:22528
	ds_read_b128 v[168:171], v244 offset:23552
	global_load_lds_dwordx4 v[216:217], off
	s_add_i32 m0, s72, 0x2000
	v_lshl_add_u64 v[218:219], s[70:71], 0, v[202:203]
	s_add_u32 s70, s70, s6
	s_addc_u32 s71, s71, s7
	s_add_i32 s72, s75, s51
	global_load_lds_dwordx4 v[218:219], off
	v_lshl_add_u64 v[220:221], s[70:71], 0, v[0:1]
	s_mov_b32 m0, s72
	v_lshl_add_u64 v[222:223], s[70:71], 0, v[202:203]
	global_load_lds_dwordx4 v[220:221], off
	s_add_i32 m0, s72, 0x2000
	s_and_b64 s[70:71], s[36:37], s[42:43]
	global_load_lds_dwordx4 v[222:223], off
	s_andn2_b64 vcc, exec, s[70:71]
	s_cbranch_vccnz .LBB0_1314
	ds_read_b32 v196, v245
	ds_read_b32 v197, v245 offset:512
	ds_read_b32 v198, v246
	s_waitcnt lgkmcnt(0)
	v_min_u32_e32 v196, 0x41ff, v196
	v_mul_lo_u32 v196, v196, s2
	v_add_lshl_u32 v204, v196, v3, 1
	ds_read_b32 v196, v246 offset:512
	v_min_u32_e32 v197, 0x41ff, v197
	v_mul_lo_u32 v197, v197, s2
	v_add_lshl_u32 v206, v197, v3, 1
	v_min_u32_e32 v197, 0x41ff, v198
	s_waitcnt lgkmcnt(0)
	v_min_u32_e32 v196, 0x41ff, v196
	v_mul_lo_u32 v197, v197, s2
	v_mul_lo_u32 v196, v196, s2
	v_add_lshl_u32 v208, v197, v200, 1
	v_add_lshl_u32 v210, v196, v200, 1
	s_branch .LBB0_1314

; #define PG8_GOFFS(slot_) do { _Pragma("unroll") for (int _i = 0; _i < 2; ++_i) { int R, C; stage_rc(tid * 16 + _i * 8192, R, C); _Pragma("unroll") for (int _h = 0; _h < 2; ++_h) { \
;         unsigned t_ = gtab[(slot_) * 256 + R + 128 * _h]; t_ = t_ < (unsigned)(T - 1) ? t_ : (unsigned)(T - 1); voffA[_h][_i] = (t_ * (unsigned)K + (unsigned)C) * 2u; } } } while (0)
; #define PG8_STAGE(bufoff, gbase, voff) do { _Pragma("unroll") for (int _i = 0; _i < 2; ++_i) \
;         __builtin_amdgcn_global_load_lds((const unsigned*)((const char*)(gbase) + (voff)[_i]), (LAS unsigned*)(lds + (bufoff) + ldsw + _i * 8192), 16, 0, 0); } while (0)
; #define PG8_STAGE_A1(bufoff, gbase) do { if (Epi::GATHER) PG8_STAGE(bufoff, gbase, voffA[1]); else PG8_STAGE(bufoff, (gbase) + hstep, voffA[0]); } while (0)
; #define PG8_LDA(dst, b, h) do { _Pragma("unroll") for (int m = 0; m < 4; ++m) _Pragma("unroll") for (int k = 0; k < 2; ++k) dst[m][k] = *(const LAS bf16x8*)(lds + PG8_SA(b, h) + aoff + m * 2048 + k * 1024); } while (0)
; #define PG8_WAIT_V(n) asm volatile("s_waitcnt vmcnt(" #n ")" ::: "memory")
; #define PG8_WAIT_L(n) asm volatile("s_waitcnt lgkmcnt(" #n ")" ::: "memory")
; #define PG8_BAR __builtin_amdgcn_s_barrier()
; template <class Epi, class Sched>
; __device__ __forceinline__ void gemm_phase(const int tid, LAS unsigned char* lds, const bf16* Aop, const bf16* Bop, const int K_, const Sched& S, const Epi& E, const bf16* Aop1 = nullptr, const bf16* Bop1 = nullptr) {
;     ...
;         for (int t = 0; t < nt; t += 2) {
;             const bool last = (t == nt - 2);
;             const char* a1 = cA + (size_t)(t + 1) * kstep;
;             const char* a2 = last ? nA : cA + (size_t)(t + 2) * kstep; const char* b2 = last ? nB : cB + (size_t)(t + 2) * kstep;
;             const char* a3 = a2 + kstep; const char* b3 = b2 + kstep;
;             PG8_LDB(B0, 0, 0); PG8_LDB(B1, 0, 1); PG8_SCHED; PG8_LDA(At, 0, 0); PG8_STAGE_A1(PG8_SA(1, 1), a1);
;             PG8_WAIT_V(8); PG8_WAIT_L(0); PG8_BAR; PG8_MMA(0, 0, At, B0); PG8_MMA(0, 1, At, B1); PG8_BAR; PG8_SCHED;
;             PG8_LDA(At, 0, 1); PG8_STAGE(PG8_SB(0, 0), b2, voffB); PG8_STAGE(PG8_SB(0, 1), b2 + hstep, voffB); if (Epi::GATHER && last && has_next) PG8_GOFFS((ui + 1) & 1); PG8_STAGE(PG8_SA(0, 0), a2, voffA[0]);
;             PG8_WAIT_V(8); PG8_WAIT_L(0); PG8_BAR; PG8_MMA(1, 0, At, B0); PG8_MMA(1, 1, At, B1); PG8_BAR; PG8_SCHED;
.LBB0_1398:
	v_mov_b32_e32 v127, 0
	s_andn2_b64 vcc, exec, s[16:17]
	s_cbranch_vccnz .LBB0_1401
	s_add_u32 s34, s34, 0x80
	s_addc_u32 s35, s35, 0
	s_add_u32 s65, s36, 0x100
	s_addc_u32 s66, s37, 0
	s_mov_b32 s36, 0
	s_add_i32 s67, s36, 2
	s_add_u32 s68, s34, 0x80
	s_addc_u32 s37, s35, 0
	s_add_i32 s70, 0, 0x10000
	s_cmp_eq_u32 s58, s36
	s_cselect_b32 s37, s27, s37
	s_cselect_b32 s36, s26, s68
	v_add_u32_e32 v147, s70, v144
	s_cselect_b32 s69, s29, s66
	s_cselect_b32 s68, s28, s65
	s_add_i32 s71, 0, 0x14000
	ds_read_b128 v[148:151], v147
	ds_read_b128 v[152:155], v147 offset:1024
	ds_read_b128 v[156:159], v147 offset:2048
	ds_read_b128 v[160:163], v147 offset:3072
	v_add_u32_e32 v147, s71, v144
	ds_read_b128 v[164:167], v147
	ds_read_b128 v[168:171], v147 offset:1024
	ds_read_b128 v[172:175], v147 offset:2048
	ds_read_b128 v[176:179], v147 offset:3072
	v_lshl_add_u64 v[196:197], s[34:35], 0, v[140:141]
	s_add_i32 m0, s51, 0xc000
	ds_read_b128 v[180:183], v146
	ds_read_b128 v[184:187], v146 offset:1024
	ds_read_b128 v[188:191], v146 offset:2048
	ds_read_b128 v[192:195], v146 offset:3072
	ds_read_b128 v[202:205], v146 offset:4096
	ds_read_b128 v[206:209], v146 offset:5120
	ds_read_b128 v[210:213], v146 offset:6144
	ds_read_b128 v[214:217], v146 offset:7168
	global_load_lds_dwordx4 v[196:197], off
	v_lshl_add_u64 v[196:197], s[34:35], 0, v[142:143]
	s_add_i32 m0, s51, 0xe000
	s_nop 0
	global_load_lds_dwordx4 v[196:197], off
	s_waitcnt vmcnt(8)
	s_waitcnt lgkmcnt(0)
	s_barrier
	v_mfma_f32_16x16x32_bf16 v[124:127], v[148:151], v[180:183], 0
	v_mfma_f32_16x16x32_bf16 v[128:131], v[156:159], v[180:183], 0
	v_mfma_f32_16x16x32_bf16 v[112:115], v[148:151], v[188:191], 0
	v_mfma_f32_16x16x32_bf16 v[108:111], v[156:159], v[188:191], 0
	v_mfma_f32_16x16x32_bf16 v[96:99], v[148:151], v[202:205], 0
	v_mfma_f32_16x16x32_bf16 v[92:95], v[156:159], v[202:205], 0
	v_mfma_f32_16x16x32_bf16 v[80:83], v[148:151], v[210:213], 0
	v_mfma_f32_16x16x32_bf16 v[76:79], v[156:159], v[210:213], 0
	v_mfma_f32_16x16x32_bf16 v[124:127], v[152:155], v[184:187], v[124:127]
	v_mfma_f32_16x16x32_bf16 v[128:131], v[160:163], v[184:187], v[128:131]
	v_mfma_f32_16x16x32_bf16 v[112:115], v[152:155], v[192:195], v[112:115]
	v_mfma_f32_16x16x32_bf16 v[108:111], v[160:163], v[192:195], v[108:111]
	v_mfma_f32_16x16x32_bf16 v[96:99], v[152:155], v[206:209], v[96:99]
	v_mfma_f32_16x16x32_bf16 v[92:95], v[160:163], v[206:209], v[92:95]
	v_mfma_f32_16x16x32_bf16 v[80:83], v[152:155], v[214:217], v[80:83]
	v_mfma_f32_16x16x32_bf16 v[76:79], v[160:163], v[214:217], v[76:79]
	v_mfma_f32_16x16x32_bf16 v[120:123], v[164:167], v[180:183], 0
	v_mfma_f32_16x16x32_bf16 v[116:119], v[172:175], v[180:183], 0
	v_mfma_f32_16x16x32_bf16 v[104:107], v[164:167], v[188:191], 0
	v_mfma_f32_16x16x32_bf16 v[100:103], v[172:175], v[188:191], 0
	v_mfma_f32_16x16x32_bf16 v[88:91], v[164:167], v[202:205], 0
	v_mfma_f32_16x16x32_bf16 v[84:87], v[172:175], v[202:205], 0
	v_mfma_f32_16x16x32_bf16 v[72:75], v[164:167], v[210:213], 0
	v_mfma_f32_16x16x32_bf16 v[68:71], v[172:175], v[210:213], 0
	v_mfma_f32_16x16x32_bf16 v[120:123], v[168:171], v[184:187], v[120:123]
	v_mfma_f32_16x16x32_bf16 v[116:119], v[176:179], v[184:187], v[116:119]
	v_mfma_f32_16x16x32_bf16 v[104:107], v[168:171], v[192:195], v[104:107]
	v_mfma_f32_16x16x32_bf16 v[100:103], v[176:179], v[192:195], v[100:103]
	v_mfma_f32_16x16x32_bf16 v[88:91], v[168:171], v[206:209], v[88:91]
	v_mfma_f32_16x16x32_bf16 v[84:87], v[176:179], v[206:209], v[84:87]
	v_mfma_f32_16x16x32_bf16 v[72:75], v[168:171], v[214:217], v[72:75]
	v_mfma_f32_16x16x32_bf16 v[68:71], v[176:179], v[214:217], v[68:71]
	s_barrier
	s_add_i32 s70, s70, s50
	v_lshl_add_u64 v[196:197], s[68:69], 0, v[134:135]
	s_mov_b32 m0, s70
	ds_read_b128 v[180:183], v146 offset:16384
	ds_read_b128 v[184:187], v146 offset:17408
	ds_read_b128 v[188:191], v146 offset:18432
	ds_read_b128 v[192:195], v146 offset:19456
	ds_read_b128 v[202:205], v146 offset:20480
	ds_read_b128 v[206:209], v146 offset:21504
	ds_read_b128 v[210:213], v146 offset:22528
	ds_read_b128 v[214:217], v146 offset:23552
	global_load_lds_dwordx4 v[196:197], off
	s_add_i32 m0, s70, 0x2000
	v_lshl_add_u64 v[198:199], s[68:69], 0, v[0:1]
	s_add_u32 s68, s68, s6
	s_addc_u32 s69, s69, s7
	s_add_i32 s70, s71, s50
	global_load_lds_dwordx4 v[198:199], off
	v_lshl_add_u64 v[218:219], s[68:69], 0, v[134:135]
	s_mov_b32 m0, s70
	v_lshl_add_u64 v[220:221], s[68:69], 0, v[0:1]
	global_load_lds_dwordx4 v[218:219], off
	s_add_i32 m0, s70, 0x2000
	v_lshl_add_u64 v[222:223], s[36:37], 0, v[136:137]
	global_load_lds_dwordx4 v[220:221], off
	s_mov_b32 m0, s51
	v_lshl_add_u64 v[224:225], s[36:37], 0, v[132:133]
	global_load_lds_dwordx4 v[222:223], off
	s_mov_b32 m0, s52
	s_nop 0
	global_load_lds_dwordx4 v[224:225], off
	s_waitcnt vmcnt(8)
	s_waitcnt lgkmcnt(0)
	s_barrier
; #define PG8_STAGE(bufoff, gbase, voff) do { _Pragma("unroll") for (int _i = 0; _i < 2; ++_i) \
;         __builtin_amdgcn_global_load_lds((const unsigned*)((const char*)(gbase) + (voff)[_i]), (LAS unsigned*)(lds + (bufoff) + ldsw + _i * 8192), 16, 0, 0); } while (0)
; #define PG8_STAGE_A1(bufoff, gbase) do { if (Epi::GATHER) PG8_STAGE(bufoff, gbase, voffA[1]); else PG8_STAGE(bufoff, (gbase) + hstep, voffA[0]); } while (0)
; #define PG8_LDA(dst, b, h) do { _Pragma("unroll") for (int m = 0; m < 4; ++m) _Pragma("unroll") for (int k = 0; k < 2; ++k) dst[m][k] = *(const LAS bf16x8*)(lds + PG8_SA(b, h) + aoff + m * 2048 + k * 1024); } while (0)
; #define PG8_LDB(dst, b, h) do { _Pragma("unroll") for (int n = 0; n < 2; ++n) _Pragma("unroll") for (int k = 0; k < 2; ++k) dst[n][k] = *(const LAS bf16x8*)(lds + PG8_SB(b, h) + boff + n * 2048 + k * 1024); } while (0)
; #define PG8_MMA(ai, bj, At, Bt) do { __builtin_amdgcn_s_setprio(1); _Pragma("unroll") for (int m = 0; m < 4; ++m) _Pragma("unroll") for (int n = 0; n < 2; ++n) _Pragma("unroll") for (int k = 0; k < 2; ++k) \
;         acc[ai][bj][m][n] = __builtin_amdgcn_mfma_f32_16x16x32_bf16(Bt[n][k], At[m][k], acc[ai][bj][m][n], 0, 0, 0); __builtin_amdgcn_s_setprio(0); } while (0)
; #define PG8_WAIT_V(n) asm volatile("s_waitcnt vmcnt(" #n ")" ::: "memory")
; #define PG8_WAIT_L(n) asm volatile("s_waitcnt lgkmcnt(" #n ")" ::: "memory")
; #define PG8_BAR __builtin_amdgcn_s_barrier()
; #define PG8_SCHED __builtin_amdgcn_sched_barrier(0)
; template <class Epi, class Sched>
; __device__ __forceinline__ void gemm_phase(const int tid, LAS unsigned char* lds, const bf16* Aop, const bf16* Bop, const int K_, const Sched& S, const Epi& E, const bf16* Aop1 = nullptr, const bf16* Bop1 = nullptr) {
;     ...
;             PG8_WAIT_V(8); PG8_WAIT_L(0); PG8_BAR; PG8_MMA(1, 0, At, B0); PG8_MMA(1, 1, At, B1); PG8_BAR; PG8_SCHED;
;             PG8_LDB(B0, 1, 0); PG8_LDB(B1, 1, 1); PG8_SCHED; PG8_LDA(At, 1, 0); PG8_STAGE_A1(PG8_SA(0, 1), a2);
;             PG8_WAIT_V(8); PG8_WAIT_L(0); PG8_BAR; PG8_MMA(0, 0, At, B0); PG8_MMA(0, 1, At, B1); PG8_BAR; PG8_SCHED;
;             PG8_LDA(At, 1, 1); PG8_STAGE(PG8_SB(1, 0), b3, voffB); PG8_STAGE(PG8_SB(1, 1), b3 + hstep, voffB); PG8_STAGE(PG8_SA(1, 0), a3, voffA[0]);
;             PG8_WAIT_V(8); PG8_WAIT_L(0); PG8_BAR; PG8_MMA(1, 0, At, B0); PG8_MMA(1, 1, At, B1); PG8_BAR; PG8_SCHED;
	v_mfma_f32_16x16x32_bf16 v[64:67], v[148:151], v[180:183], 0
	v_mfma_f32_16x16x32_bf16 v[60:63], v[156:159], v[180:183], 0
	v_mfma_f32_16x16x32_bf16 v[48:51], v[148:151], v[188:191], 0
	v_mfma_f32_16x16x32_bf16 v[44:47], v[156:159], v[188:191], 0
	v_mfma_f32_16x16x32_bf16 v[32:35], v[148:151], v[202:205], 0
	v_mfma_f32_16x16x32_bf16 v[28:31], v[156:159], v[202:205], 0
	v_mfma_f32_16x16x32_bf16 v[16:19], v[148:151], v[210:213], 0
	v_mfma_f32_16x16x32_bf16 v[12:15], v[156:159], v[210:213], 0
	v_mfma_f32_16x16x32_bf16 v[64:67], v[152:155], v[184:187], v[64:67]
	v_mfma_f32_16x16x32_bf16 v[60:63], v[160:163], v[184:187], v[60:63]
	v_mfma_f32_16x16x32_bf16 v[48:51], v[152:155], v[192:195], v[48:51]
	v_mfma_f32_16x16x32_bf16 v[44:47], v[160:163], v[192:195], v[44:47]
	v_mfma_f32_16x16x32_bf16 v[32:35], v[152:155], v[206:209], v[32:35]
	v_mfma_f32_16x16x32_bf16 v[28:31], v[160:163], v[206:209], v[28:31]
	v_mfma_f32_16x16x32_bf16 v[16:19], v[152:155], v[214:217], v[16:19]
	v_mfma_f32_16x16x32_bf16 v[12:15], v[160:163], v[214:217], v[12:15]
	v_mfma_f32_16x16x32_bf16 v[56:59], v[164:167], v[180:183], 0
	v_mfma_f32_16x16x32_bf16 v[52:55], v[172:175], v[180:183], 0
	v_mfma_f32_16x16x32_bf16 v[40:43], v[164:167], v[188:191], 0
	v_mfma_f32_16x16x32_bf16 v[36:39], v[172:175], v[188:191], 0
	v_mfma_f32_16x16x32_bf16 v[24:27], v[164:167], v[202:205], 0
	v_mfma_f32_16x16x32_bf16 v[20:23], v[172:175], v[202:205], 0
	v_mfma_f32_16x16x32_bf16 v[8:11], v[164:167], v[210:213], 0
	v_mfma_f32_16x16x32_bf16 v[4:7], v[172:175], v[210:213], 0
	v_mfma_f32_16x16x32_bf16 v[56:59], v[168:171], v[184:187], v[56:59]
	v_mfma_f32_16x16x32_bf16 v[52:55], v[176:179], v[184:187], v[52:55]
	v_mfma_f32_16x16x32_bf16 v[40:43], v[168:171], v[192:195], v[40:43]
	v_mfma_f32_16x16x32_bf16 v[36:39], v[176:179], v[192:195], v[36:39]
	v_mfma_f32_16x16x32_bf16 v[24:27], v[168:171], v[206:209], v[24:27]
	v_mfma_f32_16x16x32_bf16 v[20:23], v[176:179], v[206:209], v[20:23]
	v_mfma_f32_16x16x32_bf16 v[8:11], v[168:171], v[214:217], v[8:11]
	v_mfma_f32_16x16x32_bf16 v[4:7], v[176:179], v[214:217], v[4:7]
	s_barrier
	s_add_i32 s68, 0, 0x18000
	v_add_u32_e32 v147, s68, v144
	s_add_i32 s69, 0, 0x1c000
	ds_read_b128 v[148:151], v147
	ds_read_b128 v[152:155], v147 offset:1024
	ds_read_b128 v[156:159], v147 offset:2048
	ds_read_b128 v[160:163], v147 offset:3072
	v_add_u32_e32 v147, s69, v144
	ds_read_b128 v[164:167], v147
	ds_read_b128 v[168:171], v147 offset:1024
	ds_read_b128 v[172:175], v147 offset:2048
	ds_read_b128 v[176:179], v147 offset:3072
	s_add_u32 s36, s36, s6
	s_addc_u32 s37, s37, s7
	s_mov_b32 m0, s53
	v_lshl_add_u64 v[230:231], s[36:37], 0, v[136:137]
	ds_read_b128 v[180:183], v146 offset:32768
	ds_read_b128 v[184:187], v146 offset:33792
	ds_read_b128 v[188:191], v146 offset:34816
	ds_read_b128 v[192:195], v146 offset:35840
	ds_read_b128 v[202:205], v146 offset:36864
	ds_read_b128 v[206:209], v146 offset:37888
	ds_read_b128 v[210:213], v146 offset:38912
	ds_read_b128 v[214:217], v146 offset:39936
	global_load_lds_dwordx4 v[230:231], off
	v_lshl_add_u64 v[230:231], s[36:37], 0, v[132:133]
	s_mov_b32 m0, s54
	s_nop 0
	global_load_lds_dwordx4 v[230:231], off
	s_waitcnt vmcnt(8)
	s_waitcnt lgkmcnt(0)
	s_barrier
	v_mfma_f32_16x16x32_bf16 v[124:127], v[148:151], v[180:183], v[124:127]
	v_mfma_f32_16x16x32_bf16 v[128:131], v[156:159], v[180:183], v[128:131]
	v_mfma_f32_16x16x32_bf16 v[112:115], v[148:151], v[188:191], v[112:115]
	v_mfma_f32_16x16x32_bf16 v[108:111], v[156:159], v[188:191], v[108:111]
	v_mfma_f32_16x16x32_bf16 v[96:99], v[148:151], v[202:205], v[96:99]
	v_mfma_f32_16x16x32_bf16 v[92:95], v[156:159], v[202:205], v[92:95]
	v_mfma_f32_16x16x32_bf16 v[80:83], v[148:151], v[210:213], v[80:83]
	v_mfma_f32_16x16x32_bf16 v[76:79], v[156:159], v[210:213], v[76:79]
	v_mfma_f32_16x16x32_bf16 v[124:127], v[152:155], v[184:187], v[124:127]
	v_mfma_f32_16x16x32_bf16 v[128:131], v[160:163], v[184:187], v[128:131]
	v_mfma_f32_16x16x32_bf16 v[112:115], v[152:155], v[192:195], v[112:115]
	v_mfma_f32_16x16x32_bf16 v[108:111], v[160:163], v[192:195], v[108:111]
	v_mfma_f32_16x16x32_bf16 v[96:99], v[152:155], v[206:209], v[96:99]
	v_mfma_f32_16x16x32_bf16 v[92:95], v[160:163], v[206:209], v[92:95]
	v_mfma_f32_16x16x32_bf16 v[80:83], v[152:155], v[214:217], v[80:83]
	v_mfma_f32_16x16x32_bf16 v[76:79], v[160:163], v[214:217], v[76:79]
	v_mfma_f32_16x16x32_bf16 v[120:123], v[164:167], v[180:183], v[120:123]
	v_mfma_f32_16x16x32_bf16 v[116:119], v[172:175], v[180:183], v[116:119]
	v_mfma_f32_16x16x32_bf16 v[104:107], v[164:167], v[188:191], v[104:107]
	v_mfma_f32_16x16x32_bf16 v[100:103], v[172:175], v[188:191], v[100:103]
	v_mfma_f32_16x16x32_bf16 v[88:91], v[164:167], v[202:205], v[88:91]
	v_mfma_f32_16x16x32_bf16 v[84:87], v[172:175], v[202:205], v[84:87]
	v_mfma_f32_16x16x32_bf16 v[72:75], v[164:167], v[210:213], v[72:75]
	v_mfma_f32_16x16x32_bf16 v[68:71], v[172:175], v[210:213], v[68:71]
	v_mfma_f32_16x16x32_bf16 v[120:123], v[168:171], v[184:187], v[120:123]
	v_mfma_f32_16x16x32_bf16 v[116:119], v[176:179], v[184:187], v[116:119]
	v_mfma_f32_16x16x32_bf16 v[104:107], v[168:171], v[192:195], v[104:107]
	v_mfma_f32_16x16x32_bf16 v[100:103], v[176:179], v[192:195], v[100:103]
	v_mfma_f32_16x16x32_bf16 v[88:91], v[168:171], v[206:209], v[88:91]
	v_mfma_f32_16x16x32_bf16 v[84:87], v[176:179], v[206:209], v[84:87]
	v_mfma_f32_16x16x32_bf16 v[72:75], v[168:171], v[214:217], v[72:75]
	v_mfma_f32_16x16x32_bf16 v[68:71], v[176:179], v[214:217], v[68:71]
	s_barrier
; #define PG8_GOFFS(slot_) do { _Pragma("unroll") for (int _i = 0; _i < 2; ++_i) { int R, C; stage_rc(tid * 16 + _i * 8192, R, C); _Pragma("unroll") for (int _h = 0; _h < 2; ++_h) { \
;         unsigned t_ = gtab[(slot_) * 256 + R + 128 * _h]; t_ = t_ < (unsigned)(T - 1) ? t_ : (unsigned)(T - 1); voffA[_h][_i] = (t_ * (unsigned)K + (unsigned)C) * 2u; } } } while (0)
; #define PG8_STAGE(bufoff, gbase, voff) do { _Pragma("unroll") for (int _i = 0; _i < 2; ++_i) \
;         __builtin_amdgcn_global_load_lds((const unsigned*)((const char*)(gbase) + (voff)[_i]), (LAS unsigned*)(lds + (bufoff) + ldsw + _i * 8192), 16, 0, 0); } while (0)
; #define PG8_BAR __builtin_amdgcn_s_barrier()
; template <class Epi, class Sched>
; __device__ __forceinline__ void gemm_phase(const int tid, LAS unsigned char* lds, const bf16* Aop, const bf16* Bop, const int K_, const Sched& S, const Epi& E, const bf16* Aop1 = nullptr, const bf16* Bop1 = nullptr) {
;     ...
;         for (int t = 0; t < nt; t += 2) {
;             const bool last = (t == nt - 2);
;             const char* a1 = cA + (size_t)(t + 1) * kstep;
;             const char* a2 = last ? nA : cA + (size_t)(t + 2) * kstep; const char* b2 = last ? nB : cB + (size_t)(t + 2) * kstep;
;             const char* a3 = a2 + kstep; const char* b3 = b2 + kstep;
;             PG8_LDB(B0, 0, 0); PG8_LDB(B1, 0, 1); PG8_SCHED; PG8_LDA(At, 0, 0); PG8_STAGE_A1(PG8_SA(1, 1), a1);
;             PG8_WAIT_V(8); PG8_WAIT_L(0); PG8_BAR; PG8_MMA(0, 0, At, B0); PG8_MMA(0, 1, At, B1); PG8_BAR; PG8_SCHED;
;             PG8_LDA(At, 0, 1); PG8_STAGE(PG8_SB(0, 0), b2, voffB); PG8_STAGE(PG8_SB(0, 1), b2 + hstep, voffB); if (Epi::GATHER && last && has_next) PG8_GOFFS((ui + 1) & 1); PG8_STAGE(PG8_SA(0, 0), a2, voffA[0]);
;             PG8_WAIT_V(8); PG8_WAIT_L(0); PG8_BAR; PG8_MMA(1, 0, At, B0); PG8_MMA(1, 1, At, B1); PG8_BAR; PG8_SCHED;
;             PG8_LDB(B0, 1, 0); PG8_LDB(B1, 1, 1); PG8_SCHED; PG8_LDA(At, 1, 0); PG8_STAGE_A1(PG8_SA(0, 1), a2);
;             PG8_WAIT_V(8); PG8_WAIT_L(0); PG8_BAR; PG8_MMA(0, 0, At, B0); PG8_MMA(0, 1, At, B1); PG8_BAR; PG8_SCHED;
;             PG8_LDA(At, 1, 1); PG8_STAGE(PG8_SB(1, 0), b3, voffB); PG8_STAGE(PG8_SB(1, 1), b3 + hstep, voffB); PG8_STAGE(PG8_SA(1, 0), a3, voffA[0]);
;             PG8_WAIT_V(8); PG8_WAIT_L(0); PG8_BAR; PG8_MMA(1, 0, At, B0); PG8_MMA(1, 1, At, B1); PG8_BAR; PG8_SCHED;
;         }
	s_add_i32 s36, s68, s50
	v_lshl_add_u64 v[196:197], v[196:197], 0, s[20:21]
	s_mov_b32 m0, s36
	ds_read_b128 v[180:183], v146 offset:49152
	ds_read_b128 v[184:187], v146 offset:50176
	ds_read_b128 v[188:191], v146 offset:51200
	ds_read_b128 v[192:195], v146 offset:52224
	ds_read_b128 v[202:205], v146 offset:53248
	ds_read_b128 v[206:209], v146 offset:54272
	ds_read_b128 v[210:213], v146 offset:55296
	ds_read_b128 v[214:217], v146 offset:56320
	global_load_lds_dwordx4 v[196:197], off
	v_lshl_add_u64 v[196:197], v[198:199], 0, s[20:21]
	s_add_i32 m0, s36, 0x2000
	s_add_i32 s36, s69, s50
	global_load_lds_dwordx4 v[196:197], off
	v_lshl_add_u64 v[196:197], v[218:219], 0, s[20:21]
	s_mov_b32 m0, s36
	s_nop 0
	global_load_lds_dwordx4 v[196:197], off
	v_lshl_add_u64 v[196:197], v[220:221], 0, s[20:21]
	s_add_i32 m0, s36, 0x2000
	s_nop 0
	global_load_lds_dwordx4 v[196:197], off
	v_lshl_add_u64 v[196:197], v[222:223], 0, s[20:21]
	s_mov_b32 m0, s56
	s_nop 0
	global_load_lds_dwordx4 v[196:197], off
	v_lshl_add_u64 v[196:197], v[224:225], 0, s[20:21]
	s_mov_b32 m0, s57
	s_nop 0
	global_load_lds_dwordx4 v[196:197], off
	s_waitcnt vmcnt(8)
	s_waitcnt lgkmcnt(0)
	s_barrier
	v_mfma_f32_16x16x32_bf16 v[64:67], v[148:151], v[180:183], v[64:67]
	v_mfma_f32_16x16x32_bf16 v[60:63], v[156:159], v[180:183], v[60:63]
	v_mfma_f32_16x16x32_bf16 v[48:51], v[148:151], v[188:191], v[48:51]
	v_mfma_f32_16x16x32_bf16 v[44:47], v[156:159], v[188:191], v[44:47]
	v_mfma_f32_16x16x32_bf16 v[32:35], v[148:151], v[202:205], v[32:35]
	v_mfma_f32_16x16x32_bf16 v[28:31], v[156:159], v[202:205], v[28:31]
	v_mfma_f32_16x16x32_bf16 v[16:19], v[148:151], v[210:213], v[16:19]
	v_mfma_f32_16x16x32_bf16 v[12:15], v[156:159], v[210:213], v[12:15]
	v_mfma_f32_16x16x32_bf16 v[64:67], v[152:155], v[184:187], v[64:67]
	v_mfma_f32_16x16x32_bf16 v[60:63], v[160:163], v[184:187], v[60:63]
	v_mfma_f32_16x16x32_bf16 v[48:51], v[152:155], v[192:195], v[48:51]
	v_mfma_f32_16x16x32_bf16 v[44:47], v[160:163], v[192:195], v[44:47]
	v_mfma_f32_16x16x32_bf16 v[32:35], v[152:155], v[206:209], v[32:35]
	v_mfma_f32_16x16x32_bf16 v[28:31], v[160:163], v[206:209], v[28:31]
	v_mfma_f32_16x16x32_bf16 v[16:19], v[152:155], v[214:217], v[16:19]
	v_mfma_f32_16x16x32_bf16 v[12:15], v[160:163], v[214:217], v[12:15]
	v_mfma_f32_16x16x32_bf16 v[56:59], v[164:167], v[180:183], v[56:59]
	v_mfma_f32_16x16x32_bf16 v[52:55], v[172:175], v[180:183], v[52:55]
	v_mfma_f32_16x16x32_bf16 v[40:43], v[164:167], v[188:191], v[40:43]
	v_mfma_f32_16x16x32_bf16 v[36:39], v[172:175], v[188:191], v[36:39]
	v_mfma_f32_16x16x32_bf16 v[24:27], v[164:167], v[202:205], v[24:27]
	v_mfma_f32_16x16x32_bf16 v[20:23], v[172:175], v[202:205], v[20:23]
	v_mfma_f32_16x16x32_bf16 v[8:11], v[164:167], v[210:213], v[8:11]
	v_mfma_f32_16x16x32_bf16 v[4:7], v[172:175], v[210:213], v[4:7]
	v_mfma_f32_16x16x32_bf16 v[56:59], v[168:171], v[184:187], v[56:59]
	v_mfma_f32_16x16x32_bf16 v[52:55], v[176:179], v[184:187], v[52:55]
	v_mfma_f32_16x16x32_bf16 v[40:43], v[168:171], v[192:195], v[40:43]
	v_mfma_f32_16x16x32_bf16 v[36:39], v[176:179], v[192:195], v[36:39]
	v_mfma_f32_16x16x32_bf16 v[24:27], v[168:171], v[206:209], v[24:27]
	v_mfma_f32_16x16x32_bf16 v[20:23], v[176:179], v[206:209], v[20:23]
	v_mfma_f32_16x16x32_bf16 v[8:11], v[168:171], v[214:217], v[8:11]
	v_mfma_f32_16x16x32_bf16 v[4:7], v[176:179], v[214:217], v[4:7]
	s_barrier
	s_add_u32 s34, s34, 0x100
	s_addc_u32 s35, s35, 0
	s_add_u32 s65, s65, 0x100
	s_addc_u32 s66, s66, 0
	s_cmp_ge_i32 s67, s55
	s_mov_b32 s36, s67
	s_cbranch_scc0 .LBB0_1400
	s_branch .LBB0_1401
.LBB0_1400:
	s_add_i32 s67, s36, 2
	s_add_u32 s68, s34, 0x80
	s_addc_u32 s37, s35, 0
	s_add_i32 s70, 0, 0x10000
	s_cmp_eq_u32 s58, s36
	s_cselect_b32 s37, s27, s37
	s_cselect_b32 s36, s26, s68
	v_add_u32_e32 v147, s70, v144
	s_cselect_b32 s69, s29, s66
	s_cselect_b32 s68, s28, s65
	s_add_i32 s71, 0, 0x14000
	ds_read_b128 v[148:151], v147
	ds_read_b128 v[152:155], v147 offset:1024
	ds_read_b128 v[156:159], v147 offset:2048
	ds_read_b128 v[160:163], v147 offset:3072
	v_add_u32_e32 v147, s71, v144
	ds_read_b128 v[164:167], v147
	ds_read_b128 v[168:171], v147 offset:1024
	ds_read_b128 v[172:175], v147 offset:2048
	ds_read_b128 v[176:179], v147 offset:3072
	v_lshl_add_u64 v[196:197], s[34:35], 0, v[140:141]
	s_add_i32 m0, s51, 0xc000
	ds_read_b128 v[180:183], v146
	ds_read_b128 v[184:187], v146 offset:1024
	ds_read_b128 v[188:191], v146 offset:2048
	ds_read_b128 v[192:195], v146 offset:3072
	ds_read_b128 v[202:205], v146 offset:4096
	ds_read_b128 v[206:209], v146 offset:5120
	ds_read_b128 v[210:213], v146 offset:6144
	ds_read_b128 v[214:217], v146 offset:7168
	global_load_lds_dwordx4 v[196:197], off
	v_lshl_add_u64 v[196:197], s[34:35], 0, v[142:143]
	s_add_i32 m0, s51, 0xe000
	s_nop 0
	global_load_lds_dwordx4 v[196:197], off
	s_waitcnt vmcnt(8)
	s_waitcnt lgkmcnt(0)
	s_barrier
; #define PG8_GOFFS(slot_) do { _Pragma("unroll") for (int _i = 0; _i < 2; ++_i) { int R, C; stage_rc(tid * 16 + _i * 8192, R, C); _Pragma("unroll") for (int _h = 0; _h < 2; ++_h) { \
;         unsigned t_ = gtab[(slot_) * 256 + R + 128 * _h]; t_ = t_ < (unsigned)(T - 1) ? t_ : (unsigned)(T - 1); voffA[_h][_i] = (t_ * (unsigned)K + (unsigned)C) * 2u; } } } while (0)
; #define PG8_STAGE(bufoff, gbase, voff) do { _Pragma("unroll") for (int _i = 0; _i < 2; ++_i) \
;         __builtin_amdgcn_global_load_lds((const unsigned*)((const char*)(gbase) + (voff)[_i]), (LAS unsigned*)(lds + (bufoff) + ldsw + _i * 8192), 16, 0, 0); } while (0)
; #define PG8_BAR __builtin_amdgcn_s_barrier()
; template <class Epi, class Sched>
; __device__ __forceinline__ void gemm_phase(const int tid, LAS unsigned char* lds, const bf16* Aop, const bf16* Bop, const int K_, const Sched& S, const Epi& E, const bf16* Aop1 = nullptr, const bf16* Bop1 = nullptr) {
;     ...
;         for (int t = 0; t < nt; t += 2) {
;             const bool last = (t == nt - 2);
;             const char* a1 = cA + (size_t)(t + 1) * kstep;
;             const char* a2 = last ? nA : cA + (size_t)(t + 2) * kstep; const char* b2 = last ? nB : cB + (size_t)(t + 2) * kstep;
;             const char* a3 = a2 + kstep; const char* b3 = b2 + kstep;
;             PG8_LDB(B0, 0, 0); PG8_LDB(B1, 0, 1); PG8_SCHED; PG8_LDA(At, 0, 0); PG8_STAGE_A1(PG8_SA(1, 1), a1);
;             PG8_WAIT_V(8); PG8_WAIT_L(0); PG8_BAR; PG8_MMA(0, 0, At, B0); PG8_MMA(0, 1, At, B1); PG8_BAR; PG8_SCHED;
;             PG8_LDA(At, 0, 1); PG8_STAGE(PG8_SB(0, 0), b2, voffB); PG8_STAGE(PG8_SB(0, 1), b2 + hstep, voffB); if (Epi::GATHER && last && has_next) PG8_GOFFS((ui + 1) & 1); PG8_STAGE(PG8_SA(0, 0), a2, voffA[0]);
;             PG8_WAIT_V(8); PG8_WAIT_L(0); PG8_BAR; PG8_MMA(1, 0, At, B0); PG8_MMA(1, 1, At, B1); PG8_BAR; PG8_SCHED;
;             PG8_LDB(B0, 1, 0); PG8_LDB(B1, 1, 1); PG8_SCHED; PG8_LDA(At, 1, 0); PG8_STAGE_A1(PG8_SA(0, 1), a2);
;             PG8_WAIT_V(8); PG8_WAIT_L(0); PG8_BAR; PG8_MMA(0, 0, At, B0); PG8_MMA(0, 1, At, B1); PG8_BAR; PG8_SCHED;
;             PG8_LDA(At, 1, 1); PG8_STAGE(PG8_SB(1, 0), b3, voffB); PG8_STAGE(PG8_SB(1, 1), b3 + hstep, voffB); PG8_STAGE(PG8_SA(1, 0), a3, voffA[0]);
;             PG8_WAIT_V(8); PG8_WAIT_L(0); PG8_BAR; PG8_MMA(1, 0, At, B0); PG8_MMA(1, 1, At, B1); PG8_BAR; PG8_SCHED;
;         }
	v_mfma_f32_16x16x32_bf16 v[124:127], v[148:151], v[180:183], v[124:127]
	v_mfma_f32_16x16x32_bf16 v[128:131], v[156:159], v[180:183], v[128:131]
	v_mfma_f32_16x16x32_bf16 v[112:115], v[148:151], v[188:191], v[112:115]
	v_mfma_f32_16x16x32_bf16 v[108:111], v[156:159], v[188:191], v[108:111]
	v_mfma_f32_16x16x32_bf16 v[96:99], v[148:151], v[202:205], v[96:99]
	v_mfma_f32_16x16x32_bf16 v[92:95], v[156:159], v[202:205], v[92:95]
	v_mfma_f32_16x16x32_bf16 v[80:83], v[148:151], v[210:213], v[80:83]
	v_mfma_f32_16x16x32_bf16 v[76:79], v[156:159], v[210:213], v[76:79]
	v_mfma_f32_16x16x32_bf16 v[124:127], v[152:155], v[184:187], v[124:127]
	v_mfma_f32_16x16x32_bf16 v[128:131], v[160:163], v[184:187], v[128:131]
	v_mfma_f32_16x16x32_bf16 v[112:115], v[152:155], v[192:195], v[112:115]
	v_mfma_f32_16x16x32_bf16 v[108:111], v[160:163], v[192:195], v[108:111]
	v_mfma_f32_16x16x32_bf16 v[96:99], v[152:155], v[206:209], v[96:99]
	v_mfma_f32_16x16x32_bf16 v[92:95], v[160:163], v[206:209], v[92:95]
	v_mfma_f32_16x16x32_bf16 v[80:83], v[152:155], v[214:217], v[80:83]
	v_mfma_f32_16x16x32_bf16 v[76:79], v[160:163], v[214:217], v[76:79]
	v_mfma_f32_16x16x32_bf16 v[120:123], v[164:167], v[180:183], v[120:123]
	v_mfma_f32_16x16x32_bf16 v[116:119], v[172:175], v[180:183], v[116:119]
	v_mfma_f32_16x16x32_bf16 v[104:107], v[164:167], v[188:191], v[104:107]
	v_mfma_f32_16x16x32_bf16 v[100:103], v[172:175], v[188:191], v[100:103]
	v_mfma_f32_16x16x32_bf16 v[88:91], v[164:167], v[202:205], v[88:91]
	v_mfma_f32_16x16x32_bf16 v[84:87], v[172:175], v[202:205], v[84:87]
	v_mfma_f32_16x16x32_bf16 v[72:75], v[164:167], v[210:213], v[72:75]
	v_mfma_f32_16x16x32_bf16 v[68:71], v[172:175], v[210:213], v[68:71]
	v_mfma_f32_16x16x32_bf16 v[120:123], v[168:171], v[184:187], v[120:123]
	v_mfma_f32_16x16x32_bf16 v[116:119], v[176:179], v[184:187], v[116:119]
	v_mfma_f32_16x16x32_bf16 v[104:107], v[168:171], v[192:195], v[104:107]
	v_mfma_f32_16x16x32_bf16 v[100:103], v[176:179], v[192:195], v[100:103]
	v_mfma_f32_16x16x32_bf16 v[88:91], v[168:171], v[206:209], v[88:91]
	v_mfma_f32_16x16x32_bf16 v[84:87], v[176:179], v[206:209], v[84:87]
	v_mfma_f32_16x16x32_bf16 v[72:75], v[168:171], v[214:217], v[72:75]
	v_mfma_f32_16x16x32_bf16 v[68:71], v[176:179], v[214:217], v[68:71]
	s_barrier
	s_add_i32 s70, s70, s50
	v_lshl_add_u64 v[196:197], s[68:69], 0, v[134:135]
	s_mov_b32 m0, s70
	ds_read_b128 v[180:183], v146 offset:16384
	ds_read_b128 v[184:187], v146 offset:17408
	ds_read_b128 v[188:191], v146 offset:18432
	ds_read_b128 v[192:195], v146 offset:19456
	ds_read_b128 v[202:205], v146 offset:20480
	ds_read_b128 v[206:209], v146 offset:21504
	ds_read_b128 v[210:213], v146 offset:22528
	ds_read_b128 v[214:217], v146 offset:23552
	global_load_lds_dwordx4 v[196:197], off
	s_add_i32 m0, s70, 0x2000
	v_lshl_add_u64 v[198:199], s[68:69], 0, v[0:1]
	s_add_u32 s68, s68, s6
	s_addc_u32 s69, s69, s7
	s_add_i32 s70, s71, s50
	global_load_lds_dwordx4 v[198:199], off
	v_lshl_add_u64 v[218:219], s[68:69], 0, v[134:135]
	s_mov_b32 m0, s70
	v_lshl_add_u64 v[220:221], s[68:69], 0, v[0:1]
	global_load_lds_dwordx4 v[218:219], off
	s_add_i32 m0, s70, 0x2000
	v_lshl_add_u64 v[222:223], s[36:37], 0, v[136:137]
	global_load_lds_dwordx4 v[220:221], off
	s_mov_b32 m0, s51
	v_lshl_add_u64 v[224:225], s[36:37], 0, v[132:133]
	global_load_lds_dwordx4 v[222:223], off
	s_mov_b32 m0, s52
	s_nop 0
	global_load_lds_dwordx4 v[224:225], off
	s_waitcnt vmcnt(8)
	s_waitcnt lgkmcnt(0)
	s_barrier
	v_mfma_f32_16x16x32_bf16 v[64:67], v[148:151], v[180:183], v[64:67]
	v_mfma_f32_16x16x32_bf16 v[60:63], v[156:159], v[180:183], v[60:63]
	v_mfma_f32_16x16x32_bf16 v[48:51], v[148:151], v[188:191], v[48:51]
	v_mfma_f32_16x16x32_bf16 v[44:47], v[156:159], v[188:191], v[44:47]
	v_mfma_f32_16x16x32_bf16 v[32:35], v[148:151], v[202:205], v[32:35]
	v_mfma_f32_16x16x32_bf16 v[28:31], v[156:159], v[202:205], v[28:31]
	v_mfma_f32_16x16x32_bf16 v[16:19], v[148:151], v[210:213], v[16:19]
	v_mfma_f32_16x16x32_bf16 v[12:15], v[156:159], v[210:213], v[12:15]
	v_mfma_f32_16x16x32_bf16 v[64:67], v[152:155], v[184:187], v[64:67]
	v_mfma_f32_16x16x32_bf16 v[60:63], v[160:163], v[184:187], v[60:63]
	v_mfma_f32_16x16x32_bf16 v[48:51], v[152:155], v[192:195], v[48:51]
	v_mfma_f32_16x16x32_bf16 v[44:47], v[160:163], v[192:195], v[44:47]
	v_mfma_f32_16x16x32_bf16 v[32:35], v[152:155], v[206:209], v[32:35]
	v_mfma_f32_16x16x32_bf16 v[28:31], v[160:163], v[206:209], v[28:31]
	v_mfma_f32_16x16x32_bf16 v[16:19], v[152:155], v[214:217], v[16:19]
	v_mfma_f32_16x16x32_bf16 v[12:15], v[160:163], v[214:217], v[12:15]
	v_mfma_f32_16x16x32_bf16 v[56:59], v[164:167], v[180:183], v[56:59]
	v_mfma_f32_16x16x32_bf16 v[52:55], v[172:175], v[180:183], v[52:55]
	v_mfma_f32_16x16x32_bf16 v[40:43], v[164:167], v[188:191], v[40:43]
	v_mfma_f32_16x16x32_bf16 v[36:39], v[172:175], v[188:191], v[36:39]
	v_mfma_f32_16x16x32_bf16 v[24:27], v[164:167], v[202:205], v[24:27]
	v_mfma_f32_16x16x32_bf16 v[20:23], v[172:175], v[202:205], v[20:23]
	v_mfma_f32_16x16x32_bf16 v[8:11], v[164:167], v[210:213], v[8:11]
	v_mfma_f32_16x16x32_bf16 v[4:7], v[172:175], v[210:213], v[4:7]
	v_mfma_f32_16x16x32_bf16 v[56:59], v[168:171], v[184:187], v[56:59]
	v_mfma_f32_16x16x32_bf16 v[52:55], v[176:179], v[184:187], v[52:55]
	v_mfma_f32_16x16x32_bf16 v[40:43], v[168:171], v[192:195], v[40:43]
	v_mfma_f32_16x16x32_bf16 v[36:39], v[176:179], v[192:195], v[36:39]
	v_mfma_f32_16x16x32_bf16 v[24:27], v[168:171], v[206:209], v[24:27]
	v_mfma_f32_16x16x32_bf16 v[20:23], v[176:179], v[206:209], v[20:23]
	v_mfma_f32_16x16x32_bf16 v[8:11], v[168:171], v[214:217], v[8:11]
	v_mfma_f32_16x16x32_bf16 v[4:7], v[176:179], v[214:217], v[4:7]
	s_barrier
; #define PG8_GOFFS(slot_) do { _Pragma("unroll") for (int _i = 0; _i < 2; ++_i) { int R, C; stage_rc(tid * 16 + _i * 8192, R, C); _Pragma("unroll") for (int _h = 0; _h < 2; ++_h) { \
;         unsigned t_ = gtab[(slot_) * 256 + R + 128 * _h]; t_ = t_ < (unsigned)(T - 1) ? t_ : (unsigned)(T - 1); voffA[_h][_i] = (t_ * (unsigned)K + (unsigned)C) * 2u; } } } while (0)
; #define PG8_STAGE(bufoff, gbase, voff) do { _Pragma("unroll") for (int _i = 0; _i < 2; ++_i) \
;         __builtin_amdgcn_global_load_lds((const unsigned*)((const char*)(gbase) + (voff)[_i]), (LAS unsigned*)(lds + (bufoff) + ldsw + _i * 8192), 16, 0, 0); } while (0)
; #define PG8_BAR __builtin_amdgcn_s_barrier()
; template <class Epi, class Sched>
; __device__ __forceinline__ void gemm_phase(const int tid, LAS unsigned char* lds, const bf16* Aop, const bf16* Bop, const int K_, const Sched& S, const Epi& E, const bf16* Aop1 = nullptr, const bf16* Bop1 = nullptr) {
;     ...
;         for (int t = 0; t < nt; t += 2) {
;             const bool last = (t == nt - 2);
;             const char* a1 = cA + (size_t)(t + 1) * kstep;
;             const char* a2 = last ? nA : cA + (size_t)(t + 2) * kstep; const char* b2 = last ? nB : cB + (size_t)(t + 2) * kstep;
;             const char* a3 = a2 + kstep; const char* b3 = b2 + kstep;
;             PG8_LDB(B0, 0, 0); PG8_LDB(B1, 0, 1); PG8_SCHED; PG8_LDA(At, 0, 0); PG8_STAGE_A1(PG8_SA(1, 1), a1);
;             PG8_WAIT_V(8); PG8_WAIT_L(0); PG8_BAR; PG8_MMA(0, 0, At, B0); PG8_MMA(0, 1, At, B1); PG8_BAR; PG8_SCHED;
;             PG8_LDA(At, 0, 1); PG8_STAGE(PG8_SB(0, 0), b2, voffB); PG8_STAGE(PG8_SB(0, 1), b2 + hstep, voffB); if (Epi::GATHER && last && has_next) PG8_GOFFS((ui + 1) & 1); PG8_STAGE(PG8_SA(0, 0), a2, voffA[0]);
;             PG8_WAIT_V(8); PG8_WAIT_L(0); PG8_BAR; PG8_MMA(1, 0, At, B0); PG8_MMA(1, 1, At, B1); PG8_BAR; PG8_SCHED;
;             PG8_LDB(B0, 1, 0); PG8_LDB(B1, 1, 1); PG8_SCHED; PG8_LDA(At, 1, 0); PG8_STAGE_A1(PG8_SA(0, 1), a2);
;             PG8_WAIT_V(8); PG8_WAIT_L(0); PG8_BAR; PG8_MMA(0, 0, At, B0); PG8_MMA(0, 1, At, B1); PG8_BAR; PG8_SCHED;
;             PG8_LDA(At, 1, 1); PG8_STAGE(PG8_SB(1, 0), b3, voffB); PG8_STAGE(PG8_SB(1, 1), b3 + hstep, voffB); PG8_STAGE(PG8_SA(1, 0), a3, voffA[0]);
;             PG8_WAIT_V(8); PG8_WAIT_L(0); PG8_BAR; PG8_MMA(1, 0, At, B0); PG8_MMA(1, 1, At, B1); PG8_BAR; PG8_SCHED;
;         }
	s_add_i32 s68, 0, 0x18000
	v_add_u32_e32 v147, s68, v144
	s_add_i32 s69, 0, 0x1c000
	ds_read_b128 v[148:151], v147
	ds_read_b128 v[152:155], v147 offset:1024
	ds_read_b128 v[156:159], v147 offset:2048
	ds_read_b128 v[160:163], v147 offset:3072
	v_add_u32_e32 v147, s69, v144
	ds_read_b128 v[164:167], v147
	ds_read_b128 v[168:171], v147 offset:1024
	ds_read_b128 v[172:175], v147 offset:2048
	ds_read_b128 v[176:179], v147 offset:3072
	s_add_u32 s36, s36, s6
	s_addc_u32 s37, s37, s7
	s_mov_b32 m0, s53
	v_lshl_add_u64 v[230:231], s[36:37], 0, v[136:137]
	ds_read_b128 v[180:183], v146 offset:32768
	ds_read_b128 v[184:187], v146 offset:33792
	ds_read_b128 v[188:191], v146 offset:34816
	ds_read_b128 v[192:195], v146 offset:35840
	ds_read_b128 v[202:205], v146 offset:36864
	ds_read_b128 v[206:209], v146 offset:37888
	ds_read_b128 v[210:213], v146 offset:38912
	ds_read_b128 v[214:217], v146 offset:39936
	global_load_lds_dwordx4 v[230:231], off
	v_lshl_add_u64 v[230:231], s[36:37], 0, v[132:133]
	s_mov_b32 m0, s54
	s_nop 0
	global_load_lds_dwordx4 v[230:231], off
	s_waitcnt vmcnt(8)
	s_waitcnt lgkmcnt(0)
	s_barrier
	v_mfma_f32_16x16x32_bf16 v[124:127], v[148:151], v[180:183], v[124:127]
	v_mfma_f32_16x16x32_bf16 v[128:131], v[156:159], v[180:183], v[128:131]
	v_mfma_f32_16x16x32_bf16 v[112:115], v[148:151], v[188:191], v[112:115]
	v_mfma_f32_16x16x32_bf16 v[108:111], v[156:159], v[188:191], v[108:111]
	v_mfma_f32_16x16x32_bf16 v[96:99], v[148:151], v[202:205], v[96:99]
	v_mfma_f32_16x16x32_bf16 v[92:95], v[156:159], v[202:205], v[92:95]
	v_mfma_f32_16x16x32_bf16 v[80:83], v[148:151], v[210:213], v[80:83]
	v_mfma_f32_16x16x32_bf16 v[76:79], v[156:159], v[210:213], v[76:79]
	v_mfma_f32_16x16x32_bf16 v[124:127], v[152:155], v[184:187], v[124:127]
	v_mfma_f32_16x16x32_bf16 v[128:131], v[160:163], v[184:187], v[128:131]
	v_mfma_f32_16x16x32_bf16 v[112:115], v[152:155], v[192:195], v[112:115]
	v_mfma_f32_16x16x32_bf16 v[108:111], v[160:163], v[192:195], v[108:111]
	v_mfma_f32_16x16x32_bf16 v[96:99], v[152:155], v[206:209], v[96:99]
	v_mfma_f32_16x16x32_bf16 v[92:95], v[160:163], v[206:209], v[92:95]
	v_mfma_f32_16x16x32_bf16 v[80:83], v[152:155], v[214:217], v[80:83]
	v_mfma_f32_16x16x32_bf16 v[76:79], v[160:163], v[214:217], v[76:79]
	v_mfma_f32_16x16x32_bf16 v[120:123], v[164:167], v[180:183], v[120:123]
	v_mfma_f32_16x16x32_bf16 v[116:119], v[172:175], v[180:183], v[116:119]
	v_mfma_f32_16x16x32_bf16 v[104:107], v[164:167], v[188:191], v[104:107]
	v_mfma_f32_16x16x32_bf16 v[100:103], v[172:175], v[188:191], v[100:103]
	v_mfma_f32_16x16x32_bf16 v[88:91], v[164:167], v[202:205], v[88:91]
	v_mfma_f32_16x16x32_bf16 v[84:87], v[172:175], v[202:205], v[84:87]
	v_mfma_f32_16x16x32_bf16 v[72:75], v[164:167], v[210:213], v[72:75]
	v_mfma_f32_16x16x32_bf16 v[68:71], v[172:175], v[210:213], v[68:71]
	v_mfma_f32_16x16x32_bf16 v[120:123], v[168:171], v[184:187], v[120:123]
	v_mfma_f32_16x16x32_bf16 v[116:119], v[176:179], v[184:187], v[116:119]
	v_mfma_f32_16x16x32_bf16 v[104:107], v[168:171], v[192:195], v[104:107]
	v_mfma_f32_16x16x32_bf16 v[100:103], v[176:179], v[192:195], v[100:103]
	v_mfma_f32_16x16x32_bf16 v[88:91], v[168:171], v[206:209], v[88:91]
	v_mfma_f32_16x16x32_bf16 v[84:87], v[176:179], v[206:209], v[84:87]
	v_mfma_f32_16x16x32_bf16 v[72:75], v[168:171], v[214:217], v[72:75]
	v_mfma_f32_16x16x32_bf16 v[68:71], v[176:179], v[214:217], v[68:71]
	s_barrier
	s_add_i32 s36, s68, s50
	v_lshl_add_u64 v[196:197], v[196:197], 0, s[20:21]
	s_mov_b32 m0, s36
	ds_read_b128 v[180:183], v146 offset:49152
	ds_read_b128 v[184:187], v146 offset:50176
	ds_read_b128 v[188:191], v146 offset:51200
	ds_read_b128 v[192:195], v146 offset:52224
	ds_read_b128 v[202:205], v146 offset:53248
	ds_read_b128 v[206:209], v146 offset:54272
	ds_read_b128 v[210:213], v146 offset:55296
	ds_read_b128 v[214:217], v146 offset:56320
	global_load_lds_dwordx4 v[196:197], off
	v_lshl_add_u64 v[196:197], v[198:199], 0, s[20:21]
	s_add_i32 m0, s36, 0x2000
	s_add_i32 s36, s69, s50
	global_load_lds_dwordx4 v[196:197], off
	v_lshl_add_u64 v[196:197], v[218:219], 0, s[20:21]
	s_mov_b32 m0, s36
	s_nop 0
	global_load_lds_dwordx4 v[196:197], off
	v_lshl_add_u64 v[196:197], v[220:221], 0, s[20:21]
	s_add_i32 m0, s36, 0x2000
	s_nop 0
	global_load_lds_dwordx4 v[196:197], off
	v_lshl_add_u64 v[196:197], v[222:223], 0, s[20:21]
	s_mov_b32 m0, s56
	s_nop 0
	global_load_lds_dwordx4 v[196:197], off
	v_lshl_add_u64 v[196:197], v[224:225], 0, s[20:21]
	s_mov_b32 m0, s57
	s_nop 0
	global_load_lds_dwordx4 v[196:197], off
	s_waitcnt vmcnt(8)
	s_waitcnt lgkmcnt(0)
	s_barrier
	v_mfma_f32_16x16x32_bf16 v[64:67], v[148:151], v[180:183], v[64:67]
	v_mfma_f32_16x16x32_bf16 v[60:63], v[156:159], v[180:183], v[60:63]
	v_mfma_f32_16x16x32_bf16 v[48:51], v[148:151], v[188:191], v[48:51]
	v_mfma_f32_16x16x32_bf16 v[44:47], v[156:159], v[188:191], v[44:47]
	v_mfma_f32_16x16x32_bf16 v[32:35], v[148:151], v[202:205], v[32:35]
	v_mfma_f32_16x16x32_bf16 v[28:31], v[156:159], v[202:205], v[28:31]
	v_mfma_f32_16x16x32_bf16 v[16:19], v[148:151], v[210:213], v[16:19]
	v_mfma_f32_16x16x32_bf16 v[12:15], v[156:159], v[210:213], v[12:15]
	v_mfma_f32_16x16x32_bf16 v[64:67], v[152:155], v[184:187], v[64:67]
	v_mfma_f32_16x16x32_bf16 v[60:63], v[160:163], v[184:187], v[60:63]
	v_mfma_f32_16x16x32_bf16 v[48:51], v[152:155], v[192:195], v[48:51]
	v_mfma_f32_16x16x32_bf16 v[44:47], v[160:163], v[192:195], v[44:47]
	v_mfma_f32_16x16x32_bf16 v[32:35], v[152:155], v[206:209], v[32:35]
	v_mfma_f32_16x16x32_bf16 v[28:31], v[160:163], v[206:209], v[28:31]
	v_mfma_f32_16x16x32_bf16 v[16:19], v[152:155], v[214:217], v[16:19]
	v_mfma_f32_16x16x32_bf16 v[12:15], v[160:163], v[214:217], v[12:15]
	v_mfma_f32_16x16x32_bf16 v[56:59], v[164:167], v[180:183], v[56:59]
	v_mfma_f32_16x16x32_bf16 v[52:55], v[172:175], v[180:183], v[52:55]
	v_mfma_f32_16x16x32_bf16 v[40:43], v[164:167], v[188:191], v[40:43]
	v_mfma_f32_16x16x32_bf16 v[36:39], v[172:175], v[188:191], v[36:39]
	v_mfma_f32_16x16x32_bf16 v[24:27], v[164:167], v[202:205], v[24:27]
	v_mfma_f32_16x16x32_bf16 v[20:23], v[172:175], v[202:205], v[20:23]
	v_mfma_f32_16x16x32_bf16 v[8:11], v[164:167], v[210:213], v[8:11]
	v_mfma_f32_16x16x32_bf16 v[4:7], v[172:175], v[210:213], v[4:7]
	v_mfma_f32_16x16x32_bf16 v[56:59], v[168:171], v[184:187], v[56:59]
	v_mfma_f32_16x16x32_bf16 v[52:55], v[176:179], v[184:187], v[52:55]
	v_mfma_f32_16x16x32_bf16 v[40:43], v[168:171], v[192:195], v[40:43]
	v_mfma_f32_16x16x32_bf16 v[36:39], v[176:179], v[192:195], v[36:39]
	v_mfma_f32_16x16x32_bf16 v[24:27], v[168:171], v[206:209], v[24:27]
	v_mfma_f32_16x16x32_bf16 v[20:23], v[176:179], v[206:209], v[20:23]
	v_mfma_f32_16x16x32_bf16 v[8:11], v[168:171], v[214:217], v[8:11]
	v_mfma_f32_16x16x32_bf16 v[4:7], v[176:179], v[214:217], v[4:7]
	s_barrier
	s_add_u32 s34, s34, 0x100
	s_addc_u32 s35, s35, 0
	s_add_u32 s65, s65, 0x100
	s_addc_u32 s66, s66, 0
	s_cmp_ge_i32 s67, s55
	s_mov_b32 s36, s67
	s_cbranch_scc0 .LBB0_1400

; #define PG8_GOFFS(slot_) do { _Pragma("unroll") for (int _i = 0; _i < 2; ++_i) { int R, C; stage_rc(tid * 16 + _i * 8192, R, C); _Pragma("unroll") for (int _h = 0; _h < 2; ++_h) { \
;         unsigned t_ = gtab[(slot_) * 256 + R + 128 * _h]; t_ = t_ < (unsigned)(T - 1) ? t_ : (unsigned)(T - 1); voffA[_h][_i] = (t_ * (unsigned)K + (unsigned)C) * 2u; } } } while (0)
; #define PG8_STAGE(bufoff, gbase, voff) do { _Pragma("unroll") for (int _i = 0; _i < 2; ++_i) \
;         __builtin_amdgcn_global_load_lds((const unsigned*)((const char*)(gbase) + (voff)[_i]), (LAS unsigned*)(lds + (bufoff) + ldsw + _i * 8192), 16, 0, 0); } while (0)
; #define PG8_BAR __builtin_amdgcn_s_barrier()
; template <class Epi, class Sched>
; __device__ __forceinline__ void gemm_phase(const int tid, LAS unsigned char* lds, const bf16* Aop, const bf16* Bop, const int K_, const Sched& S, const Epi& E, const bf16* Aop1 = nullptr, const bf16* Bop1 = nullptr) {
;     ...
;         for (int t = 0; t < nt; t += 2) {
;             const bool last = (t == nt - 2);
;             const char* a1 = cA + (size_t)(t + 1) * kstep;
;             const char* a2 = last ? nA : cA + (size_t)(t + 2) * kstep; const char* b2 = last ? nB : cB + (size_t)(t + 2) * kstep;
;             const char* a3 = a2 + kstep; const char* b3 = b2 + kstep;
;             PG8_LDB(B0, 0, 0); PG8_LDB(B1, 0, 1); PG8_SCHED; PG8_LDA(At, 0, 0); PG8_STAGE_A1(PG8_SA(1, 1), a1);
;             PG8_WAIT_V(8); PG8_WAIT_L(0); PG8_BAR; PG8_MMA(0, 0, At, B0); PG8_MMA(0, 1, At, B1); PG8_BAR; PG8_SCHED;
;             PG8_LDA(At, 0, 1); PG8_STAGE(PG8_SB(0, 0), b2, voffB); PG8_STAGE(PG8_SB(0, 1), b2 + hstep, voffB); if (Epi::GATHER && last && has_next) PG8_GOFFS((ui + 1) & 1); PG8_STAGE(PG8_SA(0, 0), a2, voffA[0]);
;             PG8_WAIT_V(8); PG8_WAIT_L(0); PG8_BAR; PG8_MMA(1, 0, At, B0); PG8_MMA(1, 1, At, B1); PG8_BAR; PG8_SCHED;
;             PG8_LDB(B0, 1, 0); PG8_LDB(B1, 1, 1); PG8_SCHED; PG8_LDA(At, 1, 0); PG8_STAGE_A1(PG8_SA(0, 1), a2);
;             PG8_WAIT_V(8); PG8_WAIT_L(0); PG8_BAR; PG8_MMA(0, 0, At, B0); PG8_MMA(0, 1, At, B1); PG8_BAR; PG8_SCHED;
;             PG8_LDA(At, 1, 1); PG8_STAGE(PG8_SB(1, 0), b3, voffB); PG8_STAGE(PG8_SB(1, 1), b3 + hstep, voffB); PG8_STAGE(PG8_SA(1, 0), a3, voffA[0]);
;             PG8_WAIT_V(8); PG8_WAIT_L(0); PG8_BAR; PG8_MMA(1, 0, At, B0); PG8_MMA(1, 1, At, B1); PG8_BAR; PG8_SCHED;
;         }
.LBB0_1418:
	v_mov_b32_e32 v127, 0
	s_andn2_b64 vcc, exec, s[16:17]
	s_cbranch_vccnz .LBB0_1421
	s_add_u32 s34, s34, 0x80
	s_addc_u32 s35, s35, 0
	s_add_u32 s15, s36, 0x100
	s_addc_u32 s67, s37, 0
	s_mov_b32 s36, 0
	s_add_i32 s68, s36, 2
	s_add_u32 s69, s34, 0x80
	s_addc_u32 s37, s35, 0
	s_add_i32 s72, 0, 0x10000
	s_cmp_eq_u32 s61, s36
	s_cselect_b32 s37, s27, s37
	s_cselect_b32 s36, s26, s69
	s_cselect_b32 s71, s29, s67
	s_cselect_b32 s70, s28, s15
	s_add_i32 s69, 0, 0x14000
	v_add_u32_e32 v158, s72, v3
	v_add_u32_e32 v174, s69, v3
	ds_read_b128 v[146:149], v158
	ds_read_b128 v[150:153], v158 offset:1024
	ds_read_b128 v[154:157], v158 offset:2048
	ds_read_b128 v[158:161], v158 offset:3072
	ds_read_b128 v[162:165], v174
	ds_read_b128 v[166:169], v174 offset:1024
	ds_read_b128 v[170:173], v174 offset:2048
	ds_read_b128 v[174:177], v174 offset:3072
	v_lshl_add_u64 v[194:195], s[34:35], 0, v[140:141]
	s_add_i32 m0, s53, 0xc000
	ds_read_b128 v[178:181], v144
	ds_read_b128 v[182:185], v144 offset:1024
	ds_read_b128 v[186:189], v144 offset:2048
	ds_read_b128 v[190:193], v144 offset:3072
	ds_read_b128 v[202:205], v144 offset:4096
	ds_read_b128 v[206:209], v144 offset:5120
	ds_read_b128 v[210:213], v144 offset:6144
	ds_read_b128 v[214:217], v144 offset:7168
	global_load_lds_dwordx4 v[194:195], off
	v_lshl_add_u64 v[194:195], s[34:35], 0, v[142:143]
	s_add_i32 m0, s53, 0xe000
	s_nop 0
	global_load_lds_dwordx4 v[194:195], off
	s_waitcnt vmcnt(8)
	s_waitcnt lgkmcnt(0)
	s_barrier
	v_mfma_f32_16x16x32_bf16 v[124:127], v[146:149], v[178:181], 0
	v_mfma_f32_16x16x32_bf16 v[128:131], v[154:157], v[178:181], 0
	v_mfma_f32_16x16x32_bf16 v[112:115], v[146:149], v[186:189], 0
	v_mfma_f32_16x16x32_bf16 v[108:111], v[154:157], v[186:189], 0
	v_mfma_f32_16x16x32_bf16 v[96:99], v[146:149], v[202:205], 0
	v_mfma_f32_16x16x32_bf16 v[92:95], v[154:157], v[202:205], 0
	v_mfma_f32_16x16x32_bf16 v[80:83], v[146:149], v[210:213], 0
	v_mfma_f32_16x16x32_bf16 v[76:79], v[154:157], v[210:213], 0
	v_mfma_f32_16x16x32_bf16 v[124:127], v[150:153], v[182:185], v[124:127]
	v_mfma_f32_16x16x32_bf16 v[128:131], v[158:161], v[182:185], v[128:131]
	v_mfma_f32_16x16x32_bf16 v[112:115], v[150:153], v[190:193], v[112:115]
	v_mfma_f32_16x16x32_bf16 v[108:111], v[158:161], v[190:193], v[108:111]
	v_mfma_f32_16x16x32_bf16 v[96:99], v[150:153], v[206:209], v[96:99]
	v_mfma_f32_16x16x32_bf16 v[92:95], v[158:161], v[206:209], v[92:95]
	v_mfma_f32_16x16x32_bf16 v[80:83], v[150:153], v[214:217], v[80:83]
	v_mfma_f32_16x16x32_bf16 v[76:79], v[158:161], v[214:217], v[76:79]
	v_mfma_f32_16x16x32_bf16 v[120:123], v[162:165], v[178:181], 0
	v_mfma_f32_16x16x32_bf16 v[116:119], v[170:173], v[178:181], 0
	v_mfma_f32_16x16x32_bf16 v[104:107], v[162:165], v[186:189], 0
	v_mfma_f32_16x16x32_bf16 v[100:103], v[170:173], v[186:189], 0
	v_mfma_f32_16x16x32_bf16 v[88:91], v[162:165], v[202:205], 0
	v_mfma_f32_16x16x32_bf16 v[84:87], v[170:173], v[202:205], 0
	v_mfma_f32_16x16x32_bf16 v[72:75], v[162:165], v[210:213], 0
	v_mfma_f32_16x16x32_bf16 v[68:71], v[170:173], v[210:213], 0
	v_mfma_f32_16x16x32_bf16 v[120:123], v[166:169], v[182:185], v[120:123]
	v_mfma_f32_16x16x32_bf16 v[116:119], v[174:177], v[182:185], v[116:119]
	v_mfma_f32_16x16x32_bf16 v[104:107], v[166:169], v[190:193], v[104:107]
	v_mfma_f32_16x16x32_bf16 v[100:103], v[174:177], v[190:193], v[100:103]
	v_mfma_f32_16x16x32_bf16 v[88:91], v[166:169], v[206:209], v[88:91]
	v_mfma_f32_16x16x32_bf16 v[84:87], v[174:177], v[206:209], v[84:87]
	v_mfma_f32_16x16x32_bf16 v[72:75], v[166:169], v[214:217], v[72:75]
	v_mfma_f32_16x16x32_bf16 v[68:71], v[174:177], v[214:217], v[68:71]
	s_barrier
	s_add_i32 s72, s72, s52
	v_lshl_add_u64 v[194:195], s[70:71], 0, v[134:135]
	s_mov_b32 m0, s72
	ds_read_b128 v[178:181], v144 offset:16384
	ds_read_b128 v[182:185], v144 offset:17408
	ds_read_b128 v[186:189], v144 offset:18432
	ds_read_b128 v[190:193], v144 offset:19456
	ds_read_b128 v[202:205], v144 offset:20480
	ds_read_b128 v[206:209], v144 offset:21504
	ds_read_b128 v[210:213], v144 offset:22528
	ds_read_b128 v[214:217], v144 offset:23552
	global_load_lds_dwordx4 v[194:195], off
	s_add_i32 m0, s72, 0x2000
	v_lshl_add_u64 v[196:197], s[70:71], 0, v[0:1]
	s_add_u32 s70, s70, s6
	s_addc_u32 s71, s71, s7
	s_add_i32 s69, s69, s52
	global_load_lds_dwordx4 v[196:197], off
	v_lshl_add_u64 v[198:199], s[70:71], 0, v[134:135]
	s_mov_b32 m0, s69
	v_lshl_add_u64 v[218:219], s[70:71], 0, v[0:1]
	global_load_lds_dwordx4 v[198:199], off
	s_add_i32 m0, s69, 0x2000
	v_lshl_add_u64 v[220:221], s[36:37], 0, v[136:137]
	global_load_lds_dwordx4 v[218:219], off
	s_mov_b32 m0, s53
	v_lshl_add_u64 v[222:223], s[36:37], 0, v[132:133]
	global_load_lds_dwordx4 v[220:221], off
	s_mov_b32 m0, s54
	s_nop 0
	global_load_lds_dwordx4 v[222:223], off
	s_waitcnt vmcnt(8)
	s_waitcnt lgkmcnt(0)
	s_barrier
; #define PG8_GOFFS(slot_) do { _Pragma("unroll") for (int _i = 0; _i < 2; ++_i) { int R, C; stage_rc(tid * 16 + _i * 8192, R, C); _Pragma("unroll") for (int _h = 0; _h < 2; ++_h) { \
;         unsigned t_ = gtab[(slot_) * 256 + R + 128 * _h]; t_ = t_ < (unsigned)(T - 1) ? t_ : (unsigned)(T - 1); voffA[_h][_i] = (t_ * (unsigned)K + (unsigned)C) * 2u; } } } while (0)
; #define PG8_STAGE(bufoff, gbase, voff) do { _Pragma("unroll") for (int _i = 0; _i < 2; ++_i) \
;         __builtin_amdgcn_global_load_lds((const unsigned*)((const char*)(gbase) + (voff)[_i]), (LAS unsigned*)(lds + (bufoff) + ldsw + _i * 8192), 16, 0, 0); } while (0)
; #define PG8_BAR __builtin_amdgcn_s_barrier()
; template <class Epi, class Sched>
; __device__ __forceinline__ void gemm_phase(const int tid, LAS unsigned char* lds, const bf16* Aop, const bf16* Bop, const int K_, const Sched& S, const Epi& E, const bf16* Aop1 = nullptr, const bf16* Bop1 = nullptr) {
;     ...
;         for (int t = 0; t < nt; t += 2) {
;             const bool last = (t == nt - 2);
;             const char* a1 = cA + (size_t)(t + 1) * kstep;
;             const char* a2 = last ? nA : cA + (size_t)(t + 2) * kstep; const char* b2 = last ? nB : cB + (size_t)(t + 2) * kstep;
;             const char* a3 = a2 + kstep; const char* b3 = b2 + kstep;
;             PG8_LDB(B0, 0, 0); PG8_LDB(B1, 0, 1); PG8_SCHED; PG8_LDA(At, 0, 0); PG8_STAGE_A1(PG8_SA(1, 1), a1);
;             PG8_WAIT_V(8); PG8_WAIT_L(0); PG8_BAR; PG8_MMA(0, 0, At, B0); PG8_MMA(0, 1, At, B1); PG8_BAR; PG8_SCHED;
;             PG8_LDA(At, 0, 1); PG8_STAGE(PG8_SB(0, 0), b2, voffB); PG8_STAGE(PG8_SB(0, 1), b2 + hstep, voffB); if (Epi::GATHER && last && has_next) PG8_GOFFS((ui + 1) & 1); PG8_STAGE(PG8_SA(0, 0), a2, voffA[0]);
;             PG8_WAIT_V(8); PG8_WAIT_L(0); PG8_BAR; PG8_MMA(1, 0, At, B0); PG8_MMA(1, 1, At, B1); PG8_BAR; PG8_SCHED;
;             PG8_LDB(B0, 1, 0); PG8_LDB(B1, 1, 1); PG8_SCHED; PG8_LDA(At, 1, 0); PG8_STAGE_A1(PG8_SA(0, 1), a2);
;             PG8_WAIT_V(8); PG8_WAIT_L(0); PG8_BAR; PG8_MMA(0, 0, At, B0); PG8_MMA(0, 1, At, B1); PG8_BAR; PG8_SCHED;
;             PG8_LDA(At, 1, 1); PG8_STAGE(PG8_SB(1, 0), b3, voffB); PG8_STAGE(PG8_SB(1, 1), b3 + hstep, voffB); PG8_STAGE(PG8_SA(1, 0), a3, voffA[0]);
;             PG8_WAIT_V(8); PG8_WAIT_L(0); PG8_BAR; PG8_MMA(1, 0, At, B0); PG8_MMA(1, 1, At, B1); PG8_BAR; PG8_SCHED;
;         }
	v_mfma_f32_16x16x32_bf16 v[64:67], v[146:149], v[178:181], 0
	v_mfma_f32_16x16x32_bf16 v[60:63], v[154:157], v[178:181], 0
	v_mfma_f32_16x16x32_bf16 v[48:51], v[146:149], v[186:189], 0
	v_mfma_f32_16x16x32_bf16 v[44:47], v[154:157], v[186:189], 0
	v_mfma_f32_16x16x32_bf16 v[32:35], v[146:149], v[202:205], 0
	v_mfma_f32_16x16x32_bf16 v[28:31], v[154:157], v[202:205], 0
	v_mfma_f32_16x16x32_bf16 v[16:19], v[146:149], v[210:213], 0
	v_mfma_f32_16x16x32_bf16 v[12:15], v[154:157], v[210:213], 0
	v_mfma_f32_16x16x32_bf16 v[64:67], v[150:153], v[182:185], v[64:67]
	v_mfma_f32_16x16x32_bf16 v[60:63], v[158:161], v[182:185], v[60:63]
	v_mfma_f32_16x16x32_bf16 v[48:51], v[150:153], v[190:193], v[48:51]
	v_mfma_f32_16x16x32_bf16 v[44:47], v[158:161], v[190:193], v[44:47]
	v_mfma_f32_16x16x32_bf16 v[32:35], v[150:153], v[206:209], v[32:35]
	v_mfma_f32_16x16x32_bf16 v[28:31], v[158:161], v[206:209], v[28:31]
	v_mfma_f32_16x16x32_bf16 v[16:19], v[150:153], v[214:217], v[16:19]
	v_mfma_f32_16x16x32_bf16 v[12:15], v[158:161], v[214:217], v[12:15]
	v_mfma_f32_16x16x32_bf16 v[56:59], v[162:165], v[178:181], 0
	v_mfma_f32_16x16x32_bf16 v[52:55], v[170:173], v[178:181], 0
	v_mfma_f32_16x16x32_bf16 v[40:43], v[162:165], v[186:189], 0
	v_mfma_f32_16x16x32_bf16 v[36:39], v[170:173], v[186:189], 0
	v_mfma_f32_16x16x32_bf16 v[24:27], v[162:165], v[202:205], 0
	v_mfma_f32_16x16x32_bf16 v[20:23], v[170:173], v[202:205], 0
	v_mfma_f32_16x16x32_bf16 v[8:11], v[162:165], v[210:213], 0
	v_mfma_f32_16x16x32_bf16 v[4:7], v[170:173], v[210:213], 0
	v_mfma_f32_16x16x32_bf16 v[56:59], v[166:169], v[182:185], v[56:59]
	v_mfma_f32_16x16x32_bf16 v[52:55], v[174:177], v[182:185], v[52:55]
	v_mfma_f32_16x16x32_bf16 v[40:43], v[166:169], v[190:193], v[40:43]
	v_mfma_f32_16x16x32_bf16 v[36:39], v[174:177], v[190:193], v[36:39]
	v_mfma_f32_16x16x32_bf16 v[24:27], v[166:169], v[206:209], v[24:27]
	v_mfma_f32_16x16x32_bf16 v[20:23], v[174:177], v[206:209], v[20:23]
	v_mfma_f32_16x16x32_bf16 v[8:11], v[166:169], v[214:217], v[8:11]
	v_mfma_f32_16x16x32_bf16 v[4:7], v[174:177], v[214:217], v[4:7]
	s_barrier
	s_add_i32 s69, 0, 0x18000
	s_add_i32 s70, 0, 0x1c000
	v_add_u32_e32 v158, s69, v3
	v_add_u32_e32 v174, s70, v3
	ds_read_b128 v[146:149], v158
	ds_read_b128 v[150:153], v158 offset:1024
	ds_read_b128 v[154:157], v158 offset:2048
	ds_read_b128 v[158:161], v158 offset:3072
	ds_read_b128 v[162:165], v174
	ds_read_b128 v[166:169], v174 offset:1024
	ds_read_b128 v[170:173], v174 offset:2048
	ds_read_b128 v[174:177], v174 offset:3072
	s_add_u32 s36, s36, s6
	s_addc_u32 s37, s37, s7
	s_mov_b32 m0, s55
	v_lshl_add_u64 v[224:225], s[36:37], 0, v[136:137]
	ds_read_b128 v[178:181], v144 offset:32768
	ds_read_b128 v[182:185], v144 offset:33792
	ds_read_b128 v[186:189], v144 offset:34816
	ds_read_b128 v[190:193], v144 offset:35840
	ds_read_b128 v[202:205], v144 offset:36864
	ds_read_b128 v[206:209], v144 offset:37888
	ds_read_b128 v[210:213], v144 offset:38912
	ds_read_b128 v[214:217], v144 offset:39936
	global_load_lds_dwordx4 v[224:225], off
	v_lshl_add_u64 v[224:225], s[36:37], 0, v[132:133]
	s_mov_b32 m0, s56
	s_nop 0
	global_load_lds_dwordx4 v[224:225], off
	s_waitcnt vmcnt(8)
	s_waitcnt lgkmcnt(0)
	s_barrier
	v_mfma_f32_16x16x32_bf16 v[124:127], v[146:149], v[178:181], v[124:127]
	v_mfma_f32_16x16x32_bf16 v[128:131], v[154:157], v[178:181], v[128:131]
	v_mfma_f32_16x16x32_bf16 v[112:115], v[146:149], v[186:189], v[112:115]
	v_mfma_f32_16x16x32_bf16 v[108:111], v[154:157], v[186:189], v[108:111]
	v_mfma_f32_16x16x32_bf16 v[96:99], v[146:149], v[202:205], v[96:99]
	v_mfma_f32_16x16x32_bf16 v[92:95], v[154:157], v[202:205], v[92:95]
	v_mfma_f32_16x16x32_bf16 v[80:83], v[146:149], v[210:213], v[80:83]
	v_mfma_f32_16x16x32_bf16 v[76:79], v[154:157], v[210:213], v[76:79]
	v_mfma_f32_16x16x32_bf16 v[124:127], v[150:153], v[182:185], v[124:127]
	v_mfma_f32_16x16x32_bf16 v[128:131], v[158:161], v[182:185], v[128:131]
	v_mfma_f32_16x16x32_bf16 v[112:115], v[150:153], v[190:193], v[112:115]
	v_mfma_f32_16x16x32_bf16 v[108:111], v[158:161], v[190:193], v[108:111]
	v_mfma_f32_16x16x32_bf16 v[96:99], v[150:153], v[206:209], v[96:99]
	v_mfma_f32_16x16x32_bf16 v[92:95], v[158:161], v[206:209], v[92:95]
	v_mfma_f32_16x16x32_bf16 v[80:83], v[150:153], v[214:217], v[80:83]
	v_mfma_f32_16x16x32_bf16 v[76:79], v[158:161], v[214:217], v[76:79]
	v_mfma_f32_16x16x32_bf16 v[120:123], v[162:165], v[178:181], v[120:123]
	v_mfma_f32_16x16x32_bf16 v[116:119], v[170:173], v[178:181], v[116:119]
	v_mfma_f32_16x16x32_bf16 v[104:107], v[162:165], v[186:189], v[104:107]
	v_mfma_f32_16x16x32_bf16 v[100:103], v[170:173], v[186:189], v[100:103]
	v_mfma_f32_16x16x32_bf16 v[88:91], v[162:165], v[202:205], v[88:91]
	v_mfma_f32_16x16x32_bf16 v[84:87], v[170:173], v[202:205], v[84:87]
	v_mfma_f32_16x16x32_bf16 v[72:75], v[162:165], v[210:213], v[72:75]
	v_mfma_f32_16x16x32_bf16 v[68:71], v[170:173], v[210:213], v[68:71]
	v_mfma_f32_16x16x32_bf16 v[120:123], v[166:169], v[182:185], v[120:123]
	v_mfma_f32_16x16x32_bf16 v[116:119], v[174:177], v[182:185], v[116:119]
	v_mfma_f32_16x16x32_bf16 v[104:107], v[166:169], v[190:193], v[104:107]
	v_mfma_f32_16x16x32_bf16 v[100:103], v[174:177], v[190:193], v[100:103]
	v_mfma_f32_16x16x32_bf16 v[88:91], v[166:169], v[206:209], v[88:91]
	v_mfma_f32_16x16x32_bf16 v[84:87], v[174:177], v[206:209], v[84:87]
	v_mfma_f32_16x16x32_bf16 v[72:75], v[166:169], v[214:217], v[72:75]
	v_mfma_f32_16x16x32_bf16 v[68:71], v[174:177], v[214:217], v[68:71]
	s_barrier
; #define PG8_GOFFS(slot_) do { _Pragma("unroll") for (int _i = 0; _i < 2; ++_i) { int R, C; stage_rc(tid * 16 + _i * 8192, R, C); _Pragma("unroll") for (int _h = 0; _h < 2; ++_h) { \
;         unsigned t_ = gtab[(slot_) * 256 + R + 128 * _h]; t_ = t_ < (unsigned)(T - 1) ? t_ : (unsigned)(T - 1); voffA[_h][_i] = (t_ * (unsigned)K + (unsigned)C) * 2u; } } } while (0)
; #define PG8_STAGE(bufoff, gbase, voff) do { _Pragma("unroll") for (int _i = 0; _i < 2; ++_i) \
;         __builtin_amdgcn_global_load_lds((const unsigned*)((const char*)(gbase) + (voff)[_i]), (LAS unsigned*)(lds + (bufoff) + ldsw + _i * 8192), 16, 0, 0); } while (0)
; #define PG8_BAR __builtin_amdgcn_s_barrier()
; template <class Epi, class Sched>
; __device__ __forceinline__ void gemm_phase(const int tid, LAS unsigned char* lds, const bf16* Aop, const bf16* Bop, const int K_, const Sched& S, const Epi& E, const bf16* Aop1 = nullptr, const bf16* Bop1 = nullptr) {
;     ...
;         for (int t = 0; t < nt; t += 2) {
;             const bool last = (t == nt - 2);
;             const char* a1 = cA + (size_t)(t + 1) * kstep;
;             const char* a2 = last ? nA : cA + (size_t)(t + 2) * kstep; const char* b2 = last ? nB : cB + (size_t)(t + 2) * kstep;
;             const char* a3 = a2 + kstep; const char* b3 = b2 + kstep;
;             PG8_LDB(B0, 0, 0); PG8_LDB(B1, 0, 1); PG8_SCHED; PG8_LDA(At, 0, 0); PG8_STAGE_A1(PG8_SA(1, 1), a1);
;             PG8_WAIT_V(8); PG8_WAIT_L(0); PG8_BAR; PG8_MMA(0, 0, At, B0); PG8_MMA(0, 1, At, B1); PG8_BAR; PG8_SCHED;
;             PG8_LDA(At, 0, 1); PG8_STAGE(PG8_SB(0, 0), b2, voffB); PG8_STAGE(PG8_SB(0, 1), b2 + hstep, voffB); if (Epi::GATHER && last && has_next) PG8_GOFFS((ui + 1) & 1); PG8_STAGE(PG8_SA(0, 0), a2, voffA[0]);
;             PG8_WAIT_V(8); PG8_WAIT_L(0); PG8_BAR; PG8_MMA(1, 0, At, B0); PG8_MMA(1, 1, At, B1); PG8_BAR; PG8_SCHED;
;             PG8_LDB(B0, 1, 0); PG8_LDB(B1, 1, 1); PG8_SCHED; PG8_LDA(At, 1, 0); PG8_STAGE_A1(PG8_SA(0, 1), a2);
;             PG8_WAIT_V(8); PG8_WAIT_L(0); PG8_BAR; PG8_MMA(0, 0, At, B0); PG8_MMA(0, 1, At, B1); PG8_BAR; PG8_SCHED;
;             PG8_LDA(At, 1, 1); PG8_STAGE(PG8_SB(1, 0), b3, voffB); PG8_STAGE(PG8_SB(1, 1), b3 + hstep, voffB); PG8_STAGE(PG8_SA(1, 0), a3, voffA[0]);
;             PG8_WAIT_V(8); PG8_WAIT_L(0); PG8_BAR; PG8_MMA(1, 0, At, B0); PG8_MMA(1, 1, At, B1); PG8_BAR; PG8_SCHED;
;         }
	s_add_i32 s36, s69, s52
	v_lshl_add_u64 v[194:195], v[194:195], 0, s[20:21]
	s_mov_b32 m0, s36
	ds_read_b128 v[178:181], v144 offset:49152
	ds_read_b128 v[182:185], v144 offset:50176
	ds_read_b128 v[186:189], v144 offset:51200
	ds_read_b128 v[190:193], v144 offset:52224
	ds_read_b128 v[202:205], v144 offset:53248
	ds_read_b128 v[206:209], v144 offset:54272
	ds_read_b128 v[210:213], v144 offset:55296
	ds_read_b128 v[214:217], v144 offset:56320
	global_load_lds_dwordx4 v[194:195], off
	v_lshl_add_u64 v[194:195], v[196:197], 0, s[20:21]
	s_add_i32 m0, s36, 0x2000
	s_add_i32 s36, s70, s52
	global_load_lds_dwordx4 v[194:195], off
	v_lshl_add_u64 v[194:195], v[198:199], 0, s[20:21]
	s_mov_b32 m0, s36
	s_nop 0
	global_load_lds_dwordx4 v[194:195], off
	v_lshl_add_u64 v[194:195], v[218:219], 0, s[20:21]
	s_add_i32 m0, s36, 0x2000
	s_nop 0
	global_load_lds_dwordx4 v[194:195], off
	v_lshl_add_u64 v[194:195], v[220:221], 0, s[20:21]
	s_mov_b32 m0, s59
	s_nop 0
	global_load_lds_dwordx4 v[194:195], off
	v_lshl_add_u64 v[194:195], v[222:223], 0, s[20:21]
	s_mov_b32 m0, s60
	s_nop 0
	global_load_lds_dwordx4 v[194:195], off
	s_waitcnt vmcnt(8)
	s_waitcnt lgkmcnt(0)
	s_barrier
	v_mfma_f32_16x16x32_bf16 v[64:67], v[146:149], v[178:181], v[64:67]
	v_mfma_f32_16x16x32_bf16 v[60:63], v[154:157], v[178:181], v[60:63]
	v_mfma_f32_16x16x32_bf16 v[48:51], v[146:149], v[186:189], v[48:51]
	v_mfma_f32_16x16x32_bf16 v[44:47], v[154:157], v[186:189], v[44:47]
	v_mfma_f32_16x16x32_bf16 v[32:35], v[146:149], v[202:205], v[32:35]
	v_mfma_f32_16x16x32_bf16 v[28:31], v[154:157], v[202:205], v[28:31]
	v_mfma_f32_16x16x32_bf16 v[16:19], v[146:149], v[210:213], v[16:19]
	v_mfma_f32_16x16x32_bf16 v[12:15], v[154:157], v[210:213], v[12:15]
	v_mfma_f32_16x16x32_bf16 v[64:67], v[150:153], v[182:185], v[64:67]
	v_mfma_f32_16x16x32_bf16 v[60:63], v[158:161], v[182:185], v[60:63]
	v_mfma_f32_16x16x32_bf16 v[48:51], v[150:153], v[190:193], v[48:51]
	v_mfma_f32_16x16x32_bf16 v[44:47], v[158:161], v[190:193], v[44:47]
	v_mfma_f32_16x16x32_bf16 v[32:35], v[150:153], v[206:209], v[32:35]
	v_mfma_f32_16x16x32_bf16 v[28:31], v[158:161], v[206:209], v[28:31]
	v_mfma_f32_16x16x32_bf16 v[16:19], v[150:153], v[214:217], v[16:19]
	v_mfma_f32_16x16x32_bf16 v[12:15], v[158:161], v[214:217], v[12:15]
	v_mfma_f32_16x16x32_bf16 v[56:59], v[162:165], v[178:181], v[56:59]
	v_mfma_f32_16x16x32_bf16 v[52:55], v[170:173], v[178:181], v[52:55]
	v_mfma_f32_16x16x32_bf16 v[40:43], v[162:165], v[186:189], v[40:43]
	v_mfma_f32_16x16x32_bf16 v[36:39], v[170:173], v[186:189], v[36:39]
	v_mfma_f32_16x16x32_bf16 v[24:27], v[162:165], v[202:205], v[24:27]
	v_mfma_f32_16x16x32_bf16 v[20:23], v[170:173], v[202:205], v[20:23]
	v_mfma_f32_16x16x32_bf16 v[8:11], v[162:165], v[210:213], v[8:11]
	v_mfma_f32_16x16x32_bf16 v[4:7], v[170:173], v[210:213], v[4:7]
	v_mfma_f32_16x16x32_bf16 v[56:59], v[166:169], v[182:185], v[56:59]
	v_mfma_f32_16x16x32_bf16 v[52:55], v[174:177], v[182:185], v[52:55]
	v_mfma_f32_16x16x32_bf16 v[40:43], v[166:169], v[190:193], v[40:43]
	v_mfma_f32_16x16x32_bf16 v[36:39], v[174:177], v[190:193], v[36:39]
	v_mfma_f32_16x16x32_bf16 v[24:27], v[166:169], v[206:209], v[24:27]
	v_mfma_f32_16x16x32_bf16 v[20:23], v[174:177], v[206:209], v[20:23]
	v_mfma_f32_16x16x32_bf16 v[8:11], v[166:169], v[214:217], v[8:11]
	v_mfma_f32_16x16x32_bf16 v[4:7], v[174:177], v[214:217], v[4:7]
	s_barrier
	s_add_u32 s34, s34, 0x100
	s_addc_u32 s35, s35, 0
	s_add_u32 s15, s15, 0x100
	s_addc_u32 s67, s67, 0
	s_cmp_ge_i32 s68, s58
	s_mov_b32 s36, s68
	s_cbranch_scc0 .LBB0_1420
	s_branch .LBB0_1421
.LBB0_1420:
	s_add_i32 s68, s36, 2
	s_add_u32 s69, s34, 0x80
	s_addc_u32 s37, s35, 0
	s_add_i32 s72, 0, 0x10000
	s_cmp_eq_u32 s61, s36
	s_cselect_b32 s37, s27, s37
	s_cselect_b32 s36, s26, s69
	s_cselect_b32 s71, s29, s67
	s_cselect_b32 s70, s28, s15
	s_add_i32 s69, 0, 0x14000
	v_add_u32_e32 v158, s72, v3
	v_add_u32_e32 v174, s69, v3
	ds_read_b128 v[146:149], v158
	ds_read_b128 v[150:153], v158 offset:1024
	ds_read_b128 v[154:157], v158 offset:2048
	ds_read_b128 v[158:161], v158 offset:3072
	ds_read_b128 v[162:165], v174
	ds_read_b128 v[166:169], v174 offset:1024
	ds_read_b128 v[170:173], v174 offset:2048
	ds_read_b128 v[174:177], v174 offset:3072
	v_lshl_add_u64 v[194:195], s[34:35], 0, v[140:141]
	s_add_i32 m0, s53, 0xc000
	ds_read_b128 v[178:181], v144
	ds_read_b128 v[182:185], v144 offset:1024
	ds_read_b128 v[186:189], v144 offset:2048
	ds_read_b128 v[190:193], v144 offset:3072
	ds_read_b128 v[202:205], v144 offset:4096
	ds_read_b128 v[206:209], v144 offset:5120
	ds_read_b128 v[210:213], v144 offset:6144
	ds_read_b128 v[214:217], v144 offset:7168
	global_load_lds_dwordx4 v[194:195], off
	v_lshl_add_u64 v[194:195], s[34:35], 0, v[142:143]
	s_add_i32 m0, s53, 0xe000
	s_nop 0
	global_load_lds_dwordx4 v[194:195], off
	s_waitcnt vmcnt(8)
	s_waitcnt lgkmcnt(0)
	s_barrier
; #define PG8_GOFFS(slot_) do { _Pragma("unroll") for (int _i = 0; _i < 2; ++_i) { int R, C; stage_rc(tid * 16 + _i * 8192, R, C); _Pragma("unroll") for (int _h = 0; _h < 2; ++_h) { \
;         unsigned t_ = gtab[(slot_) * 256 + R + 128 * _h]; t_ = t_ < (unsigned)(T - 1) ? t_ : (unsigned)(T - 1); voffA[_h][_i] = (t_ * (unsigned)K + (unsigned)C) * 2u; } } } while (0)
; #define PG8_STAGE(bufoff, gbase, voff) do { _Pragma("unroll") for (int _i = 0; _i < 2; ++_i) \
;         __builtin_amdgcn_global_load_lds((const unsigned*)((const char*)(gbase) + (voff)[_i]), (LAS unsigned*)(lds + (bufoff) + ldsw + _i * 8192), 16, 0, 0); } while (0)
; #define PG8_BAR __builtin_amdgcn_s_barrier()
; template <class Epi, class Sched>
; __device__ __forceinline__ void gemm_phase(const int tid, LAS unsigned char* lds, const bf16* Aop, const bf16* Bop, const int K_, const Sched& S, const Epi& E, const bf16* Aop1 = nullptr, const bf16* Bop1 = nullptr) {
;     ...
;         for (int t = 0; t < nt; t += 2) {
;             const bool last = (t == nt - 2);
;             const char* a1 = cA + (size_t)(t + 1) * kstep;
;             const char* a2 = last ? nA : cA + (size_t)(t + 2) * kstep; const char* b2 = last ? nB : cB + (size_t)(t + 2) * kstep;
;             const char* a3 = a2 + kstep; const char* b3 = b2 + kstep;
;             PG8_LDB(B0, 0, 0); PG8_LDB(B1, 0, 1); PG8_SCHED; PG8_LDA(At, 0, 0); PG8_STAGE_A1(PG8_SA(1, 1), a1);
;             PG8_WAIT_V(8); PG8_WAIT_L(0); PG8_BAR; PG8_MMA(0, 0, At, B0); PG8_MMA(0, 1, At, B1); PG8_BAR; PG8_SCHED;
;             PG8_LDA(At, 0, 1); PG8_STAGE(PG8_SB(0, 0), b2, voffB); PG8_STAGE(PG8_SB(0, 1), b2 + hstep, voffB); if (Epi::GATHER && last && has_next) PG8_GOFFS((ui + 1) & 1); PG8_STAGE(PG8_SA(0, 0), a2, voffA[0]);
;             PG8_WAIT_V(8); PG8_WAIT_L(0); PG8_BAR; PG8_MMA(1, 0, At, B0); PG8_MMA(1, 1, At, B1); PG8_BAR; PG8_SCHED;
;             PG8_LDB(B0, 1, 0); PG8_LDB(B1, 1, 1); PG8_SCHED; PG8_LDA(At, 1, 0); PG8_STAGE_A1(PG8_SA(0, 1), a2);
;             PG8_WAIT_V(8); PG8_WAIT_L(0); PG8_BAR; PG8_MMA(0, 0, At, B0); PG8_MMA(0, 1, At, B1); PG8_BAR; PG8_SCHED;
;             PG8_LDA(At, 1, 1); PG8_STAGE(PG8_SB(1, 0), b3, voffB); PG8_STAGE(PG8_SB(1, 1), b3 + hstep, voffB); PG8_STAGE(PG8_SA(1, 0), a3, voffA[0]);
;             PG8_WAIT_V(8); PG8_WAIT_L(0); PG8_BAR; PG8_MMA(1, 0, At, B0); PG8_MMA(1, 1, At, B1); PG8_BAR; PG8_SCHED;
;         }
	v_mfma_f32_16x16x32_bf16 v[124:127], v[146:149], v[178:181], v[124:127]
	v_mfma_f32_16x16x32_bf16 v[128:131], v[154:157], v[178:181], v[128:131]
	v_mfma_f32_16x16x32_bf16 v[112:115], v[146:149], v[186:189], v[112:115]
	v_mfma_f32_16x16x32_bf16 v[108:111], v[154:157], v[186:189], v[108:111]
	v_mfma_f32_16x16x32_bf16 v[96:99], v[146:149], v[202:205], v[96:99]
	v_mfma_f32_16x16x32_bf16 v[92:95], v[154:157], v[202:205], v[92:95]
	v_mfma_f32_16x16x32_bf16 v[80:83], v[146:149], v[210:213], v[80:83]
	v_mfma_f32_16x16x32_bf16 v[76:79], v[154:157], v[210:213], v[76:79]
	v_mfma_f32_16x16x32_bf16 v[124:127], v[150:153], v[182:185], v[124:127]
	v_mfma_f32_16x16x32_bf16 v[128:131], v[158:161], v[182:185], v[128:131]
	v_mfma_f32_16x16x32_bf16 v[112:115], v[150:153], v[190:193], v[112:115]
	v_mfma_f32_16x16x32_bf16 v[108:111], v[158:161], v[190:193], v[108:111]
	v_mfma_f32_16x16x32_bf16 v[96:99], v[150:153], v[206:209], v[96:99]
	v_mfma_f32_16x16x32_bf16 v[92:95], v[158:161], v[206:209], v[92:95]
	v_mfma_f32_16x16x32_bf16 v[80:83], v[150:153], v[214:217], v[80:83]
	v_mfma_f32_16x16x32_bf16 v[76:79], v[158:161], v[214:217], v[76:79]
	v_mfma_f32_16x16x32_bf16 v[120:123], v[162:165], v[178:181], v[120:123]
	v_mfma_f32_16x16x32_bf16 v[116:119], v[170:173], v[178:181], v[116:119]
	v_mfma_f32_16x16x32_bf16 v[104:107], v[162:165], v[186:189], v[104:107]
	v_mfma_f32_16x16x32_bf16 v[100:103], v[170:173], v[186:189], v[100:103]
	v_mfma_f32_16x16x32_bf16 v[88:91], v[162:165], v[202:205], v[88:91]
	v_mfma_f32_16x16x32_bf16 v[84:87], v[170:173], v[202:205], v[84:87]
	v_mfma_f32_16x16x32_bf16 v[72:75], v[162:165], v[210:213], v[72:75]
	v_mfma_f32_16x16x32_bf16 v[68:71], v[170:173], v[210:213], v[68:71]
	v_mfma_f32_16x16x32_bf16 v[120:123], v[166:169], v[182:185], v[120:123]
	v_mfma_f32_16x16x32_bf16 v[116:119], v[174:177], v[182:185], v[116:119]
	v_mfma_f32_16x16x32_bf16 v[104:107], v[166:169], v[190:193], v[104:107]
	v_mfma_f32_16x16x32_bf16 v[100:103], v[174:177], v[190:193], v[100:103]
	v_mfma_f32_16x16x32_bf16 v[88:91], v[166:169], v[206:209], v[88:91]
	v_mfma_f32_16x16x32_bf16 v[84:87], v[174:177], v[206:209], v[84:87]
	v_mfma_f32_16x16x32_bf16 v[72:75], v[166:169], v[214:217], v[72:75]
	v_mfma_f32_16x16x32_bf16 v[68:71], v[174:177], v[214:217], v[68:71]
	s_barrier
	s_add_i32 s72, s72, s52
	v_lshl_add_u64 v[194:195], s[70:71], 0, v[134:135]
	s_mov_b32 m0, s72
	ds_read_b128 v[178:181], v144 offset:16384
	ds_read_b128 v[182:185], v144 offset:17408
	ds_read_b128 v[186:189], v144 offset:18432
	ds_read_b128 v[190:193], v144 offset:19456
	ds_read_b128 v[202:205], v144 offset:20480
	ds_read_b128 v[206:209], v144 offset:21504
	ds_read_b128 v[210:213], v144 offset:22528
	ds_read_b128 v[214:217], v144 offset:23552
	global_load_lds_dwordx4 v[194:195], off
	s_add_i32 m0, s72, 0x2000
	v_lshl_add_u64 v[196:197], s[70:71], 0, v[0:1]
	s_add_u32 s70, s70, s6
	s_addc_u32 s71, s71, s7
	s_add_i32 s69, s69, s52
	global_load_lds_dwordx4 v[196:197], off
	v_lshl_add_u64 v[198:199], s[70:71], 0, v[134:135]
	s_mov_b32 m0, s69
	v_lshl_add_u64 v[218:219], s[70:71], 0, v[0:1]
	global_load_lds_dwordx4 v[198:199], off
	s_add_i32 m0, s69, 0x2000
	v_lshl_add_u64 v[220:221], s[36:37], 0, v[136:137]
	global_load_lds_dwordx4 v[218:219], off
	s_mov_b32 m0, s53
	v_lshl_add_u64 v[222:223], s[36:37], 0, v[132:133]
	global_load_lds_dwordx4 v[220:221], off
	s_mov_b32 m0, s54
	s_nop 0
	global_load_lds_dwordx4 v[222:223], off
	s_waitcnt vmcnt(8)
	s_waitcnt lgkmcnt(0)
	s_barrier
	v_mfma_f32_16x16x32_bf16 v[64:67], v[146:149], v[178:181], v[64:67]
	v_mfma_f32_16x16x32_bf16 v[60:63], v[154:157], v[178:181], v[60:63]
	v_mfma_f32_16x16x32_bf16 v[48:51], v[146:149], v[186:189], v[48:51]
	v_mfma_f32_16x16x32_bf16 v[44:47], v[154:157], v[186:189], v[44:47]
	v_mfma_f32_16x16x32_bf16 v[32:35], v[146:149], v[202:205], v[32:35]
	v_mfma_f32_16x16x32_bf16 v[28:31], v[154:157], v[202:205], v[28:31]
	v_mfma_f32_16x16x32_bf16 v[16:19], v[146:149], v[210:213], v[16:19]
	v_mfma_f32_16x16x32_bf16 v[12:15], v[154:157], v[210:213], v[12:15]
	v_mfma_f32_16x16x32_bf16 v[64:67], v[150:153], v[182:185], v[64:67]
	v_mfma_f32_16x16x32_bf16 v[60:63], v[158:161], v[182:185], v[60:63]
	v_mfma_f32_16x16x32_bf16 v[48:51], v[150:153], v[190:193], v[48:51]
	v_mfma_f32_16x16x32_bf16 v[44:47], v[158:161], v[190:193], v[44:47]
	v_mfma_f32_16x16x32_bf16 v[32:35], v[150:153], v[206:209], v[32:35]
	v_mfma_f32_16x16x32_bf16 v[28:31], v[158:161], v[206:209], v[28:31]
	v_mfma_f32_16x16x32_bf16 v[16:19], v[150:153], v[214:217], v[16:19]
	v_mfma_f32_16x16x32_bf16 v[12:15], v[158:161], v[214:217], v[12:15]
	v_mfma_f32_16x16x32_bf16 v[56:59], v[162:165], v[178:181], v[56:59]
	v_mfma_f32_16x16x32_bf16 v[52:55], v[170:173], v[178:181], v[52:55]
	v_mfma_f32_16x16x32_bf16 v[40:43], v[162:165], v[186:189], v[40:43]
	v_mfma_f32_16x16x32_bf16 v[36:39], v[170:173], v[186:189], v[36:39]
	v_mfma_f32_16x16x32_bf16 v[24:27], v[162:165], v[202:205], v[24:27]
	v_mfma_f32_16x16x32_bf16 v[20:23], v[170:173], v[202:205], v[20:23]
	v_mfma_f32_16x16x32_bf16 v[8:11], v[162:165], v[210:213], v[8:11]
	v_mfma_f32_16x16x32_bf16 v[4:7], v[170:173], v[210:213], v[4:7]
	v_mfma_f32_16x16x32_bf16 v[56:59], v[166:169], v[182:185], v[56:59]
	v_mfma_f32_16x16x32_bf16 v[52:55], v[174:177], v[182:185], v[52:55]
	v_mfma_f32_16x16x32_bf16 v[40:43], v[166:169], v[190:193], v[40:43]
	v_mfma_f32_16x16x32_bf16 v[36:39], v[174:177], v[190:193], v[36:39]
	v_mfma_f32_16x16x32_bf16 v[24:27], v[166:169], v[206:209], v[24:27]
	v_mfma_f32_16x16x32_bf16 v[20:23], v[174:177], v[206:209], v[20:23]
	v_mfma_f32_16x16x32_bf16 v[8:11], v[166:169], v[214:217], v[8:11]
	v_mfma_f32_16x16x32_bf16 v[4:7], v[174:177], v[214:217], v[4:7]
	s_barrier
; #define PG8_GOFFS(slot_) do { _Pragma("unroll") for (int _i = 0; _i < 2; ++_i) { int R, C; stage_rc(tid * 16 + _i * 8192, R, C); _Pragma("unroll") for (int _h = 0; _h < 2; ++_h) { \
;         unsigned t_ = gtab[(slot_) * 256 + R + 128 * _h]; t_ = t_ < (unsigned)(T - 1) ? t_ : (unsigned)(T - 1); voffA[_h][_i] = (t_ * (unsigned)K + (unsigned)C) * 2u; } } } while (0)
; #define PG8_STAGE(bufoff, gbase, voff) do { _Pragma("unroll") for (int _i = 0; _i < 2; ++_i) \
;         __builtin_amdgcn_global_load_lds((const unsigned*)((const char*)(gbase) + (voff)[_i]), (LAS unsigned*)(lds + (bufoff) + ldsw + _i * 8192), 16, 0, 0); } while (0)
; #define PG8_BAR __builtin_amdgcn_s_barrier()
; template <class Epi, class Sched>
; __device__ __forceinline__ void gemm_phase(const int tid, LAS unsigned char* lds, const bf16* Aop, const bf16* Bop, const int K_, const Sched& S, const Epi& E, const bf16* Aop1 = nullptr, const bf16* Bop1 = nullptr) {
;     ...
;         for (int t = 0; t < nt; t += 2) {
;             const bool last = (t == nt - 2);
;             const char* a1 = cA + (size_t)(t + 1) * kstep;
;             const char* a2 = last ? nA : cA + (size_t)(t + 2) * kstep; const char* b2 = last ? nB : cB + (size_t)(t + 2) * kstep;
;             const char* a3 = a2 + kstep; const char* b3 = b2 + kstep;
;             PG8_LDB(B0, 0, 0); PG8_LDB(B1, 0, 1); PG8_SCHED; PG8_LDA(At, 0, 0); PG8_STAGE_A1(PG8_SA(1, 1), a1);
;             PG8_WAIT_V(8); PG8_WAIT_L(0); PG8_BAR; PG8_MMA(0, 0, At, B0); PG8_MMA(0, 1, At, B1); PG8_BAR; PG8_SCHED;
;             PG8_LDA(At, 0, 1); PG8_STAGE(PG8_SB(0, 0), b2, voffB); PG8_STAGE(PG8_SB(0, 1), b2 + hstep, voffB); if (Epi::GATHER && last && has_next) PG8_GOFFS((ui + 1) & 1); PG8_STAGE(PG8_SA(0, 0), a2, voffA[0]);
;             PG8_WAIT_V(8); PG8_WAIT_L(0); PG8_BAR; PG8_MMA(1, 0, At, B0); PG8_MMA(1, 1, At, B1); PG8_BAR; PG8_SCHED;
;             PG8_LDB(B0, 1, 0); PG8_LDB(B1, 1, 1); PG8_SCHED; PG8_LDA(At, 1, 0); PG8_STAGE_A1(PG8_SA(0, 1), a2);
;             PG8_WAIT_V(8); PG8_WAIT_L(0); PG8_BAR; PG8_MMA(0, 0, At, B0); PG8_MMA(0, 1, At, B1); PG8_BAR; PG8_SCHED;
;             PG8_LDA(At, 1, 1); PG8_STAGE(PG8_SB(1, 0), b3, voffB); PG8_STAGE(PG8_SB(1, 1), b3 + hstep, voffB); PG8_STAGE(PG8_SA(1, 0), a3, voffA[0]);
;             PG8_WAIT_V(8); PG8_WAIT_L(0); PG8_BAR; PG8_MMA(1, 0, At, B0); PG8_MMA(1, 1, At, B1); PG8_BAR; PG8_SCHED;
;         }
	s_add_i32 s69, 0, 0x18000
	s_add_i32 s70, 0, 0x1c000
	v_add_u32_e32 v158, s69, v3
	v_add_u32_e32 v174, s70, v3
	ds_read_b128 v[146:149], v158
	ds_read_b128 v[150:153], v158 offset:1024
	ds_read_b128 v[154:157], v158 offset:2048
	ds_read_b128 v[158:161], v158 offset:3072
	ds_read_b128 v[162:165], v174
	ds_read_b128 v[166:169], v174 offset:1024
	ds_read_b128 v[170:173], v174 offset:2048
	ds_read_b128 v[174:177], v174 offset:3072
	s_add_u32 s36, s36, s6
	s_addc_u32 s37, s37, s7
	s_mov_b32 m0, s55
	v_lshl_add_u64 v[224:225], s[36:37], 0, v[136:137]
	ds_read_b128 v[178:181], v144 offset:32768
	ds_read_b128 v[182:185], v144 offset:33792
	ds_read_b128 v[186:189], v144 offset:34816
	ds_read_b128 v[190:193], v144 offset:35840
	ds_read_b128 v[202:205], v144 offset:36864
	ds_read_b128 v[206:209], v144 offset:37888
	ds_read_b128 v[210:213], v144 offset:38912
	ds_read_b128 v[214:217], v144 offset:39936
	global_load_lds_dwordx4 v[224:225], off
	v_lshl_add_u64 v[224:225], s[36:37], 0, v[132:133]
	s_mov_b32 m0, s56
	s_nop 0
	global_load_lds_dwordx4 v[224:225], off
	s_waitcnt vmcnt(8)
	s_waitcnt lgkmcnt(0)
	s_barrier
	v_mfma_f32_16x16x32_bf16 v[124:127], v[146:149], v[178:181], v[124:127]
	v_mfma_f32_16x16x32_bf16 v[128:131], v[154:157], v[178:181], v[128:131]
	v_mfma_f32_16x16x32_bf16 v[112:115], v[146:149], v[186:189], v[112:115]
	v_mfma_f32_16x16x32_bf16 v[108:111], v[154:157], v[186:189], v[108:111]
	v_mfma_f32_16x16x32_bf16 v[96:99], v[146:149], v[202:205], v[96:99]
	v_mfma_f32_16x16x32_bf16 v[92:95], v[154:157], v[202:205], v[92:95]
	v_mfma_f32_16x16x32_bf16 v[80:83], v[146:149], v[210:213], v[80:83]
	v_mfma_f32_16x16x32_bf16 v[76:79], v[154:157], v[210:213], v[76:79]
	v_mfma_f32_16x16x32_bf16 v[124:127], v[150:153], v[182:185], v[124:127]
	v_mfma_f32_16x16x32_bf16 v[128:131], v[158:161], v[182:185], v[128:131]
	v_mfma_f32_16x16x32_bf16 v[112:115], v[150:153], v[190:193], v[112:115]
	v_mfma_f32_16x16x32_bf16 v[108:111], v[158:161], v[190:193], v[108:111]
	v_mfma_f32_16x16x32_bf16 v[96:99], v[150:153], v[206:209], v[96:99]
	v_mfma_f32_16x16x32_bf16 v[92:95], v[158:161], v[206:209], v[92:95]
	v_mfma_f32_16x16x32_bf16 v[80:83], v[150:153], v[214:217], v[80:83]
	v_mfma_f32_16x16x32_bf16 v[76:79], v[158:161], v[214:217], v[76:79]
	v_mfma_f32_16x16x32_bf16 v[120:123], v[162:165], v[178:181], v[120:123]
	v_mfma_f32_16x16x32_bf16 v[116:119], v[170:173], v[178:181], v[116:119]
	v_mfma_f32_16x16x32_bf16 v[104:107], v[162:165], v[186:189], v[104:107]
	v_mfma_f32_16x16x32_bf16 v[100:103], v[170:173], v[186:189], v[100:103]
	v_mfma_f32_16x16x32_bf16 v[88:91], v[162:165], v[202:205], v[88:91]
	v_mfma_f32_16x16x32_bf16 v[84:87], v[170:173], v[202:205], v[84:87]
	v_mfma_f32_16x16x32_bf16 v[72:75], v[162:165], v[210:213], v[72:75]
	v_mfma_f32_16x16x32_bf16 v[68:71], v[170:173], v[210:213], v[68:71]
	v_mfma_f32_16x16x32_bf16 v[120:123], v[166:169], v[182:185], v[120:123]
	v_mfma_f32_16x16x32_bf16 v[116:119], v[174:177], v[182:185], v[116:119]
	v_mfma_f32_16x16x32_bf16 v[104:107], v[166:169], v[190:193], v[104:107]
	v_mfma_f32_16x16x32_bf16 v[100:103], v[174:177], v[190:193], v[100:103]
	v_mfma_f32_16x16x32_bf16 v[88:91], v[166:169], v[206:209], v[88:91]
	v_mfma_f32_16x16x32_bf16 v[84:87], v[174:177], v[206:209], v[84:87]
	v_mfma_f32_16x16x32_bf16 v[72:75], v[166:169], v[214:217], v[72:75]
	v_mfma_f32_16x16x32_bf16 v[68:71], v[174:177], v[214:217], v[68:71]
	s_barrier
	s_add_i32 s36, s69, s52
	v_lshl_add_u64 v[194:195], v[194:195], 0, s[20:21]
	s_mov_b32 m0, s36
	ds_read_b128 v[178:181], v144 offset:49152
	ds_read_b128 v[182:185], v144 offset:50176
	ds_read_b128 v[186:189], v144 offset:51200
	ds_read_b128 v[190:193], v144 offset:52224
	ds_read_b128 v[202:205], v144 offset:53248
	ds_read_b128 v[206:209], v144 offset:54272
	ds_read_b128 v[210:213], v144 offset:55296
	ds_read_b128 v[214:217], v144 offset:56320
	global_load_lds_dwordx4 v[194:195], off
	v_lshl_add_u64 v[194:195], v[196:197], 0, s[20:21]
	s_add_i32 m0, s36, 0x2000
	s_add_i32 s36, s70, s52
	global_load_lds_dwordx4 v[194:195], off
	v_lshl_add_u64 v[194:195], v[198:199], 0, s[20:21]
	s_mov_b32 m0, s36
	s_nop 0
	global_load_lds_dwordx4 v[194:195], off
	v_lshl_add_u64 v[194:195], v[218:219], 0, s[20:21]
	s_add_i32 m0, s36, 0x2000
	s_nop 0
	global_load_lds_dwordx4 v[194:195], off
	v_lshl_add_u64 v[194:195], v[220:221], 0, s[20:21]
	s_mov_b32 m0, s59
	s_nop 0
	global_load_lds_dwordx4 v[194:195], off
	v_lshl_add_u64 v[194:195], v[222:223], 0, s[20:21]
	s_mov_b32 m0, s60
	s_nop 0
	global_load_lds_dwordx4 v[194:195], off
	s_waitcnt vmcnt(8)
	s_waitcnt lgkmcnt(0)
	s_barrier
	v_mfma_f32_16x16x32_bf16 v[64:67], v[146:149], v[178:181], v[64:67]
	v_mfma_f32_16x16x32_bf16 v[60:63], v[154:157], v[178:181], v[60:63]
	v_mfma_f32_16x16x32_bf16 v[48:51], v[146:149], v[186:189], v[48:51]
	v_mfma_f32_16x16x32_bf16 v[44:47], v[154:157], v[186:189], v[44:47]
	v_mfma_f32_16x16x32_bf16 v[32:35], v[146:149], v[202:205], v[32:35]
	v_mfma_f32_16x16x32_bf16 v[28:31], v[154:157], v[202:205], v[28:31]
	v_mfma_f32_16x16x32_bf16 v[16:19], v[146:149], v[210:213], v[16:19]
	v_mfma_f32_16x16x32_bf16 v[12:15], v[154:157], v[210:213], v[12:15]
	v_mfma_f32_16x16x32_bf16 v[64:67], v[150:153], v[182:185], v[64:67]
	v_mfma_f32_16x16x32_bf16 v[60:63], v[158:161], v[182:185], v[60:63]
	v_mfma_f32_16x16x32_bf16 v[48:51], v[150:153], v[190:193], v[48:51]
	v_mfma_f32_16x16x32_bf16 v[44:47], v[158:161], v[190:193], v[44:47]
	v_mfma_f32_16x16x32_bf16 v[32:35], v[150:153], v[206:209], v[32:35]
	v_mfma_f32_16x16x32_bf16 v[28:31], v[158:161], v[206:209], v[28:31]
	v_mfma_f32_16x16x32_bf16 v[16:19], v[150:153], v[214:217], v[16:19]
	v_mfma_f32_16x16x32_bf16 v[12:15], v[158:161], v[214:217], v[12:15]
	v_mfma_f32_16x16x32_bf16 v[56:59], v[162:165], v[178:181], v[56:59]
	v_mfma_f32_16x16x32_bf16 v[52:55], v[170:173], v[178:181], v[52:55]
	v_mfma_f32_16x16x32_bf16 v[40:43], v[162:165], v[186:189], v[40:43]
	v_mfma_f32_16x16x32_bf16 v[36:39], v[170:173], v[186:189], v[36:39]
	v_mfma_f32_16x16x32_bf16 v[24:27], v[162:165], v[202:205], v[24:27]
	v_mfma_f32_16x16x32_bf16 v[20:23], v[170:173], v[202:205], v[20:23]
	v_mfma_f32_16x16x32_bf16 v[8:11], v[162:165], v[210:213], v[8:11]
	v_mfma_f32_16x16x32_bf16 v[4:7], v[170:173], v[210:213], v[4:7]
	v_mfma_f32_16x16x32_bf16 v[56:59], v[166:169], v[182:185], v[56:59]
	v_mfma_f32_16x16x32_bf16 v[52:55], v[174:177], v[182:185], v[52:55]
	v_mfma_f32_16x16x32_bf16 v[40:43], v[166:169], v[190:193], v[40:43]
	v_mfma_f32_16x16x32_bf16 v[36:39], v[174:177], v[190:193], v[36:39]
	v_mfma_f32_16x16x32_bf16 v[24:27], v[166:169], v[206:209], v[24:27]
	v_mfma_f32_16x16x32_bf16 v[20:23], v[174:177], v[206:209], v[20:23]
	v_mfma_f32_16x16x32_bf16 v[8:11], v[166:169], v[214:217], v[8:11]
	v_mfma_f32_16x16x32_bf16 v[4:7], v[174:177], v[214:217], v[4:7]
	s_barrier
	s_add_u32 s34, s34, 0x100
	s_addc_u32 s35, s35, 0
	s_add_u32 s15, s15, 0x100
	s_addc_u32 s67, s67, 0
	s_cmp_ge_i32 s68, s58
	s_mov_b32 s36, s68
	s_cbranch_scc0 .LBB0_1420

; #define PG8_GOFFS(slot_) do { _Pragma("unroll") for (int _i = 0; _i < 2; ++_i) { int R, C; stage_rc(tid * 16 + _i * 8192, R, C); _Pragma("unroll") for (int _h = 0; _h < 2; ++_h) { \
;         unsigned t_ = gtab[(slot_) * 256 + R + 128 * _h]; t_ = t_ < (unsigned)(T - 1) ? t_ : (unsigned)(T - 1); voffA[_h][_i] = (t_ * (unsigned)K + (unsigned)C) * 2u; } } } while (0)
; #define PG8_STAGE(bufoff, gbase, voff) do { _Pragma("unroll") for (int _i = 0; _i < 2; ++_i) \
;         __builtin_amdgcn_global_load_lds((const unsigned*)((const char*)(gbase) + (voff)[_i]), (LAS unsigned*)(lds + (bufoff) + ldsw + _i * 8192), 16, 0, 0); } while (0)
; #define PG8_BAR __builtin_amdgcn_s_barrier()
; template <class Epi, class Sched>
; __device__ __forceinline__ void gemm_phase(const int tid, LAS unsigned char* lds, const bf16* Aop, const bf16* Bop, const int K_, const Sched& S, const Epi& E, const bf16* Aop1 = nullptr, const bf16* Bop1 = nullptr) {
;     ...
;         for (int t = 0; t < nt; t += 2) {
;             const bool last = (t == nt - 2);
;             const char* a1 = cA + (size_t)(t + 1) * kstep;
;             const char* a2 = last ? nA : cA + (size_t)(t + 2) * kstep; const char* b2 = last ? nB : cB + (size_t)(t + 2) * kstep;
;             const char* a3 = a2 + kstep; const char* b3 = b2 + kstep;
;             PG8_LDB(B0, 0, 0); PG8_LDB(B1, 0, 1); PG8_SCHED; PG8_LDA(At, 0, 0); PG8_STAGE_A1(PG8_SA(1, 1), a1);
;             PG8_WAIT_V(8); PG8_WAIT_L(0); PG8_BAR; PG8_MMA(0, 0, At, B0); PG8_MMA(0, 1, At, B1); PG8_BAR; PG8_SCHED;
;             PG8_LDA(At, 0, 1); PG8_STAGE(PG8_SB(0, 0), b2, voffB); PG8_STAGE(PG8_SB(0, 1), b2 + hstep, voffB); if (Epi::GATHER && last && has_next) PG8_GOFFS((ui + 1) & 1); PG8_STAGE(PG8_SA(0, 0), a2, voffA[0]);
;             PG8_WAIT_V(8); PG8_WAIT_L(0); PG8_BAR; PG8_MMA(1, 0, At, B0); PG8_MMA(1, 1, At, B1); PG8_BAR; PG8_SCHED;
;             PG8_LDB(B0, 1, 0); PG8_LDB(B1, 1, 1); PG8_SCHED; PG8_LDA(At, 1, 0); PG8_STAGE_A1(PG8_SA(0, 1), a2);
;             PG8_WAIT_V(8); PG8_WAIT_L(0); PG8_BAR; PG8_MMA(0, 0, At, B0); PG8_MMA(0, 1, At, B1); PG8_BAR; PG8_SCHED;
;             PG8_LDA(At, 1, 1); PG8_STAGE(PG8_SB(1, 0), b3, voffB); PG8_STAGE(PG8_SB(1, 1), b3 + hstep, voffB); PG8_STAGE(PG8_SA(1, 0), a3, voffA[0]);
;             PG8_WAIT_V(8); PG8_WAIT_L(0); PG8_BAR; PG8_MMA(1, 0, At, B0); PG8_MMA(1, 1, At, B1); PG8_BAR; PG8_SCHED;
;         }
.LBB0_1595:
	v_mov_b32_e32 v131, 0
	s_andn2_b64 vcc, exec, s[64:65]
	s_cbranch_vccnz .LBB0_1598
	s_add_u32 s2, s2, 0x80
	s_addc_u32 s3, s3, 0
	s_add_u32 s6, s4, 0x100
	s_addc_u32 s7, s5, 0
	s_mov_b32 s4, 0
	s_add_i32 s72, s4, 2
	s_add_u32 s73, s2, 0x80
	s_addc_u32 s5, s3, 0
	s_add_i32 s76, 0, 0x10000
	s_cmp_eq_u32 s37, s4
	s_cselect_b32 s5, s41, s5
	s_cselect_b32 s4, s40, s73
	v_add_u32_e32 v158, s76, v160
	s_cselect_b32 s75, s69, s7
	s_cselect_b32 s74, s68, s6
	s_add_i32 s73, 0, 0x14000
	ds_read_b128 v[132:135], v158
	ds_read_b128 v[136:139], v158 offset:1024
	ds_read_b128 v[154:157], v158 offset:2048
	ds_read_b128 v[164:167], v158 offset:3072
	v_add_u32_e32 v158, s73, v160
	ds_read_b128 v[168:171], v158
	ds_read_b128 v[172:175], v158 offset:1024
	ds_read_b128 v[176:179], v158 offset:2048
	ds_read_b128 v[180:183], v158 offset:3072
	v_lshl_add_u64 v[158:159], s[2:3], 0, v[150:151]
	s_add_i32 m0, s17, 0xc000
	ds_read_b128 v[184:187], v162
	ds_read_b128 v[188:191], v162 offset:1024
	ds_read_b128 v[192:195], v162 offset:2048
	ds_read_b128 v[202:205], v162 offset:3072
	ds_read_b128 v[206:209], v162 offset:4096
	ds_read_b128 v[210:213], v162 offset:5120
	ds_read_b128 v[214:217], v162 offset:6144
	ds_read_b128 v[218:221], v162 offset:7168
	global_load_lds_dwordx4 v[158:159], off
	v_lshl_add_u64 v[158:159], s[2:3], 0, v[152:153]
	s_add_i32 m0, s17, 0xe000
	s_nop 0
	global_load_lds_dwordx4 v[158:159], off
	s_waitcnt vmcnt(8)
	s_waitcnt lgkmcnt(0)
	s_barrier
	v_mfma_f32_16x16x32_bf16 v[128:131], v[132:135], v[184:187], 0
	v_mfma_f32_16x16x32_bf16 v[124:127], v[154:157], v[184:187], 0
	v_mfma_f32_16x16x32_bf16 v[112:115], v[132:135], v[192:195], 0
	v_mfma_f32_16x16x32_bf16 v[108:111], v[154:157], v[192:195], 0
	v_mfma_f32_16x16x32_bf16 v[96:99], v[132:135], v[206:209], 0
	v_mfma_f32_16x16x32_bf16 v[92:95], v[154:157], v[206:209], 0
	v_mfma_f32_16x16x32_bf16 v[80:83], v[132:135], v[214:217], 0
	v_mfma_f32_16x16x32_bf16 v[76:79], v[154:157], v[214:217], 0
	v_mfma_f32_16x16x32_bf16 v[128:131], v[136:139], v[188:191], v[128:131]
	v_mfma_f32_16x16x32_bf16 v[124:127], v[164:167], v[188:191], v[124:127]
	v_mfma_f32_16x16x32_bf16 v[112:115], v[136:139], v[202:205], v[112:115]
	v_mfma_f32_16x16x32_bf16 v[108:111], v[164:167], v[202:205], v[108:111]
	v_mfma_f32_16x16x32_bf16 v[96:99], v[136:139], v[210:213], v[96:99]
	v_mfma_f32_16x16x32_bf16 v[92:95], v[164:167], v[210:213], v[92:95]
	v_mfma_f32_16x16x32_bf16 v[80:83], v[136:139], v[218:221], v[80:83]
	v_mfma_f32_16x16x32_bf16 v[76:79], v[164:167], v[218:221], v[76:79]
	v_mfma_f32_16x16x32_bf16 v[120:123], v[168:171], v[184:187], 0
	v_mfma_f32_16x16x32_bf16 v[116:119], v[176:179], v[184:187], 0
	v_mfma_f32_16x16x32_bf16 v[104:107], v[168:171], v[192:195], 0
	v_mfma_f32_16x16x32_bf16 v[100:103], v[176:179], v[192:195], 0
	v_mfma_f32_16x16x32_bf16 v[88:91], v[168:171], v[206:209], 0
	v_mfma_f32_16x16x32_bf16 v[84:87], v[176:179], v[206:209], 0
	v_mfma_f32_16x16x32_bf16 v[72:75], v[168:171], v[214:217], 0
	v_mfma_f32_16x16x32_bf16 v[68:71], v[176:179], v[214:217], 0
	v_mfma_f32_16x16x32_bf16 v[120:123], v[172:175], v[188:191], v[120:123]
	v_mfma_f32_16x16x32_bf16 v[116:119], v[180:183], v[188:191], v[116:119]
	v_mfma_f32_16x16x32_bf16 v[104:107], v[172:175], v[202:205], v[104:107]
	v_mfma_f32_16x16x32_bf16 v[100:103], v[180:183], v[202:205], v[100:103]
	v_mfma_f32_16x16x32_bf16 v[88:91], v[172:175], v[210:213], v[88:91]
	v_mfma_f32_16x16x32_bf16 v[84:87], v[180:183], v[210:213], v[84:87]
	v_mfma_f32_16x16x32_bf16 v[72:75], v[172:175], v[218:221], v[72:75]
	v_mfma_f32_16x16x32_bf16 v[68:71], v[180:183], v[218:221], v[68:71]
	s_barrier
	s_add_i32 s76, s76, s16
	v_lshl_add_u64 v[158:159], s[74:75], 0, v[142:143]
	s_mov_b32 m0, s76
	ds_read_b128 v[184:187], v162 offset:16384
	ds_read_b128 v[188:191], v162 offset:17408
	ds_read_b128 v[192:195], v162 offset:18432
	ds_read_b128 v[202:205], v162 offset:19456
	ds_read_b128 v[206:209], v162 offset:20480
	ds_read_b128 v[210:213], v162 offset:21504
	ds_read_b128 v[214:217], v162 offset:22528
	ds_read_b128 v[218:221], v162 offset:23552
	global_load_lds_dwordx4 v[158:159], off
	s_add_i32 m0, s76, 0x2000
	v_lshl_add_u64 v[196:197], s[74:75], 0, v[146:147]
	s_add_u32 s74, s74, s58
	s_addc_u32 s75, s75, s59
	s_add_i32 s73, s73, s16
	global_load_lds_dwordx4 v[196:197], off
	v_lshl_add_u64 v[198:199], s[74:75], 0, v[142:143]
	s_mov_b32 m0, s73
	v_lshl_add_u64 v[222:223], s[74:75], 0, v[146:147]
	global_load_lds_dwordx4 v[198:199], off
	s_add_i32 m0, s73, 0x2000
	v_lshl_add_u64 v[224:225], s[4:5], 0, v[140:141]
	global_load_lds_dwordx4 v[222:223], off
	s_mov_b32 m0, s17
	v_lshl_add_u64 v[230:231], s[4:5], 0, v[144:145]
	global_load_lds_dwordx4 v[224:225], off
	s_mov_b32 m0, s28
	s_nop 0
	global_load_lds_dwordx4 v[230:231], off
	s_waitcnt vmcnt(8)
	s_waitcnt lgkmcnt(0)
	s_barrier
; #define PG8_GOFFS(slot_) do { _Pragma("unroll") for (int _i = 0; _i < 2; ++_i) { int R, C; stage_rc(tid * 16 + _i * 8192, R, C); _Pragma("unroll") for (int _h = 0; _h < 2; ++_h) { \
;         unsigned t_ = gtab[(slot_) * 256 + R + 128 * _h]; t_ = t_ < (unsigned)(T - 1) ? t_ : (unsigned)(T - 1); voffA[_h][_i] = (t_ * (unsigned)K + (unsigned)C) * 2u; } } } while (0)
; #define PG8_STAGE(bufoff, gbase, voff) do { _Pragma("unroll") for (int _i = 0; _i < 2; ++_i) \
;         __builtin_amdgcn_global_load_lds((const unsigned*)((const char*)(gbase) + (voff)[_i]), (LAS unsigned*)(lds + (bufoff) + ldsw + _i * 8192), 16, 0, 0); } while (0)
; #define PG8_BAR __builtin_amdgcn_s_barrier()
; template <class Epi, class Sched>
; __device__ __forceinline__ void gemm_phase(const int tid, LAS unsigned char* lds, const bf16* Aop, const bf16* Bop, const int K_, const Sched& S, const Epi& E, const bf16* Aop1 = nullptr, const bf16* Bop1 = nullptr) {
;     ...
;         for (int t = 0; t < nt; t += 2) {
;             const bool last = (t == nt - 2);
;             const char* a1 = cA + (size_t)(t + 1) * kstep;
;             const char* a2 = last ? nA : cA + (size_t)(t + 2) * kstep; const char* b2 = last ? nB : cB + (size_t)(t + 2) * kstep;
;             const char* a3 = a2 + kstep; const char* b3 = b2 + kstep;
;             PG8_LDB(B0, 0, 0); PG8_LDB(B1, 0, 1); PG8_SCHED; PG8_LDA(At, 0, 0); PG8_STAGE_A1(PG8_SA(1, 1), a1);
;             PG8_WAIT_V(8); PG8_WAIT_L(0); PG8_BAR; PG8_MMA(0, 0, At, B0); PG8_MMA(0, 1, At, B1); PG8_BAR; PG8_SCHED;
;             PG8_LDA(At, 0, 1); PG8_STAGE(PG8_SB(0, 0), b2, voffB); PG8_STAGE(PG8_SB(0, 1), b2 + hstep, voffB); if (Epi::GATHER && last && has_next) PG8_GOFFS((ui + 1) & 1); PG8_STAGE(PG8_SA(0, 0), a2, voffA[0]);
;             PG8_WAIT_V(8); PG8_WAIT_L(0); PG8_BAR; PG8_MMA(1, 0, At, B0); PG8_MMA(1, 1, At, B1); PG8_BAR; PG8_SCHED;
;             PG8_LDB(B0, 1, 0); PG8_LDB(B1, 1, 1); PG8_SCHED; PG8_LDA(At, 1, 0); PG8_STAGE_A1(PG8_SA(0, 1), a2);
;             PG8_WAIT_V(8); PG8_WAIT_L(0); PG8_BAR; PG8_MMA(0, 0, At, B0); PG8_MMA(0, 1, At, B1); PG8_BAR; PG8_SCHED;
;             PG8_LDA(At, 1, 1); PG8_STAGE(PG8_SB(1, 0), b3, voffB); PG8_STAGE(PG8_SB(1, 1), b3 + hstep, voffB); PG8_STAGE(PG8_SA(1, 0), a3, voffA[0]);
;             PG8_WAIT_V(8); PG8_WAIT_L(0); PG8_BAR; PG8_MMA(1, 0, At, B0); PG8_MMA(1, 1, At, B1); PG8_BAR; PG8_SCHED;
;         }
	v_mfma_f32_16x16x32_bf16 v[64:67], v[132:135], v[184:187], 0
	v_mfma_f32_16x16x32_bf16 v[60:63], v[154:157], v[184:187], 0
	v_mfma_f32_16x16x32_bf16 v[48:51], v[132:135], v[192:195], 0
	v_mfma_f32_16x16x32_bf16 v[44:47], v[154:157], v[192:195], 0
	v_mfma_f32_16x16x32_bf16 v[32:35], v[132:135], v[206:209], 0
	v_mfma_f32_16x16x32_bf16 v[28:31], v[154:157], v[206:209], 0
	v_mfma_f32_16x16x32_bf16 v[16:19], v[132:135], v[214:217], 0
	v_mfma_f32_16x16x32_bf16 v[12:15], v[154:157], v[214:217], 0
	v_mfma_f32_16x16x32_bf16 v[64:67], v[136:139], v[188:191], v[64:67]
	v_mfma_f32_16x16x32_bf16 v[60:63], v[164:167], v[188:191], v[60:63]
	v_mfma_f32_16x16x32_bf16 v[48:51], v[136:139], v[202:205], v[48:51]
	v_mfma_f32_16x16x32_bf16 v[44:47], v[164:167], v[202:205], v[44:47]
	v_mfma_f32_16x16x32_bf16 v[32:35], v[136:139], v[210:213], v[32:35]
	v_mfma_f32_16x16x32_bf16 v[28:31], v[164:167], v[210:213], v[28:31]
	v_mfma_f32_16x16x32_bf16 v[16:19], v[136:139], v[218:221], v[16:19]
	v_mfma_f32_16x16x32_bf16 v[12:15], v[164:167], v[218:221], v[12:15]
	v_mfma_f32_16x16x32_bf16 v[56:59], v[168:171], v[184:187], 0
	v_mfma_f32_16x16x32_bf16 v[52:55], v[176:179], v[184:187], 0
	v_mfma_f32_16x16x32_bf16 v[40:43], v[168:171], v[192:195], 0
	v_mfma_f32_16x16x32_bf16 v[36:39], v[176:179], v[192:195], 0
	v_mfma_f32_16x16x32_bf16 v[24:27], v[168:171], v[206:209], 0
	v_mfma_f32_16x16x32_bf16 v[20:23], v[176:179], v[206:209], 0
	v_mfma_f32_16x16x32_bf16 v[8:11], v[168:171], v[214:217], 0
	v_mfma_f32_16x16x32_bf16 v[4:7], v[176:179], v[214:217], 0
	v_mfma_f32_16x16x32_bf16 v[56:59], v[172:175], v[188:191], v[56:59]
	v_mfma_f32_16x16x32_bf16 v[52:55], v[180:183], v[188:191], v[52:55]
	v_mfma_f32_16x16x32_bf16 v[40:43], v[172:175], v[202:205], v[40:43]
	v_mfma_f32_16x16x32_bf16 v[36:39], v[180:183], v[202:205], v[36:39]
	v_mfma_f32_16x16x32_bf16 v[24:27], v[172:175], v[210:213], v[24:27]
	v_mfma_f32_16x16x32_bf16 v[20:23], v[180:183], v[210:213], v[20:23]
	v_mfma_f32_16x16x32_bf16 v[8:11], v[172:175], v[218:221], v[8:11]
	v_mfma_f32_16x16x32_bf16 v[4:7], v[180:183], v[218:221], v[4:7]
	s_barrier
	s_add_i32 s73, 0, 0x18000
	v_add_u32_e32 v163, s73, v160
	s_add_i32 s74, 0, 0x1c000
	ds_read_b128 v[132:135], v163
	ds_read_b128 v[136:139], v163 offset:1024
	ds_read_b128 v[154:157], v163 offset:2048
	ds_read_b128 v[164:167], v163 offset:3072
	v_add_u32_e32 v163, s74, v160
	ds_read_b128 v[168:171], v163
	ds_read_b128 v[172:175], v163 offset:1024
	ds_read_b128 v[176:179], v163 offset:2048
	ds_read_b128 v[180:183], v163 offset:3072
	s_add_u32 s4, s4, s58
	s_addc_u32 s5, s5, s59
	s_mov_b32 m0, s29
	v_lshl_add_u64 v[232:233], s[4:5], 0, v[140:141]
	ds_read_b128 v[184:187], v162 offset:32768
	ds_read_b128 v[188:191], v162 offset:33792
	ds_read_b128 v[192:195], v162 offset:34816
	ds_read_b128 v[202:205], v162 offset:35840
	ds_read_b128 v[206:209], v162 offset:36864
	ds_read_b128 v[210:213], v162 offset:37888
	ds_read_b128 v[214:217], v162 offset:38912
	ds_read_b128 v[218:221], v162 offset:39936
	global_load_lds_dwordx4 v[232:233], off
	v_lshl_add_u64 v[232:233], s[4:5], 0, v[144:145]
	s_mov_b32 m0, s34
	s_nop 0
	global_load_lds_dwordx4 v[232:233], off
	s_waitcnt vmcnt(8)
	s_waitcnt lgkmcnt(0)
	s_barrier
	v_mfma_f32_16x16x32_bf16 v[128:131], v[132:135], v[184:187], v[128:131]
	v_mfma_f32_16x16x32_bf16 v[124:127], v[154:157], v[184:187], v[124:127]
	v_mfma_f32_16x16x32_bf16 v[112:115], v[132:135], v[192:195], v[112:115]
	v_mfma_f32_16x16x32_bf16 v[108:111], v[154:157], v[192:195], v[108:111]
	v_mfma_f32_16x16x32_bf16 v[96:99], v[132:135], v[206:209], v[96:99]
	v_mfma_f32_16x16x32_bf16 v[92:95], v[154:157], v[206:209], v[92:95]
	v_mfma_f32_16x16x32_bf16 v[80:83], v[132:135], v[214:217], v[80:83]
	v_mfma_f32_16x16x32_bf16 v[76:79], v[154:157], v[214:217], v[76:79]
	v_mfma_f32_16x16x32_bf16 v[128:131], v[136:139], v[188:191], v[128:131]
	v_mfma_f32_16x16x32_bf16 v[124:127], v[164:167], v[188:191], v[124:127]
	v_mfma_f32_16x16x32_bf16 v[112:115], v[136:139], v[202:205], v[112:115]
	v_mfma_f32_16x16x32_bf16 v[108:111], v[164:167], v[202:205], v[108:111]
	v_mfma_f32_16x16x32_bf16 v[96:99], v[136:139], v[210:213], v[96:99]
	v_mfma_f32_16x16x32_bf16 v[92:95], v[164:167], v[210:213], v[92:95]
	v_mfma_f32_16x16x32_bf16 v[80:83], v[136:139], v[218:221], v[80:83]
	v_mfma_f32_16x16x32_bf16 v[76:79], v[164:167], v[218:221], v[76:79]
	v_mfma_f32_16x16x32_bf16 v[120:123], v[168:171], v[184:187], v[120:123]
	v_mfma_f32_16x16x32_bf16 v[116:119], v[176:179], v[184:187], v[116:119]
	v_mfma_f32_16x16x32_bf16 v[104:107], v[168:171], v[192:195], v[104:107]
	v_mfma_f32_16x16x32_bf16 v[100:103], v[176:179], v[192:195], v[100:103]
	v_mfma_f32_16x16x32_bf16 v[88:91], v[168:171], v[206:209], v[88:91]
	v_mfma_f32_16x16x32_bf16 v[84:87], v[176:179], v[206:209], v[84:87]
	v_mfma_f32_16x16x32_bf16 v[72:75], v[168:171], v[214:217], v[72:75]
	v_mfma_f32_16x16x32_bf16 v[68:71], v[176:179], v[214:217], v[68:71]
	v_mfma_f32_16x16x32_bf16 v[120:123], v[172:175], v[188:191], v[120:123]
	v_mfma_f32_16x16x32_bf16 v[116:119], v[180:183], v[188:191], v[116:119]
	v_mfma_f32_16x16x32_bf16 v[104:107], v[172:175], v[202:205], v[104:107]
	v_mfma_f32_16x16x32_bf16 v[100:103], v[180:183], v[202:205], v[100:103]
	v_mfma_f32_16x16x32_bf16 v[88:91], v[172:175], v[210:213], v[88:91]
	v_mfma_f32_16x16x32_bf16 v[84:87], v[180:183], v[210:213], v[84:87]
	v_mfma_f32_16x16x32_bf16 v[72:75], v[172:175], v[218:221], v[72:75]
	v_mfma_f32_16x16x32_bf16 v[68:71], v[180:183], v[218:221], v[68:71]
	s_barrier
; #define PG8_GOFFS(slot_) do { _Pragma("unroll") for (int _i = 0; _i < 2; ++_i) { int R, C; stage_rc(tid * 16 + _i * 8192, R, C); _Pragma("unroll") for (int _h = 0; _h < 2; ++_h) { \
;         unsigned t_ = gtab[(slot_) * 256 + R + 128 * _h]; t_ = t_ < (unsigned)(T - 1) ? t_ : (unsigned)(T - 1); voffA[_h][_i] = (t_ * (unsigned)K + (unsigned)C) * 2u; } } } while (0)
; #define PG8_STAGE(bufoff, gbase, voff) do { _Pragma("unroll") for (int _i = 0; _i < 2; ++_i) \
;         __builtin_amdgcn_global_load_lds((const unsigned*)((const char*)(gbase) + (voff)[_i]), (LAS unsigned*)(lds + (bufoff) + ldsw + _i * 8192), 16, 0, 0); } while (0)
; #define PG8_BAR __builtin_amdgcn_s_barrier()
; template <class Epi, class Sched>
; __device__ __forceinline__ void gemm_phase(const int tid, LAS unsigned char* lds, const bf16* Aop, const bf16* Bop, const int K_, const Sched& S, const Epi& E, const bf16* Aop1 = nullptr, const bf16* Bop1 = nullptr) {
;     ...
;         for (int t = 0; t < nt; t += 2) {
;             const bool last = (t == nt - 2);
;             const char* a1 = cA + (size_t)(t + 1) * kstep;
;             const char* a2 = last ? nA : cA + (size_t)(t + 2) * kstep; const char* b2 = last ? nB : cB + (size_t)(t + 2) * kstep;
;             const char* a3 = a2 + kstep; const char* b3 = b2 + kstep;
;             PG8_LDB(B0, 0, 0); PG8_LDB(B1, 0, 1); PG8_SCHED; PG8_LDA(At, 0, 0); PG8_STAGE_A1(PG8_SA(1, 1), a1);
;             PG8_WAIT_V(8); PG8_WAIT_L(0); PG8_BAR; PG8_MMA(0, 0, At, B0); PG8_MMA(0, 1, At, B1); PG8_BAR; PG8_SCHED;
;             PG8_LDA(At, 0, 1); PG8_STAGE(PG8_SB(0, 0), b2, voffB); PG8_STAGE(PG8_SB(0, 1), b2 + hstep, voffB); if (Epi::GATHER && last && has_next) PG8_GOFFS((ui + 1) & 1); PG8_STAGE(PG8_SA(0, 0), a2, voffA[0]);
;             PG8_WAIT_V(8); PG8_WAIT_L(0); PG8_BAR; PG8_MMA(1, 0, At, B0); PG8_MMA(1, 1, At, B1); PG8_BAR; PG8_SCHED;
;             PG8_LDB(B0, 1, 0); PG8_LDB(B1, 1, 1); PG8_SCHED; PG8_LDA(At, 1, 0); PG8_STAGE_A1(PG8_SA(0, 1), a2);
;             PG8_WAIT_V(8); PG8_WAIT_L(0); PG8_BAR; PG8_MMA(0, 0, At, B0); PG8_MMA(0, 1, At, B1); PG8_BAR; PG8_SCHED;
;             PG8_LDA(At, 1, 1); PG8_STAGE(PG8_SB(1, 0), b3, voffB); PG8_STAGE(PG8_SB(1, 1), b3 + hstep, voffB); PG8_STAGE(PG8_SA(1, 0), a3, voffA[0]);
;             PG8_WAIT_V(8); PG8_WAIT_L(0); PG8_BAR; PG8_MMA(1, 0, At, B0); PG8_MMA(1, 1, At, B1); PG8_BAR; PG8_SCHED;
;         }
	s_add_i32 s4, s73, s16
	v_lshl_add_u64 v[158:159], v[158:159], 0, s[20:21]
	s_mov_b32 m0, s4
	ds_read_b128 v[184:187], v162 offset:49152
	ds_read_b128 v[188:191], v162 offset:50176
	ds_read_b128 v[192:195], v162 offset:51200
	ds_read_b128 v[202:205], v162 offset:52224
	ds_read_b128 v[206:209], v162 offset:53248
	ds_read_b128 v[210:213], v162 offset:54272
	ds_read_b128 v[214:217], v162 offset:55296
	ds_read_b128 v[218:221], v162 offset:56320
	global_load_lds_dwordx4 v[158:159], off
	v_lshl_add_u64 v[158:159], v[196:197], 0, s[20:21]
	s_add_i32 m0, s4, 0x2000
	s_add_i32 s4, s74, s16
	global_load_lds_dwordx4 v[158:159], off
	v_lshl_add_u64 v[158:159], v[198:199], 0, s[20:21]
	s_mov_b32 m0, s4
	s_nop 0
	global_load_lds_dwordx4 v[158:159], off
	v_lshl_add_u64 v[158:159], v[222:223], 0, s[20:21]
	s_add_i32 m0, s4, 0x2000
	s_nop 0
	global_load_lds_dwordx4 v[158:159], off
	v_lshl_add_u64 v[158:159], v[224:225], 0, s[20:21]
	s_mov_b32 m0, s35
	s_nop 0
	global_load_lds_dwordx4 v[158:159], off
	v_lshl_add_u64 v[158:159], v[230:231], 0, s[20:21]
	s_mov_b32 m0, s36
	s_nop 0
	global_load_lds_dwordx4 v[158:159], off
	s_waitcnt vmcnt(8)
	s_waitcnt lgkmcnt(0)
	s_barrier
	v_mfma_f32_16x16x32_bf16 v[64:67], v[132:135], v[184:187], v[64:67]
	v_mfma_f32_16x16x32_bf16 v[60:63], v[154:157], v[184:187], v[60:63]
	v_mfma_f32_16x16x32_bf16 v[48:51], v[132:135], v[192:195], v[48:51]
	v_mfma_f32_16x16x32_bf16 v[44:47], v[154:157], v[192:195], v[44:47]
	v_mfma_f32_16x16x32_bf16 v[32:35], v[132:135], v[206:209], v[32:35]
	v_mfma_f32_16x16x32_bf16 v[28:31], v[154:157], v[206:209], v[28:31]
	v_mfma_f32_16x16x32_bf16 v[16:19], v[132:135], v[214:217], v[16:19]
	v_mfma_f32_16x16x32_bf16 v[12:15], v[154:157], v[214:217], v[12:15]
	v_mfma_f32_16x16x32_bf16 v[64:67], v[136:139], v[188:191], v[64:67]
	v_mfma_f32_16x16x32_bf16 v[60:63], v[164:167], v[188:191], v[60:63]
	v_mfma_f32_16x16x32_bf16 v[48:51], v[136:139], v[202:205], v[48:51]
	v_mfma_f32_16x16x32_bf16 v[44:47], v[164:167], v[202:205], v[44:47]
	v_mfma_f32_16x16x32_bf16 v[32:35], v[136:139], v[210:213], v[32:35]
	v_mfma_f32_16x16x32_bf16 v[28:31], v[164:167], v[210:213], v[28:31]
	v_mfma_f32_16x16x32_bf16 v[16:19], v[136:139], v[218:221], v[16:19]
	v_mfma_f32_16x16x32_bf16 v[12:15], v[164:167], v[218:221], v[12:15]
	v_mfma_f32_16x16x32_bf16 v[56:59], v[168:171], v[184:187], v[56:59]
	v_mfma_f32_16x16x32_bf16 v[52:55], v[176:179], v[184:187], v[52:55]
	v_mfma_f32_16x16x32_bf16 v[40:43], v[168:171], v[192:195], v[40:43]
	v_mfma_f32_16x16x32_bf16 v[36:39], v[176:179], v[192:195], v[36:39]
	v_mfma_f32_16x16x32_bf16 v[24:27], v[168:171], v[206:209], v[24:27]
	v_mfma_f32_16x16x32_bf16 v[20:23], v[176:179], v[206:209], v[20:23]
	v_mfma_f32_16x16x32_bf16 v[8:11], v[168:171], v[214:217], v[8:11]
	v_mfma_f32_16x16x32_bf16 v[4:7], v[176:179], v[214:217], v[4:7]
	v_mfma_f32_16x16x32_bf16 v[56:59], v[172:175], v[188:191], v[56:59]
	v_mfma_f32_16x16x32_bf16 v[52:55], v[180:183], v[188:191], v[52:55]
	v_mfma_f32_16x16x32_bf16 v[40:43], v[172:175], v[202:205], v[40:43]
	v_mfma_f32_16x16x32_bf16 v[36:39], v[180:183], v[202:205], v[36:39]
	v_mfma_f32_16x16x32_bf16 v[24:27], v[172:175], v[210:213], v[24:27]
	v_mfma_f32_16x16x32_bf16 v[20:23], v[180:183], v[210:213], v[20:23]
	v_mfma_f32_16x16x32_bf16 v[8:11], v[172:175], v[218:221], v[8:11]
	v_mfma_f32_16x16x32_bf16 v[4:7], v[180:183], v[218:221], v[4:7]
	s_barrier
	s_add_u32 s2, s2, 0x100
	s_addc_u32 s3, s3, 0
	s_add_u32 s6, s6, 0x100
	s_addc_u32 s7, s7, 0
	s_cmp_ge_i32 s72, s8
	s_mov_b32 s4, s72
	s_cbranch_scc0 .LBB0_1597
	s_branch .LBB0_1598
.LBB0_1597:
	s_add_i32 s72, s4, 2
	s_add_u32 s73, s2, 0x80
	s_addc_u32 s5, s3, 0
	s_add_i32 s76, 0, 0x10000
	s_cmp_eq_u32 s37, s4
	s_cselect_b32 s5, s41, s5
	s_cselect_b32 s4, s40, s73
	v_add_u32_e32 v158, s76, v160
	s_cselect_b32 s75, s69, s7
	s_cselect_b32 s74, s68, s6
	s_add_i32 s73, 0, 0x14000
	ds_read_b128 v[132:135], v158
	ds_read_b128 v[136:139], v158 offset:1024
	ds_read_b128 v[154:157], v158 offset:2048
	ds_read_b128 v[164:167], v158 offset:3072
	v_add_u32_e32 v158, s73, v160
	ds_read_b128 v[168:171], v158
	ds_read_b128 v[172:175], v158 offset:1024
	ds_read_b128 v[176:179], v158 offset:2048
	ds_read_b128 v[180:183], v158 offset:3072
	v_lshl_add_u64 v[158:159], s[2:3], 0, v[150:151]
	s_add_i32 m0, s17, 0xc000
	ds_read_b128 v[184:187], v162
	ds_read_b128 v[188:191], v162 offset:1024
	ds_read_b128 v[192:195], v162 offset:2048
	ds_read_b128 v[202:205], v162 offset:3072
	ds_read_b128 v[206:209], v162 offset:4096
	ds_read_b128 v[210:213], v162 offset:5120
	ds_read_b128 v[214:217], v162 offset:6144
	ds_read_b128 v[218:221], v162 offset:7168
	global_load_lds_dwordx4 v[158:159], off
	v_lshl_add_u64 v[158:159], s[2:3], 0, v[152:153]
	s_add_i32 m0, s17, 0xe000
	s_nop 0
	global_load_lds_dwordx4 v[158:159], off
	s_waitcnt vmcnt(8)
	s_waitcnt lgkmcnt(0)
	s_barrier
; #define PG8_GOFFS(slot_) do { _Pragma("unroll") for (int _i = 0; _i < 2; ++_i) { int R, C; stage_rc(tid * 16 + _i * 8192, R, C); _Pragma("unroll") for (int _h = 0; _h < 2; ++_h) { \
;         unsigned t_ = gtab[(slot_) * 256 + R + 128 * _h]; t_ = t_ < (unsigned)(T - 1) ? t_ : (unsigned)(T - 1); voffA[_h][_i] = (t_ * (unsigned)K + (unsigned)C) * 2u; } } } while (0)
; #define PG8_STAGE(bufoff, gbase, voff) do { _Pragma("unroll") for (int _i = 0; _i < 2; ++_i) \
;         __builtin_amdgcn_global_load_lds((const unsigned*)((const char*)(gbase) + (voff)[_i]), (LAS unsigned*)(lds + (bufoff) + ldsw + _i * 8192), 16, 0, 0); } while (0)
; #define PG8_BAR __builtin_amdgcn_s_barrier()
; template <class Epi, class Sched>
; __device__ __forceinline__ void gemm_phase(const int tid, LAS unsigned char* lds, const bf16* Aop, const bf16* Bop, const int K_, const Sched& S, const Epi& E, const bf16* Aop1 = nullptr, const bf16* Bop1 = nullptr) {
;     ...
;         for (int t = 0; t < nt; t += 2) {
;             const bool last = (t == nt - 2);
;             const char* a1 = cA + (size_t)(t + 1) * kstep;
;             const char* a2 = last ? nA : cA + (size_t)(t + 2) * kstep; const char* b2 = last ? nB : cB + (size_t)(t + 2) * kstep;
;             const char* a3 = a2 + kstep; const char* b3 = b2 + kstep;
;             PG8_LDB(B0, 0, 0); PG8_LDB(B1, 0, 1); PG8_SCHED; PG8_LDA(At, 0, 0); PG8_STAGE_A1(PG8_SA(1, 1), a1);
;             PG8_WAIT_V(8); PG8_WAIT_L(0); PG8_BAR; PG8_MMA(0, 0, At, B0); PG8_MMA(0, 1, At, B1); PG8_BAR; PG8_SCHED;
;             PG8_LDA(At, 0, 1); PG8_STAGE(PG8_SB(0, 0), b2, voffB); PG8_STAGE(PG8_SB(0, 1), b2 + hstep, voffB); if (Epi::GATHER && last && has_next) PG8_GOFFS((ui + 1) & 1); PG8_STAGE(PG8_SA(0, 0), a2, voffA[0]);
;             PG8_WAIT_V(8); PG8_WAIT_L(0); PG8_BAR; PG8_MMA(1, 0, At, B0); PG8_MMA(1, 1, At, B1); PG8_BAR; PG8_SCHED;
;             PG8_LDB(B0, 1, 0); PG8_LDB(B1, 1, 1); PG8_SCHED; PG8_LDA(At, 1, 0); PG8_STAGE_A1(PG8_SA(0, 1), a2);
;             PG8_WAIT_V(8); PG8_WAIT_L(0); PG8_BAR; PG8_MMA(0, 0, At, B0); PG8_MMA(0, 1, At, B1); PG8_BAR; PG8_SCHED;
;             PG8_LDA(At, 1, 1); PG8_STAGE(PG8_SB(1, 0), b3, voffB); PG8_STAGE(PG8_SB(1, 1), b3 + hstep, voffB); PG8_STAGE(PG8_SA(1, 0), a3, voffA[0]);
;             PG8_WAIT_V(8); PG8_WAIT_L(0); PG8_BAR; PG8_MMA(1, 0, At, B0); PG8_MMA(1, 1, At, B1); PG8_BAR; PG8_SCHED;
;         }
	v_mfma_f32_16x16x32_bf16 v[128:131], v[132:135], v[184:187], v[128:131]
	v_mfma_f32_16x16x32_bf16 v[124:127], v[154:157], v[184:187], v[124:127]
	v_mfma_f32_16x16x32_bf16 v[112:115], v[132:135], v[192:195], v[112:115]
	v_mfma_f32_16x16x32_bf16 v[108:111], v[154:157], v[192:195], v[108:111]
	v_mfma_f32_16x16x32_bf16 v[96:99], v[132:135], v[206:209], v[96:99]
	v_mfma_f32_16x16x32_bf16 v[92:95], v[154:157], v[206:209], v[92:95]
	v_mfma_f32_16x16x32_bf16 v[80:83], v[132:135], v[214:217], v[80:83]
	v_mfma_f32_16x16x32_bf16 v[76:79], v[154:157], v[214:217], v[76:79]
	v_mfma_f32_16x16x32_bf16 v[128:131], v[136:139], v[188:191], v[128:131]
	v_mfma_f32_16x16x32_bf16 v[124:127], v[164:167], v[188:191], v[124:127]
	v_mfma_f32_16x16x32_bf16 v[112:115], v[136:139], v[202:205], v[112:115]
	v_mfma_f32_16x16x32_bf16 v[108:111], v[164:167], v[202:205], v[108:111]
	v_mfma_f32_16x16x32_bf16 v[96:99], v[136:139], v[210:213], v[96:99]
	v_mfma_f32_16x16x32_bf16 v[92:95], v[164:167], v[210:213], v[92:95]
	v_mfma_f32_16x16x32_bf16 v[80:83], v[136:139], v[218:221], v[80:83]
	v_mfma_f32_16x16x32_bf16 v[76:79], v[164:167], v[218:221], v[76:79]
	v_mfma_f32_16x16x32_bf16 v[120:123], v[168:171], v[184:187], v[120:123]
	v_mfma_f32_16x16x32_bf16 v[116:119], v[176:179], v[184:187], v[116:119]
	v_mfma_f32_16x16x32_bf16 v[104:107], v[168:171], v[192:195], v[104:107]
	v_mfma_f32_16x16x32_bf16 v[100:103], v[176:179], v[192:195], v[100:103]
	v_mfma_f32_16x16x32_bf16 v[88:91], v[168:171], v[206:209], v[88:91]
	v_mfma_f32_16x16x32_bf16 v[84:87], v[176:179], v[206:209], v[84:87]
	v_mfma_f32_16x16x32_bf16 v[72:75], v[168:171], v[214:217], v[72:75]
	v_mfma_f32_16x16x32_bf16 v[68:71], v[176:179], v[214:217], v[68:71]
	v_mfma_f32_16x16x32_bf16 v[120:123], v[172:175], v[188:191], v[120:123]
	v_mfma_f32_16x16x32_bf16 v[116:119], v[180:183], v[188:191], v[116:119]
	v_mfma_f32_16x16x32_bf16 v[104:107], v[172:175], v[202:205], v[104:107]
	v_mfma_f32_16x16x32_bf16 v[100:103], v[180:183], v[202:205], v[100:103]
	v_mfma_f32_16x16x32_bf16 v[88:91], v[172:175], v[210:213], v[88:91]
	v_mfma_f32_16x16x32_bf16 v[84:87], v[180:183], v[210:213], v[84:87]
	v_mfma_f32_16x16x32_bf16 v[72:75], v[172:175], v[218:221], v[72:75]
	v_mfma_f32_16x16x32_bf16 v[68:71], v[180:183], v[218:221], v[68:71]
	s_barrier
	s_add_i32 s76, s76, s16
	v_lshl_add_u64 v[158:159], s[74:75], 0, v[142:143]
	s_mov_b32 m0, s76
	ds_read_b128 v[184:187], v162 offset:16384
	ds_read_b128 v[188:191], v162 offset:17408
	ds_read_b128 v[192:195], v162 offset:18432
	ds_read_b128 v[202:205], v162 offset:19456
	ds_read_b128 v[206:209], v162 offset:20480
	ds_read_b128 v[210:213], v162 offset:21504
	ds_read_b128 v[214:217], v162 offset:22528
	ds_read_b128 v[218:221], v162 offset:23552
	global_load_lds_dwordx4 v[158:159], off
	s_add_i32 m0, s76, 0x2000
	v_lshl_add_u64 v[196:197], s[74:75], 0, v[146:147]
	s_add_u32 s74, s74, s58
	s_addc_u32 s75, s75, s59
	s_add_i32 s73, s73, s16
	global_load_lds_dwordx4 v[196:197], off
	v_lshl_add_u64 v[198:199], s[74:75], 0, v[142:143]
	s_mov_b32 m0, s73
	v_lshl_add_u64 v[222:223], s[74:75], 0, v[146:147]
	global_load_lds_dwordx4 v[198:199], off
	s_add_i32 m0, s73, 0x2000
	v_lshl_add_u64 v[224:225], s[4:5], 0, v[140:141]
	global_load_lds_dwordx4 v[222:223], off
	s_mov_b32 m0, s17
	v_lshl_add_u64 v[230:231], s[4:5], 0, v[144:145]
	global_load_lds_dwordx4 v[224:225], off
	s_mov_b32 m0, s28
	s_nop 0
	global_load_lds_dwordx4 v[230:231], off
	s_waitcnt vmcnt(8)
	s_waitcnt lgkmcnt(0)
	s_barrier
	v_mfma_f32_16x16x32_bf16 v[64:67], v[132:135], v[184:187], v[64:67]
	v_mfma_f32_16x16x32_bf16 v[60:63], v[154:157], v[184:187], v[60:63]
	v_mfma_f32_16x16x32_bf16 v[48:51], v[132:135], v[192:195], v[48:51]
	v_mfma_f32_16x16x32_bf16 v[44:47], v[154:157], v[192:195], v[44:47]
	v_mfma_f32_16x16x32_bf16 v[32:35], v[132:135], v[206:209], v[32:35]
	v_mfma_f32_16x16x32_bf16 v[28:31], v[154:157], v[206:209], v[28:31]
	v_mfma_f32_16x16x32_bf16 v[16:19], v[132:135], v[214:217], v[16:19]
	v_mfma_f32_16x16x32_bf16 v[12:15], v[154:157], v[214:217], v[12:15]
	v_mfma_f32_16x16x32_bf16 v[64:67], v[136:139], v[188:191], v[64:67]
	v_mfma_f32_16x16x32_bf16 v[60:63], v[164:167], v[188:191], v[60:63]
	v_mfma_f32_16x16x32_bf16 v[48:51], v[136:139], v[202:205], v[48:51]
	v_mfma_f32_16x16x32_bf16 v[44:47], v[164:167], v[202:205], v[44:47]
	v_mfma_f32_16x16x32_bf16 v[32:35], v[136:139], v[210:213], v[32:35]
	v_mfma_f32_16x16x32_bf16 v[28:31], v[164:167], v[210:213], v[28:31]
	v_mfma_f32_16x16x32_bf16 v[16:19], v[136:139], v[218:221], v[16:19]
	v_mfma_f32_16x16x32_bf16 v[12:15], v[164:167], v[218:221], v[12:15]
	v_mfma_f32_16x16x32_bf16 v[56:59], v[168:171], v[184:187], v[56:59]
	v_mfma_f32_16x16x32_bf16 v[52:55], v[176:179], v[184:187], v[52:55]
	v_mfma_f32_16x16x32_bf16 v[40:43], v[168:171], v[192:195], v[40:43]
	v_mfma_f32_16x16x32_bf16 v[36:39], v[176:179], v[192:195], v[36:39]
	v_mfma_f32_16x16x32_bf16 v[24:27], v[168:171], v[206:209], v[24:27]
	v_mfma_f32_16x16x32_bf16 v[20:23], v[176:179], v[206:209], v[20:23]
	v_mfma_f32_16x16x32_bf16 v[8:11], v[168:171], v[214:217], v[8:11]
	v_mfma_f32_16x16x32_bf16 v[4:7], v[176:179], v[214:217], v[4:7]
	v_mfma_f32_16x16x32_bf16 v[56:59], v[172:175], v[188:191], v[56:59]
	v_mfma_f32_16x16x32_bf16 v[52:55], v[180:183], v[188:191], v[52:55]
	v_mfma_f32_16x16x32_bf16 v[40:43], v[172:175], v[202:205], v[40:43]
	v_mfma_f32_16x16x32_bf16 v[36:39], v[180:183], v[202:205], v[36:39]
	v_mfma_f32_16x16x32_bf16 v[24:27], v[172:175], v[210:213], v[24:27]
	v_mfma_f32_16x16x32_bf16 v[20:23], v[180:183], v[210:213], v[20:23]
	v_mfma_f32_16x16x32_bf16 v[8:11], v[172:175], v[218:221], v[8:11]
	v_mfma_f32_16x16x32_bf16 v[4:7], v[180:183], v[218:221], v[4:7]
	s_barrier
; #define PG8_GOFFS(slot_) do { _Pragma("unroll") for (int _i = 0; _i < 2; ++_i) { int R, C; stage_rc(tid * 16 + _i * 8192, R, C); _Pragma("unroll") for (int _h = 0; _h < 2; ++_h) { \
;         unsigned t_ = gtab[(slot_) * 256 + R + 128 * _h]; t_ = t_ < (unsigned)(T - 1) ? t_ : (unsigned)(T - 1); voffA[_h][_i] = (t_ * (unsigned)K + (unsigned)C) * 2u; } } } while (0)
; #define PG8_STAGE(bufoff, gbase, voff) do { _Pragma("unroll") for (int _i = 0; _i < 2; ++_i) \
;         __builtin_amdgcn_global_load_lds((const unsigned*)((const char*)(gbase) + (voff)[_i]), (LAS unsigned*)(lds + (bufoff) + ldsw + _i * 8192), 16, 0, 0); } while (0)
; #define PG8_BAR __builtin_amdgcn_s_barrier()
; template <class Epi, class Sched>
; __device__ __forceinline__ void gemm_phase(const int tid, LAS unsigned char* lds, const bf16* Aop, const bf16* Bop, const int K_, const Sched& S, const Epi& E, const bf16* Aop1 = nullptr, const bf16* Bop1 = nullptr) {
;     ...
;         for (int t = 0; t < nt; t += 2) {
;             const bool last = (t == nt - 2);
;             const char* a1 = cA + (size_t)(t + 1) * kstep;
;             const char* a2 = last ? nA : cA + (size_t)(t + 2) * kstep; const char* b2 = last ? nB : cB + (size_t)(t + 2) * kstep;
;             const char* a3 = a2 + kstep; const char* b3 = b2 + kstep;
;             PG8_LDB(B0, 0, 0); PG8_LDB(B1, 0, 1); PG8_SCHED; PG8_LDA(At, 0, 0); PG8_STAGE_A1(PG8_SA(1, 1), a1);
;             PG8_WAIT_V(8); PG8_WAIT_L(0); PG8_BAR; PG8_MMA(0, 0, At, B0); PG8_MMA(0, 1, At, B1); PG8_BAR; PG8_SCHED;
;             PG8_LDA(At, 0, 1); PG8_STAGE(PG8_SB(0, 0), b2, voffB); PG8_STAGE(PG8_SB(0, 1), b2 + hstep, voffB); if (Epi::GATHER && last && has_next) PG8_GOFFS((ui + 1) & 1); PG8_STAGE(PG8_SA(0, 0), a2, voffA[0]);
;             PG8_WAIT_V(8); PG8_WAIT_L(0); PG8_BAR; PG8_MMA(1, 0, At, B0); PG8_MMA(1, 1, At, B1); PG8_BAR; PG8_SCHED;
;             PG8_LDB(B0, 1, 0); PG8_LDB(B1, 1, 1); PG8_SCHED; PG8_LDA(At, 1, 0); PG8_STAGE_A1(PG8_SA(0, 1), a2);
;             PG8_WAIT_V(8); PG8_WAIT_L(0); PG8_BAR; PG8_MMA(0, 0, At, B0); PG8_MMA(0, 1, At, B1); PG8_BAR; PG8_SCHED;
;             PG8_LDA(At, 1, 1); PG8_STAGE(PG8_SB(1, 0), b3, voffB); PG8_STAGE(PG8_SB(1, 1), b3 + hstep, voffB); PG8_STAGE(PG8_SA(1, 0), a3, voffA[0]);
;             PG8_WAIT_V(8); PG8_WAIT_L(0); PG8_BAR; PG8_MMA(1, 0, At, B0); PG8_MMA(1, 1, At, B1); PG8_BAR; PG8_SCHED;
;         }
	s_add_i32 s73, 0, 0x18000
	v_add_u32_e32 v163, s73, v160
	s_add_i32 s74, 0, 0x1c000
	ds_read_b128 v[132:135], v163
	ds_read_b128 v[136:139], v163 offset:1024
	ds_read_b128 v[154:157], v163 offset:2048
	ds_read_b128 v[164:167], v163 offset:3072
	v_add_u32_e32 v163, s74, v160
	ds_read_b128 v[168:171], v163
	ds_read_b128 v[172:175], v163 offset:1024
	ds_read_b128 v[176:179], v163 offset:2048
	ds_read_b128 v[180:183], v163 offset:3072
	s_add_u32 s4, s4, s58
	s_addc_u32 s5, s5, s59
	s_mov_b32 m0, s29
	v_lshl_add_u64 v[232:233], s[4:5], 0, v[140:141]
	ds_read_b128 v[184:187], v162 offset:32768
	ds_read_b128 v[188:191], v162 offset:33792
	ds_read_b128 v[192:195], v162 offset:34816
	ds_read_b128 v[202:205], v162 offset:35840
	ds_read_b128 v[206:209], v162 offset:36864
	ds_read_b128 v[210:213], v162 offset:37888
	ds_read_b128 v[214:217], v162 offset:38912
	ds_read_b128 v[218:221], v162 offset:39936
	global_load_lds_dwordx4 v[232:233], off
	v_lshl_add_u64 v[232:233], s[4:5], 0, v[144:145]
	s_mov_b32 m0, s34
	s_nop 0
	global_load_lds_dwordx4 v[232:233], off
	s_waitcnt vmcnt(8)
	s_waitcnt lgkmcnt(0)
	s_barrier
	v_mfma_f32_16x16x32_bf16 v[128:131], v[132:135], v[184:187], v[128:131]
	v_mfma_f32_16x16x32_bf16 v[124:127], v[154:157], v[184:187], v[124:127]
	v_mfma_f32_16x16x32_bf16 v[112:115], v[132:135], v[192:195], v[112:115]
	v_mfma_f32_16x16x32_bf16 v[108:111], v[154:157], v[192:195], v[108:111]
	v_mfma_f32_16x16x32_bf16 v[96:99], v[132:135], v[206:209], v[96:99]
	v_mfma_f32_16x16x32_bf16 v[92:95], v[154:157], v[206:209], v[92:95]
	v_mfma_f32_16x16x32_bf16 v[80:83], v[132:135], v[214:217], v[80:83]
	v_mfma_f32_16x16x32_bf16 v[76:79], v[154:157], v[214:217], v[76:79]
	v_mfma_f32_16x16x32_bf16 v[128:131], v[136:139], v[188:191], v[128:131]
	v_mfma_f32_16x16x32_bf16 v[124:127], v[164:167], v[188:191], v[124:127]
	v_mfma_f32_16x16x32_bf16 v[112:115], v[136:139], v[202:205], v[112:115]
	v_mfma_f32_16x16x32_bf16 v[108:111], v[164:167], v[202:205], v[108:111]
	v_mfma_f32_16x16x32_bf16 v[96:99], v[136:139], v[210:213], v[96:99]
	v_mfma_f32_16x16x32_bf16 v[92:95], v[164:167], v[210:213], v[92:95]
	v_mfma_f32_16x16x32_bf16 v[80:83], v[136:139], v[218:221], v[80:83]
	v_mfma_f32_16x16x32_bf16 v[76:79], v[164:167], v[218:221], v[76:79]
	v_mfma_f32_16x16x32_bf16 v[120:123], v[168:171], v[184:187], v[120:123]
	v_mfma_f32_16x16x32_bf16 v[116:119], v[176:179], v[184:187], v[116:119]
	v_mfma_f32_16x16x32_bf16 v[104:107], v[168:171], v[192:195], v[104:107]
	v_mfma_f32_16x16x32_bf16 v[100:103], v[176:179], v[192:195], v[100:103]
	v_mfma_f32_16x16x32_bf16 v[88:91], v[168:171], v[206:209], v[88:91]
	v_mfma_f32_16x16x32_bf16 v[84:87], v[176:179], v[206:209], v[84:87]
	v_mfma_f32_16x16x32_bf16 v[72:75], v[168:171], v[214:217], v[72:75]
	v_mfma_f32_16x16x32_bf16 v[68:71], v[176:179], v[214:217], v[68:71]
	v_mfma_f32_16x16x32_bf16 v[120:123], v[172:175], v[188:191], v[120:123]
	v_mfma_f32_16x16x32_bf16 v[116:119], v[180:183], v[188:191], v[116:119]
	v_mfma_f32_16x16x32_bf16 v[104:107], v[172:175], v[202:205], v[104:107]
	v_mfma_f32_16x16x32_bf16 v[100:103], v[180:183], v[202:205], v[100:103]
	v_mfma_f32_16x16x32_bf16 v[88:91], v[172:175], v[210:213], v[88:91]
	v_mfma_f32_16x16x32_bf16 v[84:87], v[180:183], v[210:213], v[84:87]
	v_mfma_f32_16x16x32_bf16 v[72:75], v[172:175], v[218:221], v[72:75]
	v_mfma_f32_16x16x32_bf16 v[68:71], v[180:183], v[218:221], v[68:71]
	s_barrier
	s_add_i32 s4, s73, s16
	v_lshl_add_u64 v[158:159], v[158:159], 0, s[20:21]
	s_mov_b32 m0, s4
	ds_read_b128 v[184:187], v162 offset:49152
	ds_read_b128 v[188:191], v162 offset:50176
	ds_read_b128 v[192:195], v162 offset:51200
	ds_read_b128 v[202:205], v162 offset:52224
	ds_read_b128 v[206:209], v162 offset:53248
	ds_read_b128 v[210:213], v162 offset:54272
	ds_read_b128 v[214:217], v162 offset:55296
	ds_read_b128 v[218:221], v162 offset:56320
	global_load_lds_dwordx4 v[158:159], off
	v_lshl_add_u64 v[158:159], v[196:197], 0, s[20:21]
	s_add_i32 m0, s4, 0x2000
	s_add_i32 s4, s74, s16
	global_load_lds_dwordx4 v[158:159], off
	v_lshl_add_u64 v[158:159], v[198:199], 0, s[20:21]
	s_mov_b32 m0, s4
	s_nop 0
	global_load_lds_dwordx4 v[158:159], off
	v_lshl_add_u64 v[158:159], v[222:223], 0, s[20:21]
	s_add_i32 m0, s4, 0x2000
	s_nop 0
	global_load_lds_dwordx4 v[158:159], off
	v_lshl_add_u64 v[158:159], v[224:225], 0, s[20:21]
	s_mov_b32 m0, s35
	s_nop 0
	global_load_lds_dwordx4 v[158:159], off
	v_lshl_add_u64 v[158:159], v[230:231], 0, s[20:21]
	s_mov_b32 m0, s36
	s_nop 0
	global_load_lds_dwordx4 v[158:159], off
	s_waitcnt vmcnt(8)
	s_waitcnt lgkmcnt(0)
	s_barrier
	v_mfma_f32_16x16x32_bf16 v[64:67], v[132:135], v[184:187], v[64:67]
	v_mfma_f32_16x16x32_bf16 v[60:63], v[154:157], v[184:187], v[60:63]
	v_mfma_f32_16x16x32_bf16 v[48:51], v[132:135], v[192:195], v[48:51]
	v_mfma_f32_16x16x32_bf16 v[44:47], v[154:157], v[192:195], v[44:47]
	v_mfma_f32_16x16x32_bf16 v[32:35], v[132:135], v[206:209], v[32:35]
	v_mfma_f32_16x16x32_bf16 v[28:31], v[154:157], v[206:209], v[28:31]
	v_mfma_f32_16x16x32_bf16 v[16:19], v[132:135], v[214:217], v[16:19]
	v_mfma_f32_16x16x32_bf16 v[12:15], v[154:157], v[214:217], v[12:15]
	v_mfma_f32_16x16x32_bf16 v[64:67], v[136:139], v[188:191], v[64:67]
	v_mfma_f32_16x16x32_bf16 v[60:63], v[164:167], v[188:191], v[60:63]
	v_mfma_f32_16x16x32_bf16 v[48:51], v[136:139], v[202:205], v[48:51]
	v_mfma_f32_16x16x32_bf16 v[44:47], v[164:167], v[202:205], v[44:47]
	v_mfma_f32_16x16x32_bf16 v[32:35], v[136:139], v[210:213], v[32:35]
	v_mfma_f32_16x16x32_bf16 v[28:31], v[164:167], v[210:213], v[28:31]
	v_mfma_f32_16x16x32_bf16 v[16:19], v[136:139], v[218:221], v[16:19]
	v_mfma_f32_16x16x32_bf16 v[12:15], v[164:167], v[218:221], v[12:15]
	v_mfma_f32_16x16x32_bf16 v[56:59], v[168:171], v[184:187], v[56:59]
	v_mfma_f32_16x16x32_bf16 v[52:55], v[176:179], v[184:187], v[52:55]
	v_mfma_f32_16x16x32_bf16 v[40:43], v[168:171], v[192:195], v[40:43]
	v_mfma_f32_16x16x32_bf16 v[36:39], v[176:179], v[192:195], v[36:39]
	v_mfma_f32_16x16x32_bf16 v[24:27], v[168:171], v[206:209], v[24:27]
	v_mfma_f32_16x16x32_bf16 v[20:23], v[176:179], v[206:209], v[20:23]
	v_mfma_f32_16x16x32_bf16 v[8:11], v[168:171], v[214:217], v[8:11]
	v_mfma_f32_16x16x32_bf16 v[4:7], v[176:179], v[214:217], v[4:7]
	v_mfma_f32_16x16x32_bf16 v[56:59], v[172:175], v[188:191], v[56:59]
	v_mfma_f32_16x16x32_bf16 v[52:55], v[180:183], v[188:191], v[52:55]
	v_mfma_f32_16x16x32_bf16 v[40:43], v[172:175], v[202:205], v[40:43]
	v_mfma_f32_16x16x32_bf16 v[36:39], v[180:183], v[202:205], v[36:39]
	v_mfma_f32_16x16x32_bf16 v[24:27], v[172:175], v[210:213], v[24:27]
	v_mfma_f32_16x16x32_bf16 v[20:23], v[180:183], v[210:213], v[20:23]
	v_mfma_f32_16x16x32_bf16 v[8:11], v[172:175], v[218:221], v[8:11]
	v_mfma_f32_16x16x32_bf16 v[4:7], v[180:183], v[218:221], v[4:7]
	s_barrier
	s_add_u32 s2, s2, 0x100
	s_addc_u32 s3, s3, 0
	s_add_u32 s6, s6, 0x100
	s_addc_u32 s7, s7, 0
	s_cmp_ge_i32 s72, s8
	s_mov_b32 s4, s72
	s_cbranch_scc0 .LBB0_1597
